# peeled first K iteration of 7 GEMM loops with srcC=0 so the 128 per-tile accumulator zeroing moves are gone (on top of batched residual epilogue loads)
# speedup vs baseline: 1.0116x; 1.0054x over previous
; #define PG8_WAIT_V(n) asm volatile("s_waitcnt vmcnt(" #n ")" ::: "memory")
; #define PG8_WAIT_L(n) asm volatile("s_waitcnt lgkmcnt(" #n ")" ::: "memory")
; template <class Epi, class Sched, bool ALIGN_EPI = false, bool SP2 = false>
; __device__ __forceinline__ void gemm_phase(PG8_LAS unsigned char* lds, const Gemm g, const Sched& S, const Epi& E) {
;     ...
;     f32x4 acc[2][2][4][2];
; #pragma unroll
;     for (int a = 0; a < 2; ++a)
; #pragma unroll
;         for (int b = 0; b < 2; ++b)
; #pragma unroll
;             for (int m = 0; m < 4; ++m)
; #pragma unroll
;                 for (int n = 0; n < 2; ++n) acc[a][b][m][n] = (f32x4){0.f, 0.f, 0.f, 0.f};
;     ...
;     for (;;) {
;         const bool has_next = S.next(ui + 1, nxt);
;         const char* nA = has_next ? (const char*)g.A + (size_t)nxt.pm * tstep : cA; const char* nB = has_next ? (const char*)g.Bt + (size_t)nxt.pn * tstep : cB;
;         for (int t = 0; t < nt; t += 2) {
;             const bool last = (t == nt - 2);
;             const char* a1 = cA + (size_t)(t + 1) * kstep;
;             const char* a2 = last ? nA : cA + (size_t)(t + 2) * kstep; const char* b2 = last ? nB : cB + (size_t)(t + 2) * kstep;
;             const char* a3 = a2 + kstep; const char* b3 = b2 + kstep;
;             if (last && has_next) S.a_ready(nxt);
;             if constexpr (SP2) {
;             PG8_LDB(B0, 0, 0); PG8_LDB(B1, 0, 1); PG8_SCHED; PG8_LDA(At, 0, 0); PG8_STAGE(PG8_SA(1, 1), a1 + hstep, voffA);
;             PG8_WAIT_V(8); PG8_WAIT_L(0); PG8_BAR; PG8_MMA(0, 0, At, B0); PG8_MMA(0, 1, At, B1); PG8_BAR; PG8_SCHED;
;             PG8_LDA(At, 0, 1); PG8_STAGE(PG8_SB(0, 0), b2, voffB); PG8_STAGE(PG8_SB(0, 1), b2 + hstep, voffB); PG8_STAGE(PG8_SA(0, 0), a2, voffA);
;             PG8_WAIT_V(8); PG8_WAIT_L(0); PG8_BAR; PG8_MMA(1, 0, At, B0); PG8_MMA(1, 1, At, B1); PG8_BAR; PG8_SCHED;
;             PG8_LDB(B0, 1, 0); PG8_LDB(B1, 1, 1); PG8_SCHED; PG8_LDA(At, 1, 0); PG8_STAGE(PG8_SA(0, 1), a2 + hstep, voffA);
;             PG8_WAIT_V(8); PG8_WAIT_L(0); PG8_BAR; PG8_MMA(0, 0, At, B0); PG8_MMA(0, 1, At, B1); PG8_BAR; PG8_SCHED;
;             PG8_LDA(At, 1, 1); PG8_STAGE(PG8_SB(1, 0), b3, voffB); PG8_STAGE(PG8_SB(1, 1), b3 + hstep, voffB); PG8_STAGE(PG8_SA(1, 0), a3, voffA);
;             PG8_WAIT_V(8); PG8_WAIT_L(0); PG8_BAR; PG8_MMA(1, 0, At, B0); PG8_MMA(1, 1, At, B1); PG8_BAR; PG8_SCHED;
.LBB0_352:
	s_ashr_i32 s27, s26, 31
	s_lshl_b64 s[30:31], s[26:27], 20
	s_add_u32 s30, s60, s30
	s_addc_u32 s31, s61, s31
	s_and_b64 s[34:35], s[6:7], exec
	s_cselect_b32 s27, s31, s53
	s_cselect_b32 s73, s30, s52
	s_ashr_i32 s29, s28, 31
	s_lshl_b64 s[34:35], s[28:29], 20
	s_add_u32 s34, s58, s34
	s_addc_u32 s35, s59, s35
	s_and_b64 s[54:55], s[6:7], exec
	s_cselect_b32 s29, s35, s51
	s_cselect_b32 s74, s34, s50
	s_add_u32 s75, s50, 0x100
	s_addc_u32 s76, s51, 0
	s_add_u32 s50, s52, 0x80080
	s_addc_u32 s51, s53, 0
	s_mov_b32 s77, -2
	ds_read_b128 v[128:131], v169
	ds_read_b128 v[132:135], v169 offset:1024
	ds_read_b128 v[136:139], v169 offset:2048
	ds_read_b128 v[140:143], v169 offset:3072
	ds_read_b128 v[160:163], v170
	ds_read_b128 v[172:175], v170 offset:1024
	ds_read_b128 v[176:179], v170 offset:2048
	ds_read_b128 v[180:183], v170 offset:3072
	s_add_u32 s52, s50, 0xfff80080
	s_addc_u32 s53, s51, -1
	s_cmp_eq_u32 s77, 28
	s_cselect_b32 s55, s27, s53
	s_cselect_b32 s54, s73, s52
	s_cselect_b32 s53, s29, s76
	s_cselect_b32 s52, s74, s75
	v_lshl_add_u64 v[164:165], s[50:51], 0, v[154:155]
	s_add_i32 m0, s37, 0xc000
	ds_read_b128 v[184:187], v171
	ds_read_b128 v[188:191], v171 offset:1024
	ds_read_b128 v[194:197], v171 offset:2048
	ds_read_b128 v[198:201], v171 offset:3072
	ds_read_b128 v[202:205], v171 offset:4096
	ds_read_b128 v[206:209], v171 offset:5120
	ds_read_b128 v[210:213], v171 offset:6144
	ds_read_b128 v[214:217], v171 offset:7168
	global_load_lds_dwordx4 v[164:165], off
	v_lshl_add_u64 v[164:165], s[50:51], 0, v[152:153]
	s_add_i32 m0, s37, 0xe000
	s_nop 0
	global_load_lds_dwordx4 v[164:165], off
	s_waitcnt vmcnt(8)
	s_waitcnt lgkmcnt(0)
	s_barrier
	s_setprio 1
	s_waitcnt lgkmcnt(0)
	v_mfma_f32_16x16x32_bf16 v[124:127], v[128:131], v[184:187], 0
	v_mfma_f32_16x16x32_bf16 v[120:123], v[136:139], v[184:187], 0
	v_mfma_f32_16x16x32_bf16 v[108:111], v[128:131], v[194:197], 0
	v_mfma_f32_16x16x32_bf16 v[104:107], v[136:139], v[194:197], 0
	v_mfma_f32_16x16x32_bf16 v[92:95], v[128:131], v[202:205], 0
	v_mfma_f32_16x16x32_bf16 v[88:91], v[136:139], v[202:205], 0
	v_mfma_f32_16x16x32_bf16 v[76:79], v[128:131], v[210:213], 0
	v_mfma_f32_16x16x32_bf16 v[72:75], v[136:139], v[210:213], 0
	v_mfma_f32_16x16x32_bf16 v[124:127], v[132:135], v[188:191], v[124:127]
	v_mfma_f32_16x16x32_bf16 v[120:123], v[140:143], v[188:191], v[120:123]
	v_mfma_f32_16x16x32_bf16 v[108:111], v[132:135], v[198:201], v[108:111]
	v_mfma_f32_16x16x32_bf16 v[104:107], v[140:143], v[198:201], v[104:107]
	v_mfma_f32_16x16x32_bf16 v[92:95], v[132:135], v[206:209], v[92:95]
	v_mfma_f32_16x16x32_bf16 v[88:91], v[140:143], v[206:209], v[88:91]
	v_mfma_f32_16x16x32_bf16 v[76:79], v[132:135], v[214:217], v[76:79]
	v_mfma_f32_16x16x32_bf16 v[72:75], v[140:143], v[214:217], v[72:75]
	s_setprio 0
	s_setprio 1
	v_mfma_f32_16x16x32_bf16 v[116:119], v[160:163], v[184:187], 0
	v_mfma_f32_16x16x32_bf16 v[112:115], v[176:179], v[184:187], 0
	v_mfma_f32_16x16x32_bf16 v[100:103], v[160:163], v[194:197], 0
	v_mfma_f32_16x16x32_bf16 v[96:99], v[176:179], v[194:197], 0
	v_mfma_f32_16x16x32_bf16 v[84:87], v[160:163], v[202:205], 0
	v_mfma_f32_16x16x32_bf16 v[80:83], v[176:179], v[202:205], 0
	v_mfma_f32_16x16x32_bf16 v[68:71], v[160:163], v[210:213], 0
	v_mfma_f32_16x16x32_bf16 v[64:67], v[176:179], v[210:213], 0
	v_mfma_f32_16x16x32_bf16 v[116:119], v[172:175], v[188:191], v[116:119]
	v_mfma_f32_16x16x32_bf16 v[112:115], v[180:183], v[188:191], v[112:115]
	v_mfma_f32_16x16x32_bf16 v[100:103], v[172:175], v[198:201], v[100:103]
	v_mfma_f32_16x16x32_bf16 v[96:99], v[180:183], v[198:201], v[96:99]
	v_mfma_f32_16x16x32_bf16 v[84:87], v[172:175], v[206:209], v[84:87]
	v_mfma_f32_16x16x32_bf16 v[80:83], v[180:183], v[206:209], v[80:83]
	v_mfma_f32_16x16x32_bf16 v[68:71], v[172:175], v[214:217], v[68:71]
	v_mfma_f32_16x16x32_bf16 v[64:67], v[180:183], v[214:217], v[64:67]
	s_setprio 0
	s_barrier
	s_add_i32 s78, s71, s62
	v_lshl_add_u64 v[164:165], s[52:53], 0, v[146:147]
	s_mov_b32 m0, s78
	ds_read_b128 v[184:187], v171 offset:16384
	ds_read_b128 v[188:191], v171 offset:17408
	ds_read_b128 v[194:197], v171 offset:18432
	ds_read_b128 v[198:201], v171 offset:19456
	ds_read_b128 v[202:205], v171 offset:20480
	ds_read_b128 v[206:209], v171 offset:21504
	ds_read_b128 v[210:213], v171 offset:22528
	ds_read_b128 v[214:217], v171 offset:23552
	global_load_lds_dwordx4 v[164:165], off
	s_add_i32 m0, s78, 0x2000
	s_add_u32 s78, s52, 0x80000
	v_lshl_add_u64 v[218:219], s[52:53], 0, v[150:151]
	s_addc_u32 s79, s53, 0
	s_add_i32 s80, s72, s62
	global_load_lds_dwordx4 v[218:219], off
	v_lshl_add_u64 v[220:221], s[78:79], 0, v[146:147]
	s_mov_b32 m0, s80
	v_lshl_add_u64 v[222:223], s[54:55], 0, v[148:149]
	global_load_lds_dwordx4 v[220:221], off
	v_lshl_add_u64 v[220:221], s[78:79], 0, v[150:151]
	s_add_i32 m0, s80, 0x2000
	s_nop 0
	global_load_lds_dwordx4 v[220:221], off
	v_lshl_add_u64 v[220:221], s[54:55], 0, v[144:145]
	s_mov_b32 m0, s37
	s_nop 0
	global_load_lds_dwordx4 v[220:221], off
	s_mov_b32 m0, s49
	s_nop 0
	global_load_lds_dwordx4 v[222:223], off
	s_waitcnt vmcnt(8)
	s_waitcnt lgkmcnt(0)
	s_barrier
; #define PG8_STAGE(bufoff, gbase, voff) do { _Pragma("unroll") for (int _i = 0; _i < 2; ++_i) \
;         __builtin_amdgcn_global_load_lds((const unsigned*)((const char*)(gbase) + (voff)[_i]), (PG8_LAS unsigned*)(lds + (bufoff) + ldsw + _i * 8192), 16, 0, 0); } while (0)
; #define PG8_LDA(dst, b, h) do { _Pragma("unroll") for (int m = 0; m < 4; ++m) _Pragma("unroll") for (int k = 0; k < 2; ++k) dst[m][k] = *(const PG8_LAS bf16x8*)(lds + PG8_SA(b, h) + aoff + m * 2048 + k * 1024); } while (0)
; #define PG8_LDB(dst, b, h) do { _Pragma("unroll") for (int n = 0; n < 2; ++n) _Pragma("unroll") for (int k = 0; k < 2; ++k) dst[n][k] = *(const PG8_LAS bf16x8*)(lds + PG8_SB(b, h) + boff + n * 2048 + k * 1024); } while (0)
; #define PG8_MMA(ai, bj, At, Bt) do { __builtin_amdgcn_s_setprio(1); _Pragma("unroll") for (int m = 0; m < 4; ++m) _Pragma("unroll") for (int n = 0; n < 2; ++n) _Pragma("unroll") for (int k = 0; k < 2; ++k) \
;         acc[ai][bj][m][n] = __builtin_amdgcn_mfma_f32_16x16x32_bf16(Bt[n][k], At[m][k], acc[ai][bj][m][n], 0, 0, 0); __builtin_amdgcn_s_setprio(0); } while (0)
; #define PG8_WAIT_V(n) asm volatile("s_waitcnt vmcnt(" #n ")" ::: "memory")
; #define PG8_WAIT_L(n) asm volatile("s_waitcnt lgkmcnt(" #n ")" ::: "memory")
; #define PG8_BAR __builtin_amdgcn_s_barrier()
; #define PG8_SCHED __builtin_amdgcn_sched_barrier(0)
; template <class Epi, class Sched, bool ALIGN_EPI = false, bool SP2 = false>
; __device__ __forceinline__ void gemm_phase(PG8_LAS unsigned char* lds, const Gemm g, const Sched& S, const Epi& E) {
;     ...
;             PG8_LDB(B0, 0, 0); PG8_LDB(B1, 0, 1); PG8_SCHED; PG8_LDA(At, 0, 0); PG8_STAGE(PG8_SA(1, 1), a1 + hstep, voffA);
;             PG8_WAIT_V(8); PG8_WAIT_L(0); PG8_BAR; PG8_MMA(0, 0, At, B0); PG8_MMA(0, 1, At, B1); PG8_BAR; PG8_SCHED;
;             PG8_LDA(At, 0, 1); PG8_STAGE(PG8_SB(0, 0), b2, voffB); PG8_STAGE(PG8_SB(0, 1), b2 + hstep, voffB); PG8_STAGE(PG8_SA(0, 0), a2, voffA);
;             PG8_WAIT_V(8); PG8_WAIT_L(0); PG8_BAR; PG8_MMA(1, 0, At, B0); PG8_MMA(1, 1, At, B1); PG8_BAR; PG8_SCHED;
;             PG8_LDB(B0, 1, 0); PG8_LDB(B1, 1, 1); PG8_SCHED; PG8_LDA(At, 1, 0); PG8_STAGE(PG8_SA(0, 1), a2 + hstep, voffA);
;             PG8_WAIT_V(8); PG8_WAIT_L(0); PG8_BAR; PG8_MMA(0, 0, At, B0); PG8_MMA(0, 1, At, B1); PG8_BAR; PG8_SCHED;
	s_setprio 1
	s_waitcnt lgkmcnt(0)
	v_mfma_f32_16x16x32_bf16 v[60:63], v[128:131], v[184:187], 0
	v_mfma_f32_16x16x32_bf16 v[56:59], v[136:139], v[184:187], 0
	v_mfma_f32_16x16x32_bf16 v[44:47], v[128:131], v[194:197], 0
	v_mfma_f32_16x16x32_bf16 v[40:43], v[136:139], v[194:197], 0
	v_mfma_f32_16x16x32_bf16 v[28:31], v[128:131], v[202:205], 0
	v_mfma_f32_16x16x32_bf16 v[24:27], v[136:139], v[202:205], 0
	v_mfma_f32_16x16x32_bf16 v[12:15], v[128:131], v[210:213], 0
	v_mfma_f32_16x16x32_bf16 v[8:11], v[136:139], v[210:213], 0
	v_mfma_f32_16x16x32_bf16 v[60:63], v[132:135], v[188:191], v[60:63]
	v_mfma_f32_16x16x32_bf16 v[56:59], v[140:143], v[188:191], v[56:59]
	v_mfma_f32_16x16x32_bf16 v[44:47], v[132:135], v[198:201], v[44:47]
	v_mfma_f32_16x16x32_bf16 v[40:43], v[140:143], v[198:201], v[40:43]
	v_mfma_f32_16x16x32_bf16 v[28:31], v[132:135], v[206:209], v[28:31]
	v_mfma_f32_16x16x32_bf16 v[24:27], v[140:143], v[206:209], v[24:27]
	v_mfma_f32_16x16x32_bf16 v[12:15], v[132:135], v[214:217], v[12:15]
	v_mfma_f32_16x16x32_bf16 v[8:11], v[140:143], v[214:217], v[8:11]
	s_setprio 0
	s_setprio 1
	v_mfma_f32_16x16x32_bf16 v[52:55], v[160:163], v[184:187], 0
	v_mfma_f32_16x16x32_bf16 v[48:51], v[176:179], v[184:187], 0
	v_mfma_f32_16x16x32_bf16 v[36:39], v[160:163], v[194:197], 0
	v_mfma_f32_16x16x32_bf16 v[32:35], v[176:179], v[194:197], 0
	v_mfma_f32_16x16x32_bf16 v[20:23], v[160:163], v[202:205], 0
	v_mfma_f32_16x16x32_bf16 v[16:19], v[176:179], v[202:205], 0
	v_mfma_f32_16x16x32_bf16 v[4:7], v[160:163], v[210:213], 0
	v_mfma_f32_16x16x32_bf16 v[0:3], v[176:179], v[210:213], 0
	v_mfma_f32_16x16x32_bf16 v[52:55], v[172:175], v[188:191], v[52:55]
	v_mfma_f32_16x16x32_bf16 v[48:51], v[180:183], v[188:191], v[48:51]
	v_mfma_f32_16x16x32_bf16 v[36:39], v[172:175], v[198:201], v[36:39]
	v_mfma_f32_16x16x32_bf16 v[32:35], v[180:183], v[198:201], v[32:35]
	v_mfma_f32_16x16x32_bf16 v[20:23], v[172:175], v[206:209], v[20:23]
	v_mfma_f32_16x16x32_bf16 v[16:19], v[180:183], v[206:209], v[16:19]
	v_mfma_f32_16x16x32_bf16 v[4:7], v[172:175], v[214:217], v[4:7]
	v_mfma_f32_16x16x32_bf16 v[0:3], v[180:183], v[214:217], v[0:3]
	s_setprio 0
	s_barrier
	s_add_i32 s78, 0, 0x18000
	s_add_i32 s79, 0, 0x1c000
	v_add_u32_e32 v140, s78, v167
	v_add_u32_e32 v180, s79, v167
	ds_read_b128 v[128:131], v140
	ds_read_b128 v[132:135], v140 offset:1024
	ds_read_b128 v[136:139], v140 offset:2048
	ds_read_b128 v[140:143], v140 offset:3072
	ds_read_b128 v[160:163], v180
	ds_read_b128 v[172:175], v180 offset:1024
	ds_read_b128 v[176:179], v180 offset:2048
	ds_read_b128 v[180:183], v180 offset:3072
	s_add_u32 s54, s54, 0x80000
	s_addc_u32 s55, s55, 0
	s_mov_b32 m0, s63
	v_lshl_add_u64 v[224:225], s[54:55], 0, v[144:145]
	ds_read_b128 v[184:187], v171 offset:32768
	ds_read_b128 v[188:191], v171 offset:33792
	ds_read_b128 v[194:197], v171 offset:34816
	ds_read_b128 v[198:201], v171 offset:35840
	ds_read_b128 v[202:205], v171 offset:36864
	ds_read_b128 v[206:209], v171 offset:37888
	ds_read_b128 v[210:213], v171 offset:38912
	ds_read_b128 v[214:217], v171 offset:39936
	global_load_lds_dwordx4 v[224:225], off
	v_lshl_add_u64 v[224:225], s[54:55], 0, v[148:149]
	s_mov_b32 m0, s64
	s_nop 0
	global_load_lds_dwordx4 v[224:225], off
	s_waitcnt vmcnt(8)
	s_waitcnt lgkmcnt(0)
	s_barrier
	s_setprio 1
	s_waitcnt lgkmcnt(0)
	v_mfma_f32_16x16x32_bf16 v[124:127], v[128:131], v[184:187], v[124:127]
	v_mfma_f32_16x16x32_bf16 v[120:123], v[136:139], v[184:187], v[120:123]
	v_mfma_f32_16x16x32_bf16 v[108:111], v[128:131], v[194:197], v[108:111]
	v_mfma_f32_16x16x32_bf16 v[104:107], v[136:139], v[194:197], v[104:107]
	v_mfma_f32_16x16x32_bf16 v[92:95], v[128:131], v[202:205], v[92:95]
	v_mfma_f32_16x16x32_bf16 v[88:91], v[136:139], v[202:205], v[88:91]
	v_mfma_f32_16x16x32_bf16 v[76:79], v[128:131], v[210:213], v[76:79]
	v_mfma_f32_16x16x32_bf16 v[72:75], v[136:139], v[210:213], v[72:75]
	v_mfma_f32_16x16x32_bf16 v[124:127], v[132:135], v[188:191], v[124:127]
	v_mfma_f32_16x16x32_bf16 v[120:123], v[140:143], v[188:191], v[120:123]
	v_mfma_f32_16x16x32_bf16 v[108:111], v[132:135], v[198:201], v[108:111]
	v_mfma_f32_16x16x32_bf16 v[104:107], v[140:143], v[198:201], v[104:107]
	v_mfma_f32_16x16x32_bf16 v[92:95], v[132:135], v[206:209], v[92:95]
	v_mfma_f32_16x16x32_bf16 v[88:91], v[140:143], v[206:209], v[88:91]
	v_mfma_f32_16x16x32_bf16 v[76:79], v[132:135], v[214:217], v[76:79]
	v_mfma_f32_16x16x32_bf16 v[72:75], v[140:143], v[214:217], v[72:75]
	s_setprio 0
	s_setprio 1
	v_mfma_f32_16x16x32_bf16 v[116:119], v[160:163], v[184:187], v[116:119]
	v_mfma_f32_16x16x32_bf16 v[112:115], v[176:179], v[184:187], v[112:115]
	v_mfma_f32_16x16x32_bf16 v[100:103], v[160:163], v[194:197], v[100:103]
	v_mfma_f32_16x16x32_bf16 v[96:99], v[176:179], v[194:197], v[96:99]
	v_mfma_f32_16x16x32_bf16 v[84:87], v[160:163], v[202:205], v[84:87]
	v_mfma_f32_16x16x32_bf16 v[80:83], v[176:179], v[202:205], v[80:83]
	v_mfma_f32_16x16x32_bf16 v[68:71], v[160:163], v[210:213], v[68:71]
	v_mfma_f32_16x16x32_bf16 v[64:67], v[176:179], v[210:213], v[64:67]
	v_mfma_f32_16x16x32_bf16 v[116:119], v[172:175], v[188:191], v[116:119]
	v_mfma_f32_16x16x32_bf16 v[112:115], v[180:183], v[188:191], v[112:115]
	v_mfma_f32_16x16x32_bf16 v[100:103], v[172:175], v[198:201], v[100:103]
	v_mfma_f32_16x16x32_bf16 v[96:99], v[180:183], v[198:201], v[96:99]
	v_mfma_f32_16x16x32_bf16 v[84:87], v[172:175], v[206:209], v[84:87]
	v_mfma_f32_16x16x32_bf16 v[80:83], v[180:183], v[206:209], v[80:83]
	v_mfma_f32_16x16x32_bf16 v[68:71], v[172:175], v[214:217], v[68:71]
	v_mfma_f32_16x16x32_bf16 v[64:67], v[180:183], v[214:217], v[64:67]
	s_setprio 0
	s_barrier
; #define PG8_STAGE(bufoff, gbase, voff) do { _Pragma("unroll") for (int _i = 0; _i < 2; ++_i) \
;         __builtin_amdgcn_global_load_lds((const unsigned*)((const char*)(gbase) + (voff)[_i]), (PG8_LAS unsigned*)(lds + (bufoff) + ldsw + _i * 8192), 16, 0, 0); } while (0)
; #define PG8_LDA(dst, b, h) do { _Pragma("unroll") for (int m = 0; m < 4; ++m) _Pragma("unroll") for (int k = 0; k < 2; ++k) dst[m][k] = *(const PG8_LAS bf16x8*)(lds + PG8_SA(b, h) + aoff + m * 2048 + k * 1024); } while (0)
; #define PG8_MMA(ai, bj, At, Bt) do { __builtin_amdgcn_s_setprio(1); _Pragma("unroll") for (int m = 0; m < 4; ++m) _Pragma("unroll") for (int n = 0; n < 2; ++n) _Pragma("unroll") for (int k = 0; k < 2; ++k) \
;         acc[ai][bj][m][n] = __builtin_amdgcn_mfma_f32_16x16x32_bf16(Bt[n][k], At[m][k], acc[ai][bj][m][n], 0, 0, 0); __builtin_amdgcn_s_setprio(0); } while (0)
; #define PG8_WAIT_V(n) asm volatile("s_waitcnt vmcnt(" #n ")" ::: "memory")
; #define PG8_WAIT_L(n) asm volatile("s_waitcnt lgkmcnt(" #n ")" ::: "memory")
; #define PG8_BAR __builtin_amdgcn_s_barrier()
; #define PG8_SCHED __builtin_amdgcn_sched_barrier(0)
; template <class Epi, class Sched, bool ALIGN_EPI = false, bool SP2 = false>
; __device__ __forceinline__ void gemm_phase(PG8_LAS unsigned char* lds, const Gemm g, const Sched& S, const Epi& E) {
;     ...
;         for (int t = 0; t < nt; t += 2) {
;     ...
;             PG8_LDA(At, 1, 1); PG8_STAGE(PG8_SB(1, 0), b3, voffB); PG8_STAGE(PG8_SB(1, 1), b3 + hstep, voffB); PG8_STAGE(PG8_SA(1, 0), a3, voffA);
;             PG8_WAIT_V(8); PG8_WAIT_L(0); PG8_BAR; PG8_MMA(1, 0, At, B0); PG8_MMA(1, 1, At, B1); PG8_BAR; PG8_SCHED;
	s_add_i32 s54, s78, s62
	v_lshl_add_u64 v[164:165], v[164:165], 0, s[14:15]
	s_mov_b32 m0, s54
	ds_read_b128 v[184:187], v171 offset:49152
	ds_read_b128 v[188:191], v171 offset:50176
	ds_read_b128 v[194:197], v171 offset:51200
	ds_read_b128 v[198:201], v171 offset:52224
	ds_read_b128 v[202:205], v171 offset:53248
	ds_read_b128 v[206:209], v171 offset:54272
	ds_read_b128 v[210:213], v171 offset:55296
	ds_read_b128 v[214:217], v171 offset:56320
	global_load_lds_dwordx4 v[164:165], off
	s_add_i32 m0, s54, 0x2000
	s_add_u32 s52, s52, 0x80080
	v_lshl_add_u64 v[164:165], v[218:219], 0, s[14:15]
	s_addc_u32 s53, s53, 0
	s_add_i32 s54, s79, s62
	global_load_lds_dwordx4 v[164:165], off
	v_lshl_add_u64 v[164:165], s[52:53], 0, v[146:147]
	s_mov_b32 m0, s54
	s_nop 0
	global_load_lds_dwordx4 v[164:165], off
	v_lshl_add_u64 v[164:165], s[52:53], 0, v[150:151]
	s_add_i32 m0, s54, 0x2000
	s_nop 0
	global_load_lds_dwordx4 v[164:165], off
	v_lshl_add_u64 v[164:165], v[220:221], 0, s[14:15]
	s_mov_b32 m0, s68
	s_nop 0
	global_load_lds_dwordx4 v[164:165], off
	v_lshl_add_u64 v[164:165], v[222:223], 0, s[14:15]
	s_mov_b32 m0, s69
	s_nop 0
	global_load_lds_dwordx4 v[164:165], off
	s_waitcnt vmcnt(8)
	s_waitcnt lgkmcnt(0)
	s_barrier
	s_setprio 1
	s_waitcnt lgkmcnt(0)
	v_mfma_f32_16x16x32_bf16 v[60:63], v[128:131], v[184:187], v[60:63]
	v_mfma_f32_16x16x32_bf16 v[56:59], v[136:139], v[184:187], v[56:59]
	v_mfma_f32_16x16x32_bf16 v[44:47], v[128:131], v[194:197], v[44:47]
	v_mfma_f32_16x16x32_bf16 v[40:43], v[136:139], v[194:197], v[40:43]
	v_mfma_f32_16x16x32_bf16 v[28:31], v[128:131], v[202:205], v[28:31]
	v_mfma_f32_16x16x32_bf16 v[24:27], v[136:139], v[202:205], v[24:27]
	v_mfma_f32_16x16x32_bf16 v[12:15], v[128:131], v[210:213], v[12:15]
	v_mfma_f32_16x16x32_bf16 v[8:11], v[136:139], v[210:213], v[8:11]
	v_mfma_f32_16x16x32_bf16 v[60:63], v[132:135], v[188:191], v[60:63]
	v_mfma_f32_16x16x32_bf16 v[56:59], v[140:143], v[188:191], v[56:59]
	v_mfma_f32_16x16x32_bf16 v[44:47], v[132:135], v[198:201], v[44:47]
	v_mfma_f32_16x16x32_bf16 v[40:43], v[140:143], v[198:201], v[40:43]
	v_mfma_f32_16x16x32_bf16 v[28:31], v[132:135], v[206:209], v[28:31]
	v_mfma_f32_16x16x32_bf16 v[24:27], v[140:143], v[206:209], v[24:27]
	v_mfma_f32_16x16x32_bf16 v[12:15], v[132:135], v[214:217], v[12:15]
	v_mfma_f32_16x16x32_bf16 v[8:11], v[140:143], v[214:217], v[8:11]
	s_setprio 0
	s_setprio 1
	v_mfma_f32_16x16x32_bf16 v[52:55], v[160:163], v[184:187], v[52:55]
	v_mfma_f32_16x16x32_bf16 v[48:51], v[176:179], v[184:187], v[48:51]
	v_mfma_f32_16x16x32_bf16 v[36:39], v[160:163], v[194:197], v[36:39]
	v_mfma_f32_16x16x32_bf16 v[32:35], v[176:179], v[194:197], v[32:35]
	v_mfma_f32_16x16x32_bf16 v[20:23], v[160:163], v[202:205], v[20:23]
	v_mfma_f32_16x16x32_bf16 v[16:19], v[176:179], v[202:205], v[16:19]
	v_mfma_f32_16x16x32_bf16 v[4:7], v[160:163], v[210:213], v[4:7]
	v_mfma_f32_16x16x32_bf16 v[0:3], v[176:179], v[210:213], v[0:3]
	v_mfma_f32_16x16x32_bf16 v[52:55], v[172:175], v[188:191], v[52:55]
	v_mfma_f32_16x16x32_bf16 v[48:51], v[180:183], v[188:191], v[48:51]
	v_mfma_f32_16x16x32_bf16 v[36:39], v[172:175], v[198:201], v[36:39]
	v_mfma_f32_16x16x32_bf16 v[32:35], v[180:183], v[198:201], v[32:35]
	v_mfma_f32_16x16x32_bf16 v[20:23], v[172:175], v[206:209], v[20:23]
	v_mfma_f32_16x16x32_bf16 v[16:19], v[180:183], v[206:209], v[16:19]
	v_mfma_f32_16x16x32_bf16 v[4:7], v[172:175], v[214:217], v[4:7]
	v_mfma_f32_16x16x32_bf16 v[0:3], v[180:183], v[214:217], v[0:3]
	s_setprio 0
	s_barrier
	s_add_i32 s77, s77, 2
	s_add_u32 s75, s75, 0x100
	s_addc_u32 s76, s76, 0
	s_add_u32 s50, s50, 0x100
	s_addc_u32 s51, s51, 0
	s_cmp_gt_u32 s77, 29
	s_cbranch_scc1 .Lpeel_exit_1

; #define PG8_BAR __builtin_amdgcn_s_barrier()
; template <class Epi, class Sched, bool ALIGN_EPI = false, bool SP2 = false>
; __device__ __forceinline__ void gemm_phase(PG8_LAS unsigned char* lds, const Gemm g, const Sched& S, const Epi& E) {
;     ...
;         if constexpr (ALIGN_EPI) { if (wr == 0) PG8_BAR; }
.Lpeel_exit_1:
	s_and_b64 vcc, exec, s[16:17]
	s_cbranch_vccz .LBB0_356
	s_barrier

; #define PG8_WAIT_V(n) asm volatile("s_waitcnt vmcnt(" #n ")" ::: "memory")
; #define PG8_WAIT_L(n) asm volatile("s_waitcnt lgkmcnt(" #n ")" ::: "memory")
; template <class Epi, class Sched, bool ALIGN_EPI = false, bool SP2 = false>
; __device__ __forceinline__ void gemm_phase(PG8_LAS unsigned char* lds, const Gemm g, const Sched& S, const Epi& E) {
;     ...
;     f32x4 acc[2][2][4][2];
; #pragma unroll
;     for (int a = 0; a < 2; ++a)
; #pragma unroll
;         for (int b = 0; b < 2; ++b)
; #pragma unroll
;             for (int m = 0; m < 4; ++m)
; #pragma unroll
;                 for (int n = 0; n < 2; ++n) acc[a][b][m][n] = (f32x4){0.f, 0.f, 0.f, 0.f};
;     ...
;     for (;;) {
;         const bool has_next = S.next(ui + 1, nxt);
;         const char* nA = has_next ? (const char*)g.A + (size_t)nxt.pm * tstep : cA; const char* nB = has_next ? (const char*)g.Bt + (size_t)nxt.pn * tstep : cB;
;         for (int t = 0; t < nt; t += 2) {
;             const bool last = (t == nt - 2);
;             const char* a1 = cA + (size_t)(t + 1) * kstep;
;             const char* a2 = last ? nA : cA + (size_t)(t + 2) * kstep; const char* b2 = last ? nB : cB + (size_t)(t + 2) * kstep;
;             const char* a3 = a2 + kstep; const char* b3 = b2 + kstep;
;             if (last && has_next) S.a_ready(nxt);
;             if constexpr (SP2) {
;             PG8_LDB(B0, 0, 0); PG8_LDB(B1, 0, 1); PG8_SCHED; PG8_LDA(At, 0, 0); PG8_STAGE(PG8_SA(1, 1), a1 + hstep, voffA);
;             PG8_WAIT_V(8); PG8_WAIT_L(0); PG8_BAR; PG8_MMA(0, 0, At, B0); PG8_MMA(0, 1, At, B1); PG8_BAR; PG8_SCHED;
;             PG8_LDA(At, 0, 1); PG8_STAGE(PG8_SB(0, 0), b2, voffB); PG8_STAGE(PG8_SB(0, 1), b2 + hstep, voffB); PG8_STAGE(PG8_SA(0, 0), a2, voffA);
;             PG8_WAIT_V(8); PG8_WAIT_L(0); PG8_BAR; PG8_MMA(1, 0, At, B0); PG8_MMA(1, 1, At, B1); PG8_BAR; PG8_SCHED;
;             PG8_LDB(B0, 1, 0); PG8_LDB(B1, 1, 1); PG8_SCHED; PG8_LDA(At, 1, 0); PG8_STAGE(PG8_SA(0, 1), a2 + hstep, voffA);
;             PG8_WAIT_V(8); PG8_WAIT_L(0); PG8_BAR; PG8_MMA(0, 0, At, B0); PG8_MMA(0, 1, At, B1); PG8_BAR; PG8_SCHED;
;             PG8_LDA(At, 1, 1); PG8_STAGE(PG8_SB(1, 0), b3, voffB); PG8_STAGE(PG8_SB(1, 1), b3 + hstep, voffB); PG8_STAGE(PG8_SA(1, 0), a3, voffA);
;             PG8_WAIT_V(8); PG8_WAIT_L(0); PG8_BAR; PG8_MMA(1, 0, At, B0); PG8_MMA(1, 1, At, B1); PG8_BAR; PG8_SCHED;
.LBB0_480:
	s_ashr_i32 s17, s16, 31
	s_lshl_b64 s[20:21], s[16:17], 20
	s_add_u32 s20, s49, s20
	s_addc_u32 s21, s50, s21
	s_and_b64 s[22:23], s[6:7], exec
	s_cselect_b32 s17, s21, s31
	s_cselect_b32 s63, s20, s30
	s_ashr_i32 s19, s18, 31
	s_lshl_b64 s[22:23], s[18:19], 20
	s_add_u32 s22, s37, s22
	s_addc_u32 s23, s48, s23
	s_and_b64 s[34:35], s[6:7], exec
	s_cselect_b32 s19, s23, s29
	s_cselect_b32 s64, s22, s28
	s_add_u32 s65, s28, 0x100
	s_addc_u32 s66, s29, 0
	s_add_u32 s28, s30, 0x80080
	s_addc_u32 s29, s31, 0
	s_mov_b32 s67, -2
	ds_read_b128 v[144:147], v151
	ds_read_b128 v[154:157], v151 offset:1024
	ds_read_b128 v[158:161], v151 offset:2048
	ds_read_b128 v[162:165], v151 offset:3072
	ds_read_b128 v[166:169], v152
	ds_read_b128 v[170:173], v152 offset:1024
	ds_read_b128 v[174:177], v152 offset:2048
	ds_read_b128 v[178:181], v152 offset:3072
	s_add_u32 s30, s28, 0xfff80080
	s_addc_u32 s31, s29, -1
	s_cmp_eq_u32 s67, 28
	s_cselect_b32 s35, s17, s31
	s_cselect_b32 s34, s63, s30
	s_cselect_b32 s31, s19, s66
	s_cselect_b32 s30, s64, s65
	v_lshl_add_u64 v[190:191], s[28:29], 0, v[138:139]
	s_add_i32 m0, s25, 0xc000
	ds_read_b128 v[182:185], v153
	ds_read_b128 v[186:189], v153 offset:1024
	ds_read_b128 v[194:197], v153 offset:2048
	ds_read_b128 v[198:201], v153 offset:3072
	ds_read_b128 v[202:205], v153 offset:4096
	ds_read_b128 v[206:209], v153 offset:5120
	ds_read_b128 v[210:213], v153 offset:6144
	ds_read_b128 v[214:217], v153 offset:7168
	global_load_lds_dwordx4 v[190:191], off
	v_lshl_add_u64 v[190:191], s[28:29], 0, v[136:137]
	s_add_i32 m0, s25, 0xe000
	s_nop 0
	global_load_lds_dwordx4 v[190:191], off
	s_waitcnt vmcnt(8)
	s_waitcnt lgkmcnt(0)
	s_barrier
	s_setprio 1
	s_waitcnt lgkmcnt(0)
	v_mfma_f32_16x16x32_bf16 v[124:127], v[144:147], v[182:185], 0
	v_mfma_f32_16x16x32_bf16 v[120:123], v[158:161], v[182:185], 0
	v_mfma_f32_16x16x32_bf16 v[108:111], v[144:147], v[194:197], 0
	v_mfma_f32_16x16x32_bf16 v[104:107], v[158:161], v[194:197], 0
	v_mfma_f32_16x16x32_bf16 v[92:95], v[144:147], v[202:205], 0
	v_mfma_f32_16x16x32_bf16 v[88:91], v[158:161], v[202:205], 0
	v_mfma_f32_16x16x32_bf16 v[76:79], v[144:147], v[210:213], 0
	v_mfma_f32_16x16x32_bf16 v[72:75], v[158:161], v[210:213], 0
	v_mfma_f32_16x16x32_bf16 v[124:127], v[154:157], v[186:189], v[124:127]
	v_mfma_f32_16x16x32_bf16 v[120:123], v[162:165], v[186:189], v[120:123]
	v_mfma_f32_16x16x32_bf16 v[108:111], v[154:157], v[198:201], v[108:111]
	v_mfma_f32_16x16x32_bf16 v[104:107], v[162:165], v[198:201], v[104:107]
	v_mfma_f32_16x16x32_bf16 v[92:95], v[154:157], v[206:209], v[92:95]
	v_mfma_f32_16x16x32_bf16 v[88:91], v[162:165], v[206:209], v[88:91]
	v_mfma_f32_16x16x32_bf16 v[76:79], v[154:157], v[214:217], v[76:79]
	v_mfma_f32_16x16x32_bf16 v[72:75], v[162:165], v[214:217], v[72:75]
	s_setprio 0
	s_setprio 1
	v_mfma_f32_16x16x32_bf16 v[116:119], v[166:169], v[182:185], 0
	v_mfma_f32_16x16x32_bf16 v[112:115], v[174:177], v[182:185], 0
	v_mfma_f32_16x16x32_bf16 v[100:103], v[166:169], v[194:197], 0
	v_mfma_f32_16x16x32_bf16 v[96:99], v[174:177], v[194:197], 0
	v_mfma_f32_16x16x32_bf16 v[84:87], v[166:169], v[202:205], 0
	v_mfma_f32_16x16x32_bf16 v[80:83], v[174:177], v[202:205], 0
	v_mfma_f32_16x16x32_bf16 v[68:71], v[166:169], v[210:213], 0
	v_mfma_f32_16x16x32_bf16 v[64:67], v[174:177], v[210:213], 0
	v_mfma_f32_16x16x32_bf16 v[116:119], v[170:173], v[186:189], v[116:119]
	v_mfma_f32_16x16x32_bf16 v[112:115], v[178:181], v[186:189], v[112:115]
	v_mfma_f32_16x16x32_bf16 v[100:103], v[170:173], v[198:201], v[100:103]
	v_mfma_f32_16x16x32_bf16 v[96:99], v[178:181], v[198:201], v[96:99]
	v_mfma_f32_16x16x32_bf16 v[84:87], v[170:173], v[206:209], v[84:87]
	v_mfma_f32_16x16x32_bf16 v[80:83], v[178:181], v[206:209], v[80:83]
	v_mfma_f32_16x16x32_bf16 v[68:71], v[170:173], v[214:217], v[68:71]
	v_mfma_f32_16x16x32_bf16 v[64:67], v[178:181], v[214:217], v[64:67]
	s_setprio 0
	s_barrier
	s_add_i32 s68, s60, s51
	v_lshl_add_u64 v[190:191], s[30:31], 0, v[132:133]
	s_mov_b32 m0, s68
	ds_read_b128 v[182:185], v153 offset:16384
	ds_read_b128 v[186:189], v153 offset:17408
	ds_read_b128 v[194:197], v153 offset:18432
	ds_read_b128 v[198:201], v153 offset:19456
	ds_read_b128 v[202:205], v153 offset:20480
	ds_read_b128 v[206:209], v153 offset:21504
	ds_read_b128 v[210:213], v153 offset:22528
	ds_read_b128 v[214:217], v153 offset:23552
	global_load_lds_dwordx4 v[190:191], off
	s_add_i32 m0, s68, 0x2000
	s_add_u32 s68, s30, 0x80000
	v_lshl_add_u64 v[218:219], s[30:31], 0, v[128:129]
	s_addc_u32 s69, s31, 0
	s_add_i32 s70, s61, s51
	global_load_lds_dwordx4 v[218:219], off
	v_lshl_add_u64 v[220:221], s[68:69], 0, v[132:133]
	s_mov_b32 m0, s70
	v_lshl_add_u64 v[222:223], s[34:35], 0, v[130:131]
	global_load_lds_dwordx4 v[220:221], off
	v_lshl_add_u64 v[220:221], s[68:69], 0, v[128:129]
	s_add_i32 m0, s70, 0x2000
	s_nop 0
	global_load_lds_dwordx4 v[220:221], off
	v_lshl_add_u64 v[220:221], s[34:35], 0, v[134:135]
	s_mov_b32 m0, s25
	s_nop 0
	global_load_lds_dwordx4 v[220:221], off
	s_mov_b32 m0, s27
	s_nop 0
	global_load_lds_dwordx4 v[222:223], off
	s_waitcnt vmcnt(8)
	s_waitcnt lgkmcnt(0)
	s_barrier
; #define PG8_STAGE(bufoff, gbase, voff) do { _Pragma("unroll") for (int _i = 0; _i < 2; ++_i) \
;         __builtin_amdgcn_global_load_lds((const unsigned*)((const char*)(gbase) + (voff)[_i]), (PG8_LAS unsigned*)(lds + (bufoff) + ldsw + _i * 8192), 16, 0, 0); } while (0)
; #define PG8_LDA(dst, b, h) do { _Pragma("unroll") for (int m = 0; m < 4; ++m) _Pragma("unroll") for (int k = 0; k < 2; ++k) dst[m][k] = *(const PG8_LAS bf16x8*)(lds + PG8_SA(b, h) + aoff + m * 2048 + k * 1024); } while (0)
; #define PG8_LDB(dst, b, h) do { _Pragma("unroll") for (int n = 0; n < 2; ++n) _Pragma("unroll") for (int k = 0; k < 2; ++k) dst[n][k] = *(const PG8_LAS bf16x8*)(lds + PG8_SB(b, h) + boff + n * 2048 + k * 1024); } while (0)
; #define PG8_MMA(ai, bj, At, Bt) do { __builtin_amdgcn_s_setprio(1); _Pragma("unroll") for (int m = 0; m < 4; ++m) _Pragma("unroll") for (int n = 0; n < 2; ++n) _Pragma("unroll") for (int k = 0; k < 2; ++k) \
;         acc[ai][bj][m][n] = __builtin_amdgcn_mfma_f32_16x16x32_bf16(Bt[n][k], At[m][k], acc[ai][bj][m][n], 0, 0, 0); __builtin_amdgcn_s_setprio(0); } while (0)
; #define PG8_WAIT_V(n) asm volatile("s_waitcnt vmcnt(" #n ")" ::: "memory")
; #define PG8_WAIT_L(n) asm volatile("s_waitcnt lgkmcnt(" #n ")" ::: "memory")
; #define PG8_BAR __builtin_amdgcn_s_barrier()
; #define PG8_SCHED __builtin_amdgcn_sched_barrier(0)
; template <class Epi, class Sched, bool ALIGN_EPI = false, bool SP2 = false>
; __device__ __forceinline__ void gemm_phase(PG8_LAS unsigned char* lds, const Gemm g, const Sched& S, const Epi& E) {
;     ...
;             PG8_LDB(B0, 0, 0); PG8_LDB(B1, 0, 1); PG8_SCHED; PG8_LDA(At, 0, 0); PG8_STAGE(PG8_SA(1, 1), a1 + hstep, voffA);
;             PG8_WAIT_V(8); PG8_WAIT_L(0); PG8_BAR; PG8_MMA(0, 0, At, B0); PG8_MMA(0, 1, At, B1); PG8_BAR; PG8_SCHED;
;             PG8_LDA(At, 0, 1); PG8_STAGE(PG8_SB(0, 0), b2, voffB); PG8_STAGE(PG8_SB(0, 1), b2 + hstep, voffB); PG8_STAGE(PG8_SA(0, 0), a2, voffA);
;             PG8_WAIT_V(8); PG8_WAIT_L(0); PG8_BAR; PG8_MMA(1, 0, At, B0); PG8_MMA(1, 1, At, B1); PG8_BAR; PG8_SCHED;
;             PG8_LDB(B0, 1, 0); PG8_LDB(B1, 1, 1); PG8_SCHED; PG8_LDA(At, 1, 0); PG8_STAGE(PG8_SA(0, 1), a2 + hstep, voffA);
;             PG8_WAIT_V(8); PG8_WAIT_L(0); PG8_BAR; PG8_MMA(0, 0, At, B0); PG8_MMA(0, 1, At, B1); PG8_BAR; PG8_SCHED;
	s_setprio 1
	s_waitcnt lgkmcnt(0)
	v_mfma_f32_16x16x32_bf16 v[60:63], v[144:147], v[182:185], 0
	v_mfma_f32_16x16x32_bf16 v[56:59], v[158:161], v[182:185], 0
	v_mfma_f32_16x16x32_bf16 v[44:47], v[144:147], v[194:197], 0
	v_mfma_f32_16x16x32_bf16 v[40:43], v[158:161], v[194:197], 0
	v_mfma_f32_16x16x32_bf16 v[28:31], v[144:147], v[202:205], 0
	v_mfma_f32_16x16x32_bf16 v[24:27], v[158:161], v[202:205], 0
	v_mfma_f32_16x16x32_bf16 v[12:15], v[144:147], v[210:213], 0
	v_mfma_f32_16x16x32_bf16 v[8:11], v[158:161], v[210:213], 0
	v_mfma_f32_16x16x32_bf16 v[60:63], v[154:157], v[186:189], v[60:63]
	v_mfma_f32_16x16x32_bf16 v[56:59], v[162:165], v[186:189], v[56:59]
	v_mfma_f32_16x16x32_bf16 v[44:47], v[154:157], v[198:201], v[44:47]
	v_mfma_f32_16x16x32_bf16 v[40:43], v[162:165], v[198:201], v[40:43]
	v_mfma_f32_16x16x32_bf16 v[28:31], v[154:157], v[206:209], v[28:31]
	v_mfma_f32_16x16x32_bf16 v[24:27], v[162:165], v[206:209], v[24:27]
	v_mfma_f32_16x16x32_bf16 v[12:15], v[154:157], v[214:217], v[12:15]
	v_mfma_f32_16x16x32_bf16 v[8:11], v[162:165], v[214:217], v[8:11]
	s_setprio 0
	s_setprio 1
	v_mfma_f32_16x16x32_bf16 v[52:55], v[166:169], v[182:185], 0
	v_mfma_f32_16x16x32_bf16 v[48:51], v[174:177], v[182:185], 0
	v_mfma_f32_16x16x32_bf16 v[36:39], v[166:169], v[194:197], 0
	v_mfma_f32_16x16x32_bf16 v[32:35], v[174:177], v[194:197], 0
	v_mfma_f32_16x16x32_bf16 v[20:23], v[166:169], v[202:205], 0
	v_mfma_f32_16x16x32_bf16 v[16:19], v[174:177], v[202:205], 0
	v_mfma_f32_16x16x32_bf16 v[4:7], v[166:169], v[210:213], 0
	v_mfma_f32_16x16x32_bf16 v[0:3], v[174:177], v[210:213], 0
	v_mfma_f32_16x16x32_bf16 v[52:55], v[170:173], v[186:189], v[52:55]
	v_mfma_f32_16x16x32_bf16 v[48:51], v[178:181], v[186:189], v[48:51]
	v_mfma_f32_16x16x32_bf16 v[36:39], v[170:173], v[198:201], v[36:39]
	v_mfma_f32_16x16x32_bf16 v[32:35], v[178:181], v[198:201], v[32:35]
	v_mfma_f32_16x16x32_bf16 v[20:23], v[170:173], v[206:209], v[20:23]
	v_mfma_f32_16x16x32_bf16 v[16:19], v[178:181], v[206:209], v[16:19]
	v_mfma_f32_16x16x32_bf16 v[4:7], v[170:173], v[214:217], v[4:7]
	v_mfma_f32_16x16x32_bf16 v[0:3], v[178:181], v[214:217], v[0:3]
	s_setprio 0
	s_barrier
	s_add_i32 s68, 0, 0x18000
	s_add_i32 s69, 0, 0x1c000
	v_add_u32_e32 v162, s68, v149
	v_add_u32_e32 v178, s69, v149
	ds_read_b128 v[144:147], v162
	ds_read_b128 v[154:157], v162 offset:1024
	ds_read_b128 v[158:161], v162 offset:2048
	ds_read_b128 v[162:165], v162 offset:3072
	ds_read_b128 v[166:169], v178
	ds_read_b128 v[170:173], v178 offset:1024
	ds_read_b128 v[174:177], v178 offset:2048
	ds_read_b128 v[178:181], v178 offset:3072
	s_add_u32 s34, s34, 0x80000
	s_addc_u32 s35, s35, 0
	s_mov_b32 m0, s54
	v_lshl_add_u64 v[224:225], s[34:35], 0, v[134:135]
	ds_read_b128 v[182:185], v153 offset:32768
	ds_read_b128 v[186:189], v153 offset:33792
	ds_read_b128 v[194:197], v153 offset:34816
	ds_read_b128 v[198:201], v153 offset:35840
	ds_read_b128 v[202:205], v153 offset:36864
	ds_read_b128 v[206:209], v153 offset:37888
	ds_read_b128 v[210:213], v153 offset:38912
	ds_read_b128 v[214:217], v153 offset:39936
	global_load_lds_dwordx4 v[224:225], off
	v_lshl_add_u64 v[224:225], s[34:35], 0, v[130:131]
	s_mov_b32 m0, s55
	s_nop 0
	global_load_lds_dwordx4 v[224:225], off
	s_waitcnt vmcnt(8)
	s_waitcnt lgkmcnt(0)
	s_barrier
	s_setprio 1
	s_waitcnt lgkmcnt(0)
	v_mfma_f32_16x16x32_bf16 v[124:127], v[144:147], v[182:185], v[124:127]
	v_mfma_f32_16x16x32_bf16 v[120:123], v[158:161], v[182:185], v[120:123]
	v_mfma_f32_16x16x32_bf16 v[108:111], v[144:147], v[194:197], v[108:111]
	v_mfma_f32_16x16x32_bf16 v[104:107], v[158:161], v[194:197], v[104:107]
	v_mfma_f32_16x16x32_bf16 v[92:95], v[144:147], v[202:205], v[92:95]
	v_mfma_f32_16x16x32_bf16 v[88:91], v[158:161], v[202:205], v[88:91]
	v_mfma_f32_16x16x32_bf16 v[76:79], v[144:147], v[210:213], v[76:79]
	v_mfma_f32_16x16x32_bf16 v[72:75], v[158:161], v[210:213], v[72:75]
	v_mfma_f32_16x16x32_bf16 v[124:127], v[154:157], v[186:189], v[124:127]
	v_mfma_f32_16x16x32_bf16 v[120:123], v[162:165], v[186:189], v[120:123]
	v_mfma_f32_16x16x32_bf16 v[108:111], v[154:157], v[198:201], v[108:111]
	v_mfma_f32_16x16x32_bf16 v[104:107], v[162:165], v[198:201], v[104:107]
	v_mfma_f32_16x16x32_bf16 v[92:95], v[154:157], v[206:209], v[92:95]
	v_mfma_f32_16x16x32_bf16 v[88:91], v[162:165], v[206:209], v[88:91]
	v_mfma_f32_16x16x32_bf16 v[76:79], v[154:157], v[214:217], v[76:79]
	v_mfma_f32_16x16x32_bf16 v[72:75], v[162:165], v[214:217], v[72:75]
	s_setprio 0
	s_setprio 1
	v_mfma_f32_16x16x32_bf16 v[116:119], v[166:169], v[182:185], v[116:119]
	v_mfma_f32_16x16x32_bf16 v[112:115], v[174:177], v[182:185], v[112:115]
	v_mfma_f32_16x16x32_bf16 v[100:103], v[166:169], v[194:197], v[100:103]
	v_mfma_f32_16x16x32_bf16 v[96:99], v[174:177], v[194:197], v[96:99]
	v_mfma_f32_16x16x32_bf16 v[84:87], v[166:169], v[202:205], v[84:87]
	v_mfma_f32_16x16x32_bf16 v[80:83], v[174:177], v[202:205], v[80:83]
	v_mfma_f32_16x16x32_bf16 v[68:71], v[166:169], v[210:213], v[68:71]
	v_mfma_f32_16x16x32_bf16 v[64:67], v[174:177], v[210:213], v[64:67]
	v_mfma_f32_16x16x32_bf16 v[116:119], v[170:173], v[186:189], v[116:119]
	v_mfma_f32_16x16x32_bf16 v[112:115], v[178:181], v[186:189], v[112:115]
	v_mfma_f32_16x16x32_bf16 v[100:103], v[170:173], v[198:201], v[100:103]
	v_mfma_f32_16x16x32_bf16 v[96:99], v[178:181], v[198:201], v[96:99]
	v_mfma_f32_16x16x32_bf16 v[84:87], v[170:173], v[206:209], v[84:87]
	v_mfma_f32_16x16x32_bf16 v[80:83], v[178:181], v[206:209], v[80:83]
	v_mfma_f32_16x16x32_bf16 v[68:71], v[170:173], v[214:217], v[68:71]
	v_mfma_f32_16x16x32_bf16 v[64:67], v[178:181], v[214:217], v[64:67]
	s_setprio 0
	s_barrier
; #define PG8_STAGE(bufoff, gbase, voff) do { _Pragma("unroll") for (int _i = 0; _i < 2; ++_i) \
;         __builtin_amdgcn_global_load_lds((const unsigned*)((const char*)(gbase) + (voff)[_i]), (PG8_LAS unsigned*)(lds + (bufoff) + ldsw + _i * 8192), 16, 0, 0); } while (0)
; #define PG8_LDA(dst, b, h) do { _Pragma("unroll") for (int m = 0; m < 4; ++m) _Pragma("unroll") for (int k = 0; k < 2; ++k) dst[m][k] = *(const PG8_LAS bf16x8*)(lds + PG8_SA(b, h) + aoff + m * 2048 + k * 1024); } while (0)
; #define PG8_MMA(ai, bj, At, Bt) do { __builtin_amdgcn_s_setprio(1); _Pragma("unroll") for (int m = 0; m < 4; ++m) _Pragma("unroll") for (int n = 0; n < 2; ++n) _Pragma("unroll") for (int k = 0; k < 2; ++k) \
;         acc[ai][bj][m][n] = __builtin_amdgcn_mfma_f32_16x16x32_bf16(Bt[n][k], At[m][k], acc[ai][bj][m][n], 0, 0, 0); __builtin_amdgcn_s_setprio(0); } while (0)
; #define PG8_WAIT_V(n) asm volatile("s_waitcnt vmcnt(" #n ")" ::: "memory")
; #define PG8_WAIT_L(n) asm volatile("s_waitcnt lgkmcnt(" #n ")" ::: "memory")
; #define PG8_BAR __builtin_amdgcn_s_barrier()
; #define PG8_SCHED __builtin_amdgcn_sched_barrier(0)
; template <class Epi, class Sched, bool ALIGN_EPI = false, bool SP2 = false>
; __device__ __forceinline__ void gemm_phase(PG8_LAS unsigned char* lds, const Gemm g, const Sched& S, const Epi& E) {
;     ...
;         for (int t = 0; t < nt; t += 2) {
;     ...
;             PG8_LDA(At, 1, 1); PG8_STAGE(PG8_SB(1, 0), b3, voffB); PG8_STAGE(PG8_SB(1, 1), b3 + hstep, voffB); PG8_STAGE(PG8_SA(1, 0), a3, voffA);
;             PG8_WAIT_V(8); PG8_WAIT_L(0); PG8_BAR; PG8_MMA(1, 0, At, B0); PG8_MMA(1, 1, At, B1); PG8_BAR; PG8_SCHED;
	s_add_i32 s34, s68, s51
	v_lshl_add_u64 v[190:191], v[190:191], 0, s[12:13]
	s_mov_b32 m0, s34
	ds_read_b128 v[182:185], v153 offset:49152
	ds_read_b128 v[186:189], v153 offset:50176
	ds_read_b128 v[194:197], v153 offset:51200
	ds_read_b128 v[198:201], v153 offset:52224
	ds_read_b128 v[202:205], v153 offset:53248
	ds_read_b128 v[206:209], v153 offset:54272
	ds_read_b128 v[210:213], v153 offset:55296
	ds_read_b128 v[214:217], v153 offset:56320
	global_load_lds_dwordx4 v[190:191], off
	s_add_i32 m0, s34, 0x2000
	s_add_u32 s30, s30, 0x80080
	v_lshl_add_u64 v[190:191], v[218:219], 0, s[12:13]
	s_addc_u32 s31, s31, 0
	s_add_i32 s34, s69, s51
	global_load_lds_dwordx4 v[190:191], off
	v_lshl_add_u64 v[190:191], s[30:31], 0, v[132:133]
	s_mov_b32 m0, s34
	s_nop 0
	global_load_lds_dwordx4 v[190:191], off
	v_lshl_add_u64 v[190:191], s[30:31], 0, v[128:129]
	s_add_i32 m0, s34, 0x2000
	s_nop 0
	global_load_lds_dwordx4 v[190:191], off
	v_lshl_add_u64 v[190:191], v[220:221], 0, s[12:13]
	s_mov_b32 m0, s57
	s_nop 0
	global_load_lds_dwordx4 v[190:191], off
	v_lshl_add_u64 v[190:191], v[222:223], 0, s[12:13]
	s_mov_b32 m0, s58
	s_nop 0
	global_load_lds_dwordx4 v[190:191], off
	s_waitcnt vmcnt(8)
	s_waitcnt lgkmcnt(0)
	s_barrier
	s_setprio 1
	s_waitcnt lgkmcnt(0)
	v_mfma_f32_16x16x32_bf16 v[60:63], v[144:147], v[182:185], v[60:63]
	v_mfma_f32_16x16x32_bf16 v[56:59], v[158:161], v[182:185], v[56:59]
	v_mfma_f32_16x16x32_bf16 v[44:47], v[144:147], v[194:197], v[44:47]
	v_mfma_f32_16x16x32_bf16 v[40:43], v[158:161], v[194:197], v[40:43]
	v_mfma_f32_16x16x32_bf16 v[28:31], v[144:147], v[202:205], v[28:31]
	v_mfma_f32_16x16x32_bf16 v[24:27], v[158:161], v[202:205], v[24:27]
	v_mfma_f32_16x16x32_bf16 v[12:15], v[144:147], v[210:213], v[12:15]
	v_mfma_f32_16x16x32_bf16 v[8:11], v[158:161], v[210:213], v[8:11]
	v_mfma_f32_16x16x32_bf16 v[60:63], v[154:157], v[186:189], v[60:63]
	v_mfma_f32_16x16x32_bf16 v[56:59], v[162:165], v[186:189], v[56:59]
	v_mfma_f32_16x16x32_bf16 v[44:47], v[154:157], v[198:201], v[44:47]
	v_mfma_f32_16x16x32_bf16 v[40:43], v[162:165], v[198:201], v[40:43]
	v_mfma_f32_16x16x32_bf16 v[28:31], v[154:157], v[206:209], v[28:31]
	v_mfma_f32_16x16x32_bf16 v[24:27], v[162:165], v[206:209], v[24:27]
	v_mfma_f32_16x16x32_bf16 v[12:15], v[154:157], v[214:217], v[12:15]
	v_mfma_f32_16x16x32_bf16 v[8:11], v[162:165], v[214:217], v[8:11]
	s_setprio 0
	s_setprio 1
	v_mfma_f32_16x16x32_bf16 v[52:55], v[166:169], v[182:185], v[52:55]
	v_mfma_f32_16x16x32_bf16 v[48:51], v[174:177], v[182:185], v[48:51]
	v_mfma_f32_16x16x32_bf16 v[36:39], v[166:169], v[194:197], v[36:39]
	v_mfma_f32_16x16x32_bf16 v[32:35], v[174:177], v[194:197], v[32:35]
	v_mfma_f32_16x16x32_bf16 v[20:23], v[166:169], v[202:205], v[20:23]
	v_mfma_f32_16x16x32_bf16 v[16:19], v[174:177], v[202:205], v[16:19]
	v_mfma_f32_16x16x32_bf16 v[4:7], v[166:169], v[210:213], v[4:7]
	v_mfma_f32_16x16x32_bf16 v[0:3], v[174:177], v[210:213], v[0:3]
	v_mfma_f32_16x16x32_bf16 v[52:55], v[170:173], v[186:189], v[52:55]
	v_mfma_f32_16x16x32_bf16 v[48:51], v[178:181], v[186:189], v[48:51]
	v_mfma_f32_16x16x32_bf16 v[36:39], v[170:173], v[198:201], v[36:39]
	v_mfma_f32_16x16x32_bf16 v[32:35], v[178:181], v[198:201], v[32:35]
	v_mfma_f32_16x16x32_bf16 v[20:23], v[170:173], v[206:209], v[20:23]
	v_mfma_f32_16x16x32_bf16 v[16:19], v[178:181], v[206:209], v[16:19]
	v_mfma_f32_16x16x32_bf16 v[4:7], v[170:173], v[214:217], v[4:7]
	v_mfma_f32_16x16x32_bf16 v[0:3], v[178:181], v[214:217], v[0:3]
	s_setprio 0
	s_barrier
	s_add_i32 s67, s67, 2
	s_add_u32 s65, s65, 0x100
	s_addc_u32 s66, s66, 0
	s_add_u32 s28, s28, 0x100
	s_addc_u32 s29, s29, 0
	s_cmp_gt_u32 s67, 29
	s_cbranch_scc1 .Lpeel_exit_2

; #define PG8_BAR __builtin_amdgcn_s_barrier()
; template <class Epi, class Sched, bool ALIGN_EPI = false, bool SP2 = false>
; __device__ __forceinline__ void gemm_phase(PG8_LAS unsigned char* lds, const Gemm g, const Sched& S, const Epi& E) {
;     ...
;         if constexpr (ALIGN_EPI) { if (wr == 0) PG8_BAR; }
.Lpeel_exit_2:
	s_and_b64 vcc, exec, s[14:15]
	s_cbranch_vccz .LBB0_484
	s_barrier

; #define PG8_WAIT_V(n) asm volatile("s_waitcnt vmcnt(" #n ")" ::: "memory")
; #define PG8_WAIT_L(n) asm volatile("s_waitcnt lgkmcnt(" #n ")" ::: "memory")
; template <class Epi, class Sched, bool ALIGN_EPI = false, bool SP2 = false>
; __device__ __forceinline__ void gemm_phase(PG8_LAS unsigned char* lds, const Gemm g, const Sched& S, const Epi& E) {
;     ...
;     f32x4 acc[2][2][4][2];
; #pragma unroll
;     for (int a = 0; a < 2; ++a)
; #pragma unroll
;         for (int b = 0; b < 2; ++b)
; #pragma unroll
;             for (int m = 0; m < 4; ++m)
; #pragma unroll
;                 for (int n = 0; n < 2; ++n) acc[a][b][m][n] = (f32x4){0.f, 0.f, 0.f, 0.f};
;     ...
;     for (;;) {
;         const bool has_next = S.next(ui + 1, nxt);
;         const char* nA = has_next ? (const char*)g.A + (size_t)nxt.pm * tstep : cA; const char* nB = has_next ? (const char*)g.Bt + (size_t)nxt.pn * tstep : cB;
;         for (int t = 0; t < nt; t += 2) {
;             const bool last = (t == nt - 2);
;             const char* a1 = cA + (size_t)(t + 1) * kstep;
;             const char* a2 = last ? nA : cA + (size_t)(t + 2) * kstep; const char* b2 = last ? nB : cB + (size_t)(t + 2) * kstep;
;             const char* a3 = a2 + kstep; const char* b3 = b2 + kstep;
;             if (last && has_next) S.a_ready(nxt);
;             if constexpr (SP2) {
;             PG8_LDB(B0, 0, 0); PG8_LDB(B1, 0, 1); PG8_SCHED; PG8_LDA(At, 0, 0); PG8_STAGE(PG8_SA(1, 1), a1 + hstep, voffA);
;             PG8_WAIT_V(8); PG8_WAIT_L(0); PG8_BAR; PG8_MMA(0, 0, At, B0); PG8_MMA(0, 1, At, B1); PG8_BAR; PG8_SCHED;
;             PG8_LDA(At, 0, 1); PG8_STAGE(PG8_SB(0, 0), b2, voffB); PG8_STAGE(PG8_SB(0, 1), b2 + hstep, voffB); PG8_STAGE(PG8_SA(0, 0), a2, voffA);
;             PG8_WAIT_V(8); PG8_WAIT_L(0); PG8_BAR; PG8_MMA(1, 0, At, B0); PG8_MMA(1, 1, At, B1); PG8_BAR; PG8_SCHED;
;             PG8_LDB(B0, 1, 0); PG8_LDB(B1, 1, 1); PG8_SCHED; PG8_LDA(At, 1, 0); PG8_STAGE(PG8_SA(0, 1), a2 + hstep, voffA);
;             PG8_WAIT_V(8); PG8_WAIT_L(0); PG8_BAR; PG8_MMA(0, 0, At, B0); PG8_MMA(0, 1, At, B1); PG8_BAR; PG8_SCHED;
;             PG8_LDA(At, 1, 1); PG8_STAGE(PG8_SB(1, 0), b3, voffB); PG8_STAGE(PG8_SB(1, 1), b3 + hstep, voffB); PG8_STAGE(PG8_SA(1, 0), a3, voffA);
;             PG8_WAIT_V(8); PG8_WAIT_L(0); PG8_BAR; PG8_MMA(1, 0, At, B0); PG8_MMA(1, 1, At, B1); PG8_BAR; PG8_SCHED;
.LBB0_560:
	s_add_u32 s75, s30, 0x100
	s_addc_u32 s76, s31, 0
	s_mov_b32 s77, -2
	ds_read_b128 v[120:123], v169
	ds_read_b128 v[124:127], v169 offset:1024
	ds_read_b128 v[128:131], v169 offset:2048
	ds_read_b128 v[132:135], v169 offset:3072
	ds_read_b128 v[160:163], v170
	ds_read_b128 v[172:175], v170 offset:1024
	ds_read_b128 v[176:179], v170 offset:2048
	ds_read_b128 v[180:183], v170 offset:3072
	s_add_u32 s30, s28, 0x100
	s_addc_u32 s31, s29, 0
	s_cmpk_eq_i32 s77, 0x54
	s_cselect_b32 s37, s9, s31
	s_cselect_b32 s36, s8, s30
	s_cselect_b32 s35, s27, s76
	s_cselect_b32 s34, s26, s75
	v_lshl_add_u64 v[164:165], s[28:29], 0, v[154:155]
	s_add_i32 m0, s55, 0xc000
	ds_read_b128 v[184:187], v171
	ds_read_b128 v[188:191], v171 offset:1024
	ds_read_b128 v[194:197], v171 offset:2048
	ds_read_b128 v[198:201], v171 offset:3072
	ds_read_b128 v[202:205], v171 offset:4096
	ds_read_b128 v[206:209], v171 offset:5120
	ds_read_b128 v[210:213], v171 offset:6144
	ds_read_b128 v[214:217], v171 offset:7168
	global_load_lds_dwordx4 v[164:165], off
	v_lshl_add_u64 v[164:165], s[28:29], 0, v[152:153]
	s_add_i32 m0, s55, 0xe000
	s_nop 0
	global_load_lds_dwordx4 v[164:165], off
	s_waitcnt vmcnt(8)
	s_waitcnt lgkmcnt(0)
	s_barrier
	s_setprio 1
	s_waitcnt lgkmcnt(0)
	v_mfma_f32_16x16x32_bf16 v[140:143], v[120:123], v[184:187], 0
	v_mfma_f32_16x16x32_bf16 v[136:139], v[128:131], v[184:187], 0
	v_mfma_f32_16x16x32_bf16 v[112:115], v[120:123], v[194:197], 0
	v_mfma_f32_16x16x32_bf16 v[104:107], v[128:131], v[194:197], 0
	v_mfma_f32_16x16x32_bf16 v[96:99], v[120:123], v[202:205], 0
	v_mfma_f32_16x16x32_bf16 v[88:91], v[128:131], v[202:205], 0
	v_mfma_f32_16x16x32_bf16 v[80:83], v[120:123], v[210:213], 0
	v_mfma_f32_16x16x32_bf16 v[72:75], v[128:131], v[210:213], 0
	v_mfma_f32_16x16x32_bf16 v[140:143], v[124:127], v[188:191], v[140:143]
	v_mfma_f32_16x16x32_bf16 v[136:139], v[132:135], v[188:191], v[136:139]
	v_mfma_f32_16x16x32_bf16 v[112:115], v[124:127], v[198:201], v[112:115]
	v_mfma_f32_16x16x32_bf16 v[104:107], v[132:135], v[198:201], v[104:107]
	v_mfma_f32_16x16x32_bf16 v[96:99], v[124:127], v[206:209], v[96:99]
	v_mfma_f32_16x16x32_bf16 v[88:91], v[132:135], v[206:209], v[88:91]
	v_mfma_f32_16x16x32_bf16 v[80:83], v[124:127], v[214:217], v[80:83]
	v_mfma_f32_16x16x32_bf16 v[72:75], v[132:135], v[214:217], v[72:75]
	s_setprio 0
	s_setprio 1
	v_mfma_f32_16x16x32_bf16 v[116:119], v[160:163], v[184:187], 0
	v_mfma_f32_16x16x32_bf16 v[108:111], v[176:179], v[184:187], 0
	v_mfma_f32_16x16x32_bf16 v[100:103], v[160:163], v[194:197], 0
	v_mfma_f32_16x16x32_bf16 v[92:95], v[176:179], v[194:197], 0
	v_mfma_f32_16x16x32_bf16 v[84:87], v[160:163], v[202:205], 0
	v_mfma_f32_16x16x32_bf16 v[76:79], v[176:179], v[202:205], 0
	v_mfma_f32_16x16x32_bf16 v[68:71], v[160:163], v[210:213], 0
	v_mfma_f32_16x16x32_bf16 v[64:67], v[176:179], v[210:213], 0
	v_mfma_f32_16x16x32_bf16 v[116:119], v[172:175], v[188:191], v[116:119]
	v_mfma_f32_16x16x32_bf16 v[108:111], v[180:183], v[188:191], v[108:111]
	v_mfma_f32_16x16x32_bf16 v[100:103], v[172:175], v[198:201], v[100:103]
	v_mfma_f32_16x16x32_bf16 v[92:95], v[180:183], v[198:201], v[92:95]
	v_mfma_f32_16x16x32_bf16 v[84:87], v[172:175], v[206:209], v[84:87]
	v_mfma_f32_16x16x32_bf16 v[76:79], v[180:183], v[206:209], v[76:79]
	v_mfma_f32_16x16x32_bf16 v[68:71], v[172:175], v[214:217], v[68:71]
	v_mfma_f32_16x16x32_bf16 v[64:67], v[180:183], v[214:217], v[64:67]
	s_setprio 0
	s_barrier
	s_add_i32 s28, s65, s54
	v_lshl_add_u64 v[164:165], s[34:35], 0, v[146:147]
	s_mov_b32 m0, s28
	ds_read_b128 v[184:187], v171 offset:16384
	ds_read_b128 v[188:191], v171 offset:17408
	ds_read_b128 v[194:197], v171 offset:18432
	ds_read_b128 v[198:201], v171 offset:19456
	ds_read_b128 v[202:205], v171 offset:20480
	ds_read_b128 v[206:209], v171 offset:21504
	ds_read_b128 v[210:213], v171 offset:22528
	ds_read_b128 v[214:217], v171 offset:23552
	global_load_lds_dwordx4 v[164:165], off
	s_add_i32 m0, s28, 0x2000
	s_add_u32 s28, s34, 0x160000
	v_lshl_add_u64 v[218:219], s[34:35], 0, v[150:151]
	s_addc_u32 s29, s35, 0
	s_add_i32 s78, s66, s54
	global_load_lds_dwordx4 v[218:219], off
	v_lshl_add_u64 v[220:221], s[28:29], 0, v[146:147]
	s_mov_b32 m0, s78
	v_lshl_add_u64 v[222:223], s[36:37], 0, v[148:149]
	global_load_lds_dwordx4 v[220:221], off
	v_lshl_add_u64 v[220:221], s[28:29], 0, v[150:151]
	s_add_i32 m0, s78, 0x2000
	s_nop 0
	global_load_lds_dwordx4 v[220:221], off
	v_lshl_add_u64 v[220:221], s[36:37], 0, v[144:145]
	s_mov_b32 m0, s55
	s_nop 0
	global_load_lds_dwordx4 v[220:221], off
	s_mov_b32 m0, s56
	s_nop 0
	global_load_lds_dwordx4 v[222:223], off
	s_waitcnt vmcnt(8)
	s_waitcnt lgkmcnt(0)
	s_barrier
; #define PG8_STAGE(bufoff, gbase, voff) do { _Pragma("unroll") for (int _i = 0; _i < 2; ++_i) \
;         __builtin_amdgcn_global_load_lds((const unsigned*)((const char*)(gbase) + (voff)[_i]), (PG8_LAS unsigned*)(lds + (bufoff) + ldsw + _i * 8192), 16, 0, 0); } while (0)
; #define PG8_LDA(dst, b, h) do { _Pragma("unroll") for (int m = 0; m < 4; ++m) _Pragma("unroll") for (int k = 0; k < 2; ++k) dst[m][k] = *(const PG8_LAS bf16x8*)(lds + PG8_SA(b, h) + aoff + m * 2048 + k * 1024); } while (0)
; #define PG8_LDB(dst, b, h) do { _Pragma("unroll") for (int n = 0; n < 2; ++n) _Pragma("unroll") for (int k = 0; k < 2; ++k) dst[n][k] = *(const PG8_LAS bf16x8*)(lds + PG8_SB(b, h) + boff + n * 2048 + k * 1024); } while (0)
; #define PG8_MMA(ai, bj, At, Bt) do { __builtin_amdgcn_s_setprio(1); _Pragma("unroll") for (int m = 0; m < 4; ++m) _Pragma("unroll") for (int n = 0; n < 2; ++n) _Pragma("unroll") for (int k = 0; k < 2; ++k) \
;         acc[ai][bj][m][n] = __builtin_amdgcn_mfma_f32_16x16x32_bf16(Bt[n][k], At[m][k], acc[ai][bj][m][n], 0, 0, 0); __builtin_amdgcn_s_setprio(0); } while (0)
; #define PG8_WAIT_V(n) asm volatile("s_waitcnt vmcnt(" #n ")" ::: "memory")
; #define PG8_WAIT_L(n) asm volatile("s_waitcnt lgkmcnt(" #n ")" ::: "memory")
; #define PG8_BAR __builtin_amdgcn_s_barrier()
; #define PG8_SCHED __builtin_amdgcn_sched_barrier(0)
; template <class Epi, class Sched, bool ALIGN_EPI = false, bool SP2 = false>
; __device__ __forceinline__ void gemm_phase(PG8_LAS unsigned char* lds, const Gemm g, const Sched& S, const Epi& E) {
;     ...
;             PG8_WAIT_V(8); PG8_WAIT_L(0); PG8_BAR; PG8_MMA(0, 0, At, B0); PG8_MMA(0, 1, At, B1); PG8_BAR; PG8_SCHED;
;             PG8_LDA(At, 0, 1); PG8_STAGE(PG8_SB(0, 0), b2, voffB); PG8_STAGE(PG8_SB(0, 1), b2 + hstep, voffB); PG8_STAGE(PG8_SA(0, 0), a2, voffA);
;             PG8_WAIT_V(8); PG8_WAIT_L(0); PG8_BAR; PG8_MMA(1, 0, At, B0); PG8_MMA(1, 1, At, B1); PG8_BAR; PG8_SCHED;
;             PG8_LDB(B0, 1, 0); PG8_LDB(B1, 1, 1); PG8_SCHED; PG8_LDA(At, 1, 0); PG8_STAGE(PG8_SA(0, 1), a2 + hstep, voffA);
;             PG8_WAIT_V(8); PG8_WAIT_L(0); PG8_BAR; PG8_MMA(0, 0, At, B0); PG8_MMA(0, 1, At, B1); PG8_BAR; PG8_SCHED;
	s_setprio 1
	s_waitcnt lgkmcnt(0)
	v_mfma_f32_16x16x32_bf16 v[60:63], v[120:123], v[184:187], 0
	v_mfma_f32_16x16x32_bf16 v[56:59], v[128:131], v[184:187], 0
	v_mfma_f32_16x16x32_bf16 v[48:51], v[120:123], v[194:197], 0
	v_mfma_f32_16x16x32_bf16 v[40:43], v[128:131], v[194:197], 0
	v_mfma_f32_16x16x32_bf16 v[32:35], v[120:123], v[202:205], 0
	v_mfma_f32_16x16x32_bf16 v[24:27], v[128:131], v[202:205], 0
	v_mfma_f32_16x16x32_bf16 v[16:19], v[120:123], v[210:213], 0
	v_mfma_f32_16x16x32_bf16 v[8:11], v[128:131], v[210:213], 0
	v_mfma_f32_16x16x32_bf16 v[60:63], v[124:127], v[188:191], v[60:63]
	v_mfma_f32_16x16x32_bf16 v[56:59], v[132:135], v[188:191], v[56:59]
	v_mfma_f32_16x16x32_bf16 v[48:51], v[124:127], v[198:201], v[48:51]
	v_mfma_f32_16x16x32_bf16 v[40:43], v[132:135], v[198:201], v[40:43]
	v_mfma_f32_16x16x32_bf16 v[32:35], v[124:127], v[206:209], v[32:35]
	v_mfma_f32_16x16x32_bf16 v[24:27], v[132:135], v[206:209], v[24:27]
	v_mfma_f32_16x16x32_bf16 v[16:19], v[124:127], v[214:217], v[16:19]
	v_mfma_f32_16x16x32_bf16 v[8:11], v[132:135], v[214:217], v[8:11]
	s_setprio 0
	s_setprio 1
	v_mfma_f32_16x16x32_bf16 v[52:55], v[160:163], v[184:187], 0
	v_mfma_f32_16x16x32_bf16 v[44:47], v[176:179], v[184:187], 0
	v_mfma_f32_16x16x32_bf16 v[36:39], v[160:163], v[194:197], 0
	v_mfma_f32_16x16x32_bf16 v[28:31], v[176:179], v[194:197], 0
	v_mfma_f32_16x16x32_bf16 v[20:23], v[160:163], v[202:205], 0
	v_mfma_f32_16x16x32_bf16 v[12:15], v[176:179], v[202:205], 0
	v_mfma_f32_16x16x32_bf16 v[4:7], v[160:163], v[210:213], 0
	v_mfma_f32_16x16x32_bf16 v[0:3], v[176:179], v[210:213], 0
	v_mfma_f32_16x16x32_bf16 v[52:55], v[172:175], v[188:191], v[52:55]
	v_mfma_f32_16x16x32_bf16 v[44:47], v[180:183], v[188:191], v[44:47]
	v_mfma_f32_16x16x32_bf16 v[36:39], v[172:175], v[198:201], v[36:39]
	v_mfma_f32_16x16x32_bf16 v[28:31], v[180:183], v[198:201], v[28:31]
	v_mfma_f32_16x16x32_bf16 v[20:23], v[172:175], v[206:209], v[20:23]
	v_mfma_f32_16x16x32_bf16 v[12:15], v[180:183], v[206:209], v[12:15]
	v_mfma_f32_16x16x32_bf16 v[4:7], v[172:175], v[214:217], v[4:7]
	v_mfma_f32_16x16x32_bf16 v[0:3], v[180:183], v[214:217], v[0:3]
	s_setprio 0
	s_barrier
	s_add_i32 s78, 0, 0x18000
	s_add_i32 s79, 0, 0x1c000
	v_add_u32_e32 v132, s78, v167
	v_add_u32_e32 v180, s79, v167
	ds_read_b128 v[120:123], v132
	ds_read_b128 v[124:127], v132 offset:1024
	ds_read_b128 v[128:131], v132 offset:2048
	ds_read_b128 v[132:135], v132 offset:3072
	ds_read_b128 v[160:163], v180
	ds_read_b128 v[172:175], v180 offset:1024
	ds_read_b128 v[176:179], v180 offset:2048
	ds_read_b128 v[180:183], v180 offset:3072
	s_add_u32 s28, s36, 0x160000
	s_addc_u32 s29, s37, 0
	s_mov_b32 m0, s57
	v_lshl_add_u64 v[224:225], s[28:29], 0, v[144:145]
	ds_read_b128 v[184:187], v171 offset:32768
	ds_read_b128 v[188:191], v171 offset:33792
	ds_read_b128 v[194:197], v171 offset:34816
	ds_read_b128 v[198:201], v171 offset:35840
	ds_read_b128 v[202:205], v171 offset:36864
	ds_read_b128 v[206:209], v171 offset:37888
	ds_read_b128 v[210:213], v171 offset:38912
	ds_read_b128 v[214:217], v171 offset:39936
	global_load_lds_dwordx4 v[224:225], off
	v_lshl_add_u64 v[224:225], s[28:29], 0, v[148:149]
	s_mov_b32 m0, s58
	s_nop 0
	global_load_lds_dwordx4 v[224:225], off
	s_waitcnt vmcnt(8)
	s_waitcnt lgkmcnt(0)
	s_barrier
	s_setprio 1
	s_waitcnt lgkmcnt(0)
	v_mfma_f32_16x16x32_bf16 v[140:143], v[120:123], v[184:187], v[140:143]
	v_mfma_f32_16x16x32_bf16 v[136:139], v[128:131], v[184:187], v[136:139]
	v_mfma_f32_16x16x32_bf16 v[112:115], v[120:123], v[194:197], v[112:115]
	v_mfma_f32_16x16x32_bf16 v[104:107], v[128:131], v[194:197], v[104:107]
	v_mfma_f32_16x16x32_bf16 v[96:99], v[120:123], v[202:205], v[96:99]
	v_mfma_f32_16x16x32_bf16 v[88:91], v[128:131], v[202:205], v[88:91]
	v_mfma_f32_16x16x32_bf16 v[80:83], v[120:123], v[210:213], v[80:83]
	v_mfma_f32_16x16x32_bf16 v[72:75], v[128:131], v[210:213], v[72:75]
	v_mfma_f32_16x16x32_bf16 v[140:143], v[124:127], v[188:191], v[140:143]
	v_mfma_f32_16x16x32_bf16 v[136:139], v[132:135], v[188:191], v[136:139]
	v_mfma_f32_16x16x32_bf16 v[112:115], v[124:127], v[198:201], v[112:115]
	v_mfma_f32_16x16x32_bf16 v[104:107], v[132:135], v[198:201], v[104:107]
	v_mfma_f32_16x16x32_bf16 v[96:99], v[124:127], v[206:209], v[96:99]
	v_mfma_f32_16x16x32_bf16 v[88:91], v[132:135], v[206:209], v[88:91]
	v_mfma_f32_16x16x32_bf16 v[80:83], v[124:127], v[214:217], v[80:83]
	v_mfma_f32_16x16x32_bf16 v[72:75], v[132:135], v[214:217], v[72:75]
	s_setprio 0
	s_setprio 1
	v_mfma_f32_16x16x32_bf16 v[116:119], v[160:163], v[184:187], v[116:119]
	v_mfma_f32_16x16x32_bf16 v[108:111], v[176:179], v[184:187], v[108:111]
	v_mfma_f32_16x16x32_bf16 v[100:103], v[160:163], v[194:197], v[100:103]
	v_mfma_f32_16x16x32_bf16 v[92:95], v[176:179], v[194:197], v[92:95]
	v_mfma_f32_16x16x32_bf16 v[84:87], v[160:163], v[202:205], v[84:87]
	v_mfma_f32_16x16x32_bf16 v[76:79], v[176:179], v[202:205], v[76:79]
	v_mfma_f32_16x16x32_bf16 v[68:71], v[160:163], v[210:213], v[68:71]
	v_mfma_f32_16x16x32_bf16 v[64:67], v[176:179], v[210:213], v[64:67]
	v_mfma_f32_16x16x32_bf16 v[116:119], v[172:175], v[188:191], v[116:119]
	v_mfma_f32_16x16x32_bf16 v[108:111], v[180:183], v[188:191], v[108:111]
	v_mfma_f32_16x16x32_bf16 v[100:103], v[172:175], v[198:201], v[100:103]
	v_mfma_f32_16x16x32_bf16 v[92:95], v[180:183], v[198:201], v[92:95]
	v_mfma_f32_16x16x32_bf16 v[84:87], v[172:175], v[206:209], v[84:87]
	v_mfma_f32_16x16x32_bf16 v[76:79], v[180:183], v[206:209], v[76:79]
	v_mfma_f32_16x16x32_bf16 v[68:71], v[172:175], v[214:217], v[68:71]
	v_mfma_f32_16x16x32_bf16 v[64:67], v[180:183], v[214:217], v[64:67]
	s_setprio 0
	s_barrier
; #define PG8_STAGE(bufoff, gbase, voff) do { _Pragma("unroll") for (int _i = 0; _i < 2; ++_i) \
;         __builtin_amdgcn_global_load_lds((const unsigned*)((const char*)(gbase) + (voff)[_i]), (PG8_LAS unsigned*)(lds + (bufoff) + ldsw + _i * 8192), 16, 0, 0); } while (0)
; #define PG8_LDA(dst, b, h) do { _Pragma("unroll") for (int m = 0; m < 4; ++m) _Pragma("unroll") for (int k = 0; k < 2; ++k) dst[m][k] = *(const PG8_LAS bf16x8*)(lds + PG8_SA(b, h) + aoff + m * 2048 + k * 1024); } while (0)
; #define PG8_MMA(ai, bj, At, Bt) do { __builtin_amdgcn_s_setprio(1); _Pragma("unroll") for (int m = 0; m < 4; ++m) _Pragma("unroll") for (int n = 0; n < 2; ++n) _Pragma("unroll") for (int k = 0; k < 2; ++k) \
;         acc[ai][bj][m][n] = __builtin_amdgcn_mfma_f32_16x16x32_bf16(Bt[n][k], At[m][k], acc[ai][bj][m][n], 0, 0, 0); __builtin_amdgcn_s_setprio(0); } while (0)
; #define PG8_WAIT_V(n) asm volatile("s_waitcnt vmcnt(" #n ")" ::: "memory")
; #define PG8_WAIT_L(n) asm volatile("s_waitcnt lgkmcnt(" #n ")" ::: "memory")
; #define PG8_BAR __builtin_amdgcn_s_barrier()
; #define PG8_SCHED __builtin_amdgcn_sched_barrier(0)
; template <class Epi, class Sched, bool ALIGN_EPI = false, bool SP2 = false>
; __device__ __forceinline__ void gemm_phase(PG8_LAS unsigned char* lds, const Gemm g, const Sched& S, const Epi& E) {
;     ...
;         for (int t = 0; t < nt; t += 2) {
;     ...
;             PG8_LDA(At, 1, 1); PG8_STAGE(PG8_SB(1, 0), b3, voffB); PG8_STAGE(PG8_SB(1, 1), b3 + hstep, voffB); PG8_STAGE(PG8_SA(1, 0), a3, voffA);
;             PG8_WAIT_V(8); PG8_WAIT_L(0); PG8_BAR; PG8_MMA(1, 0, At, B0); PG8_MMA(1, 1, At, B1); PG8_BAR; PG8_SCHED;
	s_add_i32 s28, s78, s54
	v_lshl_add_u64 v[164:165], v[164:165], 0, s[14:15]
	s_mov_b32 m0, s28
	ds_read_b128 v[184:187], v171 offset:49152
	ds_read_b128 v[188:191], v171 offset:50176
	ds_read_b128 v[194:197], v171 offset:51200
	ds_read_b128 v[198:201], v171 offset:52224
	ds_read_b128 v[202:205], v171 offset:53248
	ds_read_b128 v[206:209], v171 offset:54272
	ds_read_b128 v[210:213], v171 offset:55296
	ds_read_b128 v[214:217], v171 offset:56320
	global_load_lds_dwordx4 v[164:165], off
	s_add_i32 m0, s28, 0x2000
	s_add_u32 s28, s34, 0x160080
	v_lshl_add_u64 v[164:165], v[218:219], 0, s[14:15]
	s_addc_u32 s29, s35, 0
	s_add_i32 s34, s79, s54
	global_load_lds_dwordx4 v[164:165], off
	v_lshl_add_u64 v[164:165], s[28:29], 0, v[146:147]
	s_mov_b32 m0, s34
	s_nop 0
	global_load_lds_dwordx4 v[164:165], off
	v_lshl_add_u64 v[164:165], s[28:29], 0, v[150:151]
	s_add_i32 m0, s34, 0x2000
	s_nop 0
	global_load_lds_dwordx4 v[164:165], off
	v_lshl_add_u64 v[164:165], v[220:221], 0, s[14:15]
	s_mov_b32 m0, s62
	s_nop 0
	global_load_lds_dwordx4 v[164:165], off
	v_lshl_add_u64 v[164:165], v[222:223], 0, s[14:15]
	s_mov_b32 m0, s63
	s_nop 0
	global_load_lds_dwordx4 v[164:165], off
	s_waitcnt vmcnt(8)
	s_waitcnt lgkmcnt(0)
	s_barrier
	s_setprio 1
	s_waitcnt lgkmcnt(0)
	v_mfma_f32_16x16x32_bf16 v[60:63], v[120:123], v[184:187], v[60:63]
	v_mfma_f32_16x16x32_bf16 v[56:59], v[128:131], v[184:187], v[56:59]
	v_mfma_f32_16x16x32_bf16 v[48:51], v[120:123], v[194:197], v[48:51]
	v_mfma_f32_16x16x32_bf16 v[40:43], v[128:131], v[194:197], v[40:43]
	v_mfma_f32_16x16x32_bf16 v[32:35], v[120:123], v[202:205], v[32:35]
	v_mfma_f32_16x16x32_bf16 v[24:27], v[128:131], v[202:205], v[24:27]
	v_mfma_f32_16x16x32_bf16 v[16:19], v[120:123], v[210:213], v[16:19]
	v_mfma_f32_16x16x32_bf16 v[8:11], v[128:131], v[210:213], v[8:11]
	v_mfma_f32_16x16x32_bf16 v[60:63], v[124:127], v[188:191], v[60:63]
	v_mfma_f32_16x16x32_bf16 v[56:59], v[132:135], v[188:191], v[56:59]
	v_mfma_f32_16x16x32_bf16 v[48:51], v[124:127], v[198:201], v[48:51]
	v_mfma_f32_16x16x32_bf16 v[40:43], v[132:135], v[198:201], v[40:43]
	v_mfma_f32_16x16x32_bf16 v[32:35], v[124:127], v[206:209], v[32:35]
	v_mfma_f32_16x16x32_bf16 v[24:27], v[132:135], v[206:209], v[24:27]
	v_mfma_f32_16x16x32_bf16 v[16:19], v[124:127], v[214:217], v[16:19]
	v_mfma_f32_16x16x32_bf16 v[8:11], v[132:135], v[214:217], v[8:11]
	s_setprio 0
	s_setprio 1
	v_mfma_f32_16x16x32_bf16 v[52:55], v[160:163], v[184:187], v[52:55]
	v_mfma_f32_16x16x32_bf16 v[44:47], v[176:179], v[184:187], v[44:47]
	v_mfma_f32_16x16x32_bf16 v[36:39], v[160:163], v[194:197], v[36:39]
	v_mfma_f32_16x16x32_bf16 v[28:31], v[176:179], v[194:197], v[28:31]
	v_mfma_f32_16x16x32_bf16 v[20:23], v[160:163], v[202:205], v[20:23]
	v_mfma_f32_16x16x32_bf16 v[12:15], v[176:179], v[202:205], v[12:15]
	v_mfma_f32_16x16x32_bf16 v[4:7], v[160:163], v[210:213], v[4:7]
	v_mfma_f32_16x16x32_bf16 v[0:3], v[176:179], v[210:213], v[0:3]
	v_mfma_f32_16x16x32_bf16 v[52:55], v[172:175], v[188:191], v[52:55]
	v_mfma_f32_16x16x32_bf16 v[44:47], v[180:183], v[188:191], v[44:47]
	v_mfma_f32_16x16x32_bf16 v[36:39], v[172:175], v[198:201], v[36:39]
	v_mfma_f32_16x16x32_bf16 v[28:31], v[180:183], v[198:201], v[28:31]
	v_mfma_f32_16x16x32_bf16 v[20:23], v[172:175], v[206:209], v[20:23]
	v_mfma_f32_16x16x32_bf16 v[12:15], v[180:183], v[206:209], v[12:15]
	v_mfma_f32_16x16x32_bf16 v[4:7], v[172:175], v[214:217], v[4:7]
	v_mfma_f32_16x16x32_bf16 v[0:3], v[180:183], v[214:217], v[0:3]
	s_setprio 0
	s_barrier
	s_add_i32 s77, s77, 2
	s_add_u32 s75, s75, 0x100
	s_addc_u32 s76, s76, 0
	s_cmpk_gt_u32 s77, 0x55
	s_mov_b64 s[28:29], s[30:31]
	s_cbranch_scc1 .Lpeel_exit_3

; #define PG8_STAGE(bufoff, gbase, voff) do { _Pragma("unroll") for (int _i = 0; _i < 2; ++_i) \
;         __builtin_amdgcn_global_load_lds((const unsigned*)((const char*)(gbase) + (voff)[_i]), (PG8_LAS unsigned*)(lds + (bufoff) + ldsw + _i * 8192), 16, 0, 0); } while (0)
; #define PG8_LDA(dst, b, h) do { _Pragma("unroll") for (int m = 0; m < 4; ++m) _Pragma("unroll") for (int k = 0; k < 2; ++k) dst[m][k] = *(const PG8_LAS bf16x8*)(lds + PG8_SA(b, h) + aoff + m * 2048 + k * 1024); } while (0)
; #define PG8_LDB(dst, b, h) do { _Pragma("unroll") for (int n = 0; n < 2; ++n) _Pragma("unroll") for (int k = 0; k < 2; ++k) dst[n][k] = *(const PG8_LAS bf16x8*)(lds + PG8_SB(b, h) + boff + n * 2048 + k * 1024); } while (0)
; #define PG8_MMA(ai, bj, At, Bt) do { __builtin_amdgcn_s_setprio(1); _Pragma("unroll") for (int m = 0; m < 4; ++m) _Pragma("unroll") for (int n = 0; n < 2; ++n) _Pragma("unroll") for (int k = 0; k < 2; ++k) \
;         acc[ai][bj][m][n] = __builtin_amdgcn_mfma_f32_16x16x32_bf16(Bt[n][k], At[m][k], acc[ai][bj][m][n], 0, 0, 0); __builtin_amdgcn_s_setprio(0); } while (0)
; #define PG8_BAR __builtin_amdgcn_s_barrier()
; template <class Epi, class Sched, bool ALIGN_EPI = false, bool SP2 = false>
; __device__ __forceinline__ void gemm_phase(PG8_LAS unsigned char* lds, const Gemm g, const Sched& S, const Epi& E) {
;     ...
;         const bool has_next = S.next(ui + 1, nxt);
;         const char* nA = has_next ? (const char*)g.A + (size_t)nxt.pm * tstep : cA; const char* nB = has_next ? (const char*)g.Bt + (size_t)nxt.pn * tstep : cB;
;         for (int t = 0; t < nt; t += 2) {
;             const bool last = (t == nt - 2);
;             const char* a1 = cA + (size_t)(t + 1) * kstep;
;             const char* a2 = last ? nA : cA + (size_t)(t + 2) * kstep; const char* b2 = last ? nB : cB + (size_t)(t + 2) * kstep;
;             const char* a3 = a2 + kstep; const char* b3 = b2 + kstep;
;             if (last && has_next) S.a_ready(nxt);
;             if constexpr (SP2) {
;             PG8_LDB(B0, 0, 0); PG8_LDB(B1, 0, 1); PG8_SCHED; PG8_LDA(At, 0, 0); PG8_STAGE(PG8_SA(1, 1), a1 + hstep, voffA);
;             PG8_WAIT_V(8); PG8_WAIT_L(0); PG8_BAR; PG8_MMA(0, 0, At, B0); PG8_MMA(0, 1, At, B1); PG8_BAR; PG8_SCHED;
;             PG8_LDA(At, 0, 1); PG8_STAGE(PG8_SB(0, 0), b2, voffB); PG8_STAGE(PG8_SB(0, 1), b2 + hstep, voffB); PG8_STAGE(PG8_SA(0, 0), a2, voffA);
.LBB0_725:
	s_ashr_i32 s17, s16, 31
	s_lshl_b64 s[20:21], s[16:17], 20
	s_add_u32 s20, s52, s20
	s_addc_u32 s21, s53, s21
	s_and_b64 s[22:23], s[6:7], exec
	s_cselect_b32 s17, s21, s31
	s_cselect_b32 s78, s20, s30
	s_ashr_i32 s19, s18, 31
	s_lshl_b64 s[22:23], s[18:19], 20
	s_add_u32 s22, s37, s22
	s_addc_u32 s23, s50, s23
	s_and_b64 s[34:35], s[6:7], exec
	s_cselect_b32 s19, s23, s29
	s_cselect_b32 s79, s22, s28
	s_add_u32 s80, s28, 0x100
	s_addc_u32 s81, s29, 0
	s_add_u32 s28, s30, 0x80080
	s_addc_u32 s29, s31, 0
	s_mov_b32 s82, -2
	ds_read_b128 v[154:157], v150
	ds_read_b128 v[158:161], v150 offset:1024
	ds_read_b128 v[162:165], v150 offset:2048
	ds_read_b128 v[166:169], v150 offset:3072
	ds_read_b128 v[170:173], v151
	ds_read_b128 v[174:177], v151 offset:1024
	ds_read_b128 v[178:181], v151 offset:2048
	ds_read_b128 v[182:185], v151 offset:3072
	s_add_u32 s30, s28, 0xfff80080
	s_addc_u32 s31, s29, -1
	s_cmp_eq_u32 s82, 28
	s_cselect_b32 s35, s17, s31
	s_cselect_b32 s34, s78, s30
	s_cselect_b32 s31, s19, s81
	s_cselect_b32 s30, s79, s80
	v_lshl_add_u64 v[146:147], s[28:29], 0, v[140:141]
	s_add_i32 m0, s25, 0xc000
	ds_read_b128 v[186:189], v152
	ds_read_b128 v[194:197], v152 offset:1024
	ds_read_b128 v[198:201], v152 offset:2048
	ds_read_b128 v[202:205], v152 offset:3072
	ds_read_b128 v[206:209], v152 offset:4096
	ds_read_b128 v[210:213], v152 offset:5120
	ds_read_b128 v[214:217], v152 offset:6144
	ds_read_b128 v[218:221], v152 offset:7168
	global_load_lds_dwordx4 v[146:147], off
	v_lshl_add_u64 v[146:147], s[28:29], 0, v[138:139]
	s_add_i32 m0, s25, 0xe000
	s_nop 0
	global_load_lds_dwordx4 v[146:147], off
	s_waitcnt vmcnt(8)
	s_waitcnt lgkmcnt(0)
	s_barrier
	s_setprio 1
	s_waitcnt lgkmcnt(0)
	v_mfma_f32_16x16x32_bf16 v[124:127], v[154:157], v[186:189], 0
	v_mfma_f32_16x16x32_bf16 v[120:123], v[162:165], v[186:189], 0
	v_mfma_f32_16x16x32_bf16 v[116:119], v[154:157], v[198:201], 0
	v_mfma_f32_16x16x32_bf16 v[108:111], v[162:165], v[198:201], 0
	v_mfma_f32_16x16x32_bf16 v[100:103], v[154:157], v[206:209], 0
	v_mfma_f32_16x16x32_bf16 v[92:95], v[162:165], v[206:209], 0
	v_mfma_f32_16x16x32_bf16 v[84:87], v[154:157], v[214:217], 0
	v_mfma_f32_16x16x32_bf16 v[76:79], v[162:165], v[214:217], 0
	v_mfma_f32_16x16x32_bf16 v[124:127], v[158:161], v[194:197], v[124:127]
	v_mfma_f32_16x16x32_bf16 v[120:123], v[166:169], v[194:197], v[120:123]
	v_mfma_f32_16x16x32_bf16 v[116:119], v[158:161], v[202:205], v[116:119]
	v_mfma_f32_16x16x32_bf16 v[108:111], v[166:169], v[202:205], v[108:111]
	v_mfma_f32_16x16x32_bf16 v[100:103], v[158:161], v[210:213], v[100:103]
	v_mfma_f32_16x16x32_bf16 v[92:95], v[166:169], v[210:213], v[92:95]
	v_mfma_f32_16x16x32_bf16 v[84:87], v[158:161], v[218:221], v[84:87]
	v_mfma_f32_16x16x32_bf16 v[76:79], v[166:169], v[218:221], v[76:79]
	s_setprio 0
	s_setprio 1
	v_mfma_f32_16x16x32_bf16 v[112:115], v[170:173], v[186:189], 0
	v_mfma_f32_16x16x32_bf16 v[104:107], v[178:181], v[186:189], 0
	v_mfma_f32_16x16x32_bf16 v[96:99], v[170:173], v[198:201], 0
	v_mfma_f32_16x16x32_bf16 v[88:91], v[178:181], v[198:201], 0
	v_mfma_f32_16x16x32_bf16 v[80:83], v[170:173], v[206:209], 0
	v_mfma_f32_16x16x32_bf16 v[72:75], v[178:181], v[206:209], 0
	v_mfma_f32_16x16x32_bf16 v[68:71], v[170:173], v[214:217], 0
	v_mfma_f32_16x16x32_bf16 v[64:67], v[178:181], v[214:217], 0
	v_mfma_f32_16x16x32_bf16 v[112:115], v[174:177], v[194:197], v[112:115]
	v_mfma_f32_16x16x32_bf16 v[104:107], v[182:185], v[194:197], v[104:107]
	v_mfma_f32_16x16x32_bf16 v[96:99], v[174:177], v[202:205], v[96:99]
	v_mfma_f32_16x16x32_bf16 v[88:91], v[182:185], v[202:205], v[88:91]
	v_mfma_f32_16x16x32_bf16 v[80:83], v[174:177], v[210:213], v[80:83]
	v_mfma_f32_16x16x32_bf16 v[72:75], v[182:185], v[210:213], v[72:75]
	v_mfma_f32_16x16x32_bf16 v[68:71], v[174:177], v[218:221], v[68:71]
	v_mfma_f32_16x16x32_bf16 v[64:67], v[182:185], v[218:221], v[64:67]
	s_setprio 0
	s_barrier
	s_add_i32 s83, s64, s36
	v_lshl_add_u64 v[146:147], s[30:31], 0, v[132:133]
	s_mov_b32 m0, s83
	ds_read_b128 v[186:189], v152 offset:16384
	ds_read_b128 v[194:197], v152 offset:17408
	ds_read_b128 v[198:201], v152 offset:18432
	ds_read_b128 v[202:205], v152 offset:19456
	ds_read_b128 v[206:209], v152 offset:20480
	ds_read_b128 v[210:213], v152 offset:21504
	ds_read_b128 v[214:217], v152 offset:22528
	ds_read_b128 v[218:221], v152 offset:23552
	global_load_lds_dwordx4 v[146:147], off
	s_add_i32 m0, s83, 0x2000
	s_add_u32 s84, s30, 0x80000
	v_lshl_add_u64 v[190:191], s[30:31], 0, v[128:129]
	s_addc_u32 s85, s31, 0
	s_add_i32 s83, s65, s36
	global_load_lds_dwordx4 v[190:191], off
	v_lshl_add_u64 v[222:223], s[84:85], 0, v[132:133]
	s_mov_b32 m0, s83
	v_lshl_add_u64 v[224:225], s[34:35], 0, v[130:131]
	global_load_lds_dwordx4 v[222:223], off
	v_lshl_add_u64 v[222:223], s[84:85], 0, v[128:129]
	s_add_i32 m0, s83, 0x2000
	s_nop 0
	global_load_lds_dwordx4 v[222:223], off
	v_lshl_add_u64 v[222:223], s[34:35], 0, v[134:135]
	s_mov_b32 m0, s25
	s_nop 0
	global_load_lds_dwordx4 v[222:223], off
	s_mov_b32 m0, s27
	s_nop 0
	global_load_lds_dwordx4 v[224:225], off
	s_waitcnt vmcnt(8)
	s_waitcnt lgkmcnt(0)
	s_barrier
; #define PG8_STAGE(bufoff, gbase, voff) do { _Pragma("unroll") for (int _i = 0; _i < 2; ++_i) \
;         __builtin_amdgcn_global_load_lds((const unsigned*)((const char*)(gbase) + (voff)[_i]), (PG8_LAS unsigned*)(lds + (bufoff) + ldsw + _i * 8192), 16, 0, 0); } while (0)
; #define PG8_LDA(dst, b, h) do { _Pragma("unroll") for (int m = 0; m < 4; ++m) _Pragma("unroll") for (int k = 0; k < 2; ++k) dst[m][k] = *(const PG8_LAS bf16x8*)(lds + PG8_SA(b, h) + aoff + m * 2048 + k * 1024); } while (0)
; #define PG8_LDB(dst, b, h) do { _Pragma("unroll") for (int n = 0; n < 2; ++n) _Pragma("unroll") for (int k = 0; k < 2; ++k) dst[n][k] = *(const PG8_LAS bf16x8*)(lds + PG8_SB(b, h) + boff + n * 2048 + k * 1024); } while (0)
; #define PG8_MMA(ai, bj, At, Bt) do { __builtin_amdgcn_s_setprio(1); _Pragma("unroll") for (int m = 0; m < 4; ++m) _Pragma("unroll") for (int n = 0; n < 2; ++n) _Pragma("unroll") for (int k = 0; k < 2; ++k) \
;         acc[ai][bj][m][n] = __builtin_amdgcn_mfma_f32_16x16x32_bf16(Bt[n][k], At[m][k], acc[ai][bj][m][n], 0, 0, 0); __builtin_amdgcn_s_setprio(0); } while (0)
; #define PG8_WAIT_V(n) asm volatile("s_waitcnt vmcnt(" #n ")" ::: "memory")
; #define PG8_WAIT_L(n) asm volatile("s_waitcnt lgkmcnt(" #n ")" ::: "memory")
; #define PG8_BAR __builtin_amdgcn_s_barrier()
; #define PG8_SCHED __builtin_amdgcn_sched_barrier(0)
; template <class Epi, class Sched, bool ALIGN_EPI = false, bool SP2 = false>
; __device__ __forceinline__ void gemm_phase(PG8_LAS unsigned char* lds, const Gemm g, const Sched& S, const Epi& E) {
;     ...
;             PG8_WAIT_V(8); PG8_WAIT_L(0); PG8_BAR; PG8_MMA(1, 0, At, B0); PG8_MMA(1, 1, At, B1); PG8_BAR; PG8_SCHED;
;             PG8_LDB(B0, 1, 0); PG8_LDB(B1, 1, 1); PG8_SCHED; PG8_LDA(At, 1, 0); PG8_STAGE(PG8_SA(0, 1), a2 + hstep, voffA);
;             PG8_WAIT_V(8); PG8_WAIT_L(0); PG8_BAR; PG8_MMA(0, 0, At, B0); PG8_MMA(0, 1, At, B1); PG8_BAR; PG8_SCHED;
	s_setprio 1
	s_waitcnt lgkmcnt(0)
	v_mfma_f32_16x16x32_bf16 v[60:63], v[154:157], v[186:189], 0
	v_mfma_f32_16x16x32_bf16 v[56:59], v[162:165], v[186:189], 0
	v_mfma_f32_16x16x32_bf16 v[52:55], v[154:157], v[198:201], 0
	v_mfma_f32_16x16x32_bf16 v[44:47], v[162:165], v[198:201], 0
	v_mfma_f32_16x16x32_bf16 v[36:39], v[154:157], v[206:209], 0
	v_mfma_f32_16x16x32_bf16 v[28:31], v[162:165], v[206:209], 0
	v_mfma_f32_16x16x32_bf16 v[20:23], v[154:157], v[214:217], 0
	v_mfma_f32_16x16x32_bf16 v[12:15], v[162:165], v[214:217], 0
	v_mfma_f32_16x16x32_bf16 v[60:63], v[158:161], v[194:197], v[60:63]
	v_mfma_f32_16x16x32_bf16 v[56:59], v[166:169], v[194:197], v[56:59]
	v_mfma_f32_16x16x32_bf16 v[52:55], v[158:161], v[202:205], v[52:55]
	v_mfma_f32_16x16x32_bf16 v[44:47], v[166:169], v[202:205], v[44:47]
	v_mfma_f32_16x16x32_bf16 v[36:39], v[158:161], v[210:213], v[36:39]
	v_mfma_f32_16x16x32_bf16 v[28:31], v[166:169], v[210:213], v[28:31]
	v_mfma_f32_16x16x32_bf16 v[20:23], v[158:161], v[218:221], v[20:23]
	v_mfma_f32_16x16x32_bf16 v[12:15], v[166:169], v[218:221], v[12:15]
	s_setprio 0
	s_setprio 1
	v_mfma_f32_16x16x32_bf16 v[48:51], v[170:173], v[186:189], 0
	v_mfma_f32_16x16x32_bf16 v[40:43], v[178:181], v[186:189], 0
	v_mfma_f32_16x16x32_bf16 v[32:35], v[170:173], v[198:201], 0
	v_mfma_f32_16x16x32_bf16 v[24:27], v[178:181], v[198:201], 0
	v_mfma_f32_16x16x32_bf16 v[16:19], v[170:173], v[206:209], 0
	v_mfma_f32_16x16x32_bf16 v[8:11], v[178:181], v[206:209], 0
	v_mfma_f32_16x16x32_bf16 v[4:7], v[170:173], v[214:217], 0
	v_mfma_f32_16x16x32_bf16 v[0:3], v[178:181], v[214:217], 0
	v_mfma_f32_16x16x32_bf16 v[48:51], v[174:177], v[194:197], v[48:51]
	v_mfma_f32_16x16x32_bf16 v[40:43], v[182:185], v[194:197], v[40:43]
	v_mfma_f32_16x16x32_bf16 v[32:35], v[174:177], v[202:205], v[32:35]
	v_mfma_f32_16x16x32_bf16 v[24:27], v[182:185], v[202:205], v[24:27]
	v_mfma_f32_16x16x32_bf16 v[16:19], v[174:177], v[210:213], v[16:19]
	v_mfma_f32_16x16x32_bf16 v[8:11], v[182:185], v[210:213], v[8:11]
	v_mfma_f32_16x16x32_bf16 v[4:7], v[174:177], v[218:221], v[4:7]
	v_mfma_f32_16x16x32_bf16 v[0:3], v[182:185], v[218:221], v[0:3]
	s_setprio 0
	s_barrier
	s_add_i32 s83, 0, 0x18000
	v_add_u32_e32 v153, s83, v149
	s_add_i32 s84, 0, 0x1c000
	ds_read_b128 v[154:157], v153
	ds_read_b128 v[158:161], v153 offset:1024
	ds_read_b128 v[162:165], v153 offset:2048
	ds_read_b128 v[166:169], v153 offset:3072
	v_add_u32_e32 v153, s84, v149
	ds_read_b128 v[170:173], v153
	ds_read_b128 v[174:177], v153 offset:1024
	ds_read_b128 v[178:181], v153 offset:2048
	ds_read_b128 v[182:185], v153 offset:3072
	s_add_u32 s34, s34, 0x80000
	s_addc_u32 s35, s35, 0
	s_mov_b32 m0, s56
	v_lshl_add_u64 v[226:227], s[34:35], 0, v[134:135]
	ds_read_b128 v[186:189], v152 offset:32768
	ds_read_b128 v[194:197], v152 offset:33792
	ds_read_b128 v[198:201], v152 offset:34816
	ds_read_b128 v[202:205], v152 offset:35840
	ds_read_b128 v[206:209], v152 offset:36864
	ds_read_b128 v[210:213], v152 offset:37888
	ds_read_b128 v[214:217], v152 offset:38912
	ds_read_b128 v[218:221], v152 offset:39936
	global_load_lds_dwordx4 v[226:227], off
	v_lshl_add_u64 v[226:227], s[34:35], 0, v[130:131]
	s_mov_b32 m0, s57
	s_nop 0
	global_load_lds_dwordx4 v[226:227], off
	s_waitcnt vmcnt(8)
	s_waitcnt lgkmcnt(0)
	s_barrier
	s_setprio 1
	s_waitcnt lgkmcnt(0)
	v_mfma_f32_16x16x32_bf16 v[124:127], v[154:157], v[186:189], v[124:127]
	v_mfma_f32_16x16x32_bf16 v[120:123], v[162:165], v[186:189], v[120:123]
	v_mfma_f32_16x16x32_bf16 v[116:119], v[154:157], v[198:201], v[116:119]
	v_mfma_f32_16x16x32_bf16 v[108:111], v[162:165], v[198:201], v[108:111]
	v_mfma_f32_16x16x32_bf16 v[100:103], v[154:157], v[206:209], v[100:103]
	v_mfma_f32_16x16x32_bf16 v[92:95], v[162:165], v[206:209], v[92:95]
	v_mfma_f32_16x16x32_bf16 v[84:87], v[154:157], v[214:217], v[84:87]
	v_mfma_f32_16x16x32_bf16 v[76:79], v[162:165], v[214:217], v[76:79]
	v_mfma_f32_16x16x32_bf16 v[124:127], v[158:161], v[194:197], v[124:127]
	v_mfma_f32_16x16x32_bf16 v[120:123], v[166:169], v[194:197], v[120:123]
	v_mfma_f32_16x16x32_bf16 v[116:119], v[158:161], v[202:205], v[116:119]
	v_mfma_f32_16x16x32_bf16 v[108:111], v[166:169], v[202:205], v[108:111]
	v_mfma_f32_16x16x32_bf16 v[100:103], v[158:161], v[210:213], v[100:103]
	v_mfma_f32_16x16x32_bf16 v[92:95], v[166:169], v[210:213], v[92:95]
	v_mfma_f32_16x16x32_bf16 v[84:87], v[158:161], v[218:221], v[84:87]
	v_mfma_f32_16x16x32_bf16 v[76:79], v[166:169], v[218:221], v[76:79]
	s_setprio 0
	s_setprio 1
	v_mfma_f32_16x16x32_bf16 v[112:115], v[170:173], v[186:189], v[112:115]
	v_mfma_f32_16x16x32_bf16 v[104:107], v[178:181], v[186:189], v[104:107]
	v_mfma_f32_16x16x32_bf16 v[96:99], v[170:173], v[198:201], v[96:99]
	v_mfma_f32_16x16x32_bf16 v[88:91], v[178:181], v[198:201], v[88:91]
	v_mfma_f32_16x16x32_bf16 v[80:83], v[170:173], v[206:209], v[80:83]
	v_mfma_f32_16x16x32_bf16 v[72:75], v[178:181], v[206:209], v[72:75]
	v_mfma_f32_16x16x32_bf16 v[68:71], v[170:173], v[214:217], v[68:71]
	v_mfma_f32_16x16x32_bf16 v[64:67], v[178:181], v[214:217], v[64:67]
	v_mfma_f32_16x16x32_bf16 v[112:115], v[174:177], v[194:197], v[112:115]
	v_mfma_f32_16x16x32_bf16 v[104:107], v[182:185], v[194:197], v[104:107]
	v_mfma_f32_16x16x32_bf16 v[96:99], v[174:177], v[202:205], v[96:99]
	v_mfma_f32_16x16x32_bf16 v[88:91], v[182:185], v[202:205], v[88:91]
	v_mfma_f32_16x16x32_bf16 v[80:83], v[174:177], v[210:213], v[80:83]
	v_mfma_f32_16x16x32_bf16 v[72:75], v[182:185], v[210:213], v[72:75]
	v_mfma_f32_16x16x32_bf16 v[68:71], v[174:177], v[218:221], v[68:71]
	v_mfma_f32_16x16x32_bf16 v[64:67], v[182:185], v[218:221], v[64:67]
	s_setprio 0
	s_barrier
; #define PG8_STAGE(bufoff, gbase, voff) do { _Pragma("unroll") for (int _i = 0; _i < 2; ++_i) \
;         __builtin_amdgcn_global_load_lds((const unsigned*)((const char*)(gbase) + (voff)[_i]), (PG8_LAS unsigned*)(lds + (bufoff) + ldsw + _i * 8192), 16, 0, 0); } while (0)
; #define PG8_LDA(dst, b, h) do { _Pragma("unroll") for (int m = 0; m < 4; ++m) _Pragma("unroll") for (int k = 0; k < 2; ++k) dst[m][k] = *(const PG8_LAS bf16x8*)(lds + PG8_SA(b, h) + aoff + m * 2048 + k * 1024); } while (0)
; #define PG8_MMA(ai, bj, At, Bt) do { __builtin_amdgcn_s_setprio(1); _Pragma("unroll") for (int m = 0; m < 4; ++m) _Pragma("unroll") for (int n = 0; n < 2; ++n) _Pragma("unroll") for (int k = 0; k < 2; ++k) \
;         acc[ai][bj][m][n] = __builtin_amdgcn_mfma_f32_16x16x32_bf16(Bt[n][k], At[m][k], acc[ai][bj][m][n], 0, 0, 0); __builtin_amdgcn_s_setprio(0); } while (0)
; #define PG8_WAIT_V(n) asm volatile("s_waitcnt vmcnt(" #n ")" ::: "memory")
; #define PG8_WAIT_L(n) asm volatile("s_waitcnt lgkmcnt(" #n ")" ::: "memory")
; #define PG8_BAR __builtin_amdgcn_s_barrier()
; #define PG8_SCHED __builtin_amdgcn_sched_barrier(0)
; template <class Epi, class Sched, bool ALIGN_EPI = false, bool SP2 = false>
; __device__ __forceinline__ void gemm_phase(PG8_LAS unsigned char* lds, const Gemm g, const Sched& S, const Epi& E) {
;     ...
;             PG8_LDA(At, 1, 1); PG8_STAGE(PG8_SB(1, 0), b3, voffB); PG8_STAGE(PG8_SB(1, 1), b3 + hstep, voffB); PG8_STAGE(PG8_SA(1, 0), a3, voffA);
;             PG8_WAIT_V(8); PG8_WAIT_L(0); PG8_BAR; PG8_MMA(1, 0, At, B0); PG8_MMA(1, 1, At, B1); PG8_BAR; PG8_SCHED;
	s_add_i32 s34, s83, s36
	v_lshl_add_u64 v[146:147], v[146:147], 0, s[12:13]
	s_mov_b32 m0, s34
	ds_read_b128 v[186:189], v152 offset:49152
	ds_read_b128 v[194:197], v152 offset:50176
	ds_read_b128 v[198:201], v152 offset:51200
	ds_read_b128 v[202:205], v152 offset:52224
	ds_read_b128 v[206:209], v152 offset:53248
	ds_read_b128 v[210:213], v152 offset:54272
	ds_read_b128 v[214:217], v152 offset:55296
	ds_read_b128 v[218:221], v152 offset:56320
	global_load_lds_dwordx4 v[146:147], off
	s_add_i32 m0, s34, 0x2000
	s_add_u32 s30, s30, 0x80080
	v_lshl_add_u64 v[146:147], v[190:191], 0, s[12:13]
	s_addc_u32 s31, s31, 0
	s_add_i32 s34, s84, s36
	global_load_lds_dwordx4 v[146:147], off
	v_lshl_add_u64 v[146:147], s[30:31], 0, v[132:133]
	s_mov_b32 m0, s34
	s_nop 0
	global_load_lds_dwordx4 v[146:147], off
	v_lshl_add_u64 v[146:147], s[30:31], 0, v[128:129]
	s_add_i32 m0, s34, 0x2000
	s_nop 0
	global_load_lds_dwordx4 v[146:147], off
	v_lshl_add_u64 v[146:147], v[222:223], 0, s[12:13]
	s_mov_b32 m0, s59
	s_nop 0
	global_load_lds_dwordx4 v[146:147], off
	v_lshl_add_u64 v[146:147], v[224:225], 0, s[12:13]
	s_mov_b32 m0, s60
	s_nop 0
	global_load_lds_dwordx4 v[146:147], off
	s_waitcnt vmcnt(8)
	s_waitcnt lgkmcnt(0)
	s_barrier
	s_setprio 1
	s_waitcnt lgkmcnt(0)
	v_mfma_f32_16x16x32_bf16 v[60:63], v[154:157], v[186:189], v[60:63]
	v_mfma_f32_16x16x32_bf16 v[56:59], v[162:165], v[186:189], v[56:59]
	v_mfma_f32_16x16x32_bf16 v[52:55], v[154:157], v[198:201], v[52:55]
	v_mfma_f32_16x16x32_bf16 v[44:47], v[162:165], v[198:201], v[44:47]
	v_mfma_f32_16x16x32_bf16 v[36:39], v[154:157], v[206:209], v[36:39]
	v_mfma_f32_16x16x32_bf16 v[28:31], v[162:165], v[206:209], v[28:31]
	v_mfma_f32_16x16x32_bf16 v[20:23], v[154:157], v[214:217], v[20:23]
	v_mfma_f32_16x16x32_bf16 v[12:15], v[162:165], v[214:217], v[12:15]
	v_mfma_f32_16x16x32_bf16 v[60:63], v[158:161], v[194:197], v[60:63]
	v_mfma_f32_16x16x32_bf16 v[56:59], v[166:169], v[194:197], v[56:59]
	v_mfma_f32_16x16x32_bf16 v[52:55], v[158:161], v[202:205], v[52:55]
	v_mfma_f32_16x16x32_bf16 v[44:47], v[166:169], v[202:205], v[44:47]
	v_mfma_f32_16x16x32_bf16 v[36:39], v[158:161], v[210:213], v[36:39]
	v_mfma_f32_16x16x32_bf16 v[28:31], v[166:169], v[210:213], v[28:31]
	v_mfma_f32_16x16x32_bf16 v[20:23], v[158:161], v[218:221], v[20:23]
	v_mfma_f32_16x16x32_bf16 v[12:15], v[166:169], v[218:221], v[12:15]
	s_setprio 0
	s_setprio 1
	v_mfma_f32_16x16x32_bf16 v[48:51], v[170:173], v[186:189], v[48:51]
	v_mfma_f32_16x16x32_bf16 v[40:43], v[178:181], v[186:189], v[40:43]
	v_mfma_f32_16x16x32_bf16 v[32:35], v[170:173], v[198:201], v[32:35]
	v_mfma_f32_16x16x32_bf16 v[24:27], v[178:181], v[198:201], v[24:27]
	v_mfma_f32_16x16x32_bf16 v[16:19], v[170:173], v[206:209], v[16:19]
	v_mfma_f32_16x16x32_bf16 v[8:11], v[178:181], v[206:209], v[8:11]
	v_mfma_f32_16x16x32_bf16 v[4:7], v[170:173], v[214:217], v[4:7]
	v_mfma_f32_16x16x32_bf16 v[0:3], v[178:181], v[214:217], v[0:3]
	v_mfma_f32_16x16x32_bf16 v[48:51], v[174:177], v[194:197], v[48:51]
	v_mfma_f32_16x16x32_bf16 v[40:43], v[182:185], v[194:197], v[40:43]
	v_mfma_f32_16x16x32_bf16 v[32:35], v[174:177], v[202:205], v[32:35]
	v_mfma_f32_16x16x32_bf16 v[24:27], v[182:185], v[202:205], v[24:27]
	v_mfma_f32_16x16x32_bf16 v[16:19], v[174:177], v[210:213], v[16:19]
	v_mfma_f32_16x16x32_bf16 v[8:11], v[182:185], v[210:213], v[8:11]
	v_mfma_f32_16x16x32_bf16 v[4:7], v[174:177], v[218:221], v[4:7]
	v_mfma_f32_16x16x32_bf16 v[0:3], v[182:185], v[218:221], v[0:3]
	s_setprio 0
	s_barrier
	s_add_i32 s82, s82, 2
	s_add_u32 s80, s80, 0x100
	s_addc_u32 s81, s81, 0
	s_add_u32 s28, s28, 0x100
	s_addc_u32 s29, s29, 0
	s_cmp_gt_u32 s82, 29
	s_cbranch_scc1 .Lpeel_exit_4

; #define PG8_STAGE(bufoff, gbase, voff) do { _Pragma("unroll") for (int _i = 0; _i < 2; ++_i) \
;         __builtin_amdgcn_global_load_lds((const unsigned*)((const char*)(gbase) + (voff)[_i]), (PG8_LAS unsigned*)(lds + (bufoff) + ldsw + _i * 8192), 16, 0, 0); } while (0)
; #define PG8_LDA(dst, b, h) do { _Pragma("unroll") for (int m = 0; m < 4; ++m) _Pragma("unroll") for (int k = 0; k < 2; ++k) dst[m][k] = *(const PG8_LAS bf16x8*)(lds + PG8_SA(b, h) + aoff + m * 2048 + k * 1024); } while (0)
; #define PG8_LDB(dst, b, h) do { _Pragma("unroll") for (int n = 0; n < 2; ++n) _Pragma("unroll") for (int k = 0; k < 2; ++k) dst[n][k] = *(const PG8_LAS bf16x8*)(lds + PG8_SB(b, h) + boff + n * 2048 + k * 1024); } while (0)
; #define PG8_MMA(ai, bj, At, Bt) do { __builtin_amdgcn_s_setprio(1); _Pragma("unroll") for (int m = 0; m < 4; ++m) _Pragma("unroll") for (int n = 0; n < 2; ++n) _Pragma("unroll") for (int k = 0; k < 2; ++k) \
;         acc[ai][bj][m][n] = __builtin_amdgcn_mfma_f32_16x16x32_bf16(Bt[n][k], At[m][k], acc[ai][bj][m][n], 0, 0, 0); __builtin_amdgcn_s_setprio(0); } while (0)
; #define PG8_BAR __builtin_amdgcn_s_barrier()
; template <class Epi, class Sched, bool ALIGN_EPI = false, bool SP2 = false>
; __device__ __forceinline__ void gemm_phase(PG8_LAS unsigned char* lds, const Gemm g, const Sched& S, const Epi& E) {
;     ...
;         const bool has_next = S.next(ui + 1, nxt);
;         const char* nA = has_next ? (const char*)g.A + (size_t)nxt.pm * tstep : cA; const char* nB = has_next ? (const char*)g.Bt + (size_t)nxt.pn * tstep : cB;
;         for (int t = 0; t < nt; t += 2) {
;             const bool last = (t == nt - 2);
;             const char* a1 = cA + (size_t)(t + 1) * kstep;
;             const char* a2 = last ? nA : cA + (size_t)(t + 2) * kstep; const char* b2 = last ? nB : cB + (size_t)(t + 2) * kstep;
;             const char* a3 = a2 + kstep; const char* b3 = b2 + kstep;
;             if (last && has_next) S.a_ready(nxt);
;             if constexpr (SP2) {
;             PG8_LDB(B0, 0, 0); PG8_LDB(B1, 0, 1); PG8_SCHED; PG8_LDA(At, 0, 0); PG8_STAGE(PG8_SA(1, 1), a1 + hstep, voffA);
;             PG8_WAIT_V(8); PG8_WAIT_L(0); PG8_BAR; PG8_MMA(0, 0, At, B0); PG8_MMA(0, 1, At, B1); PG8_BAR; PG8_SCHED;
;             PG8_LDA(At, 0, 1); PG8_STAGE(PG8_SB(0, 0), b2, voffB); PG8_STAGE(PG8_SB(0, 1), b2 + hstep, voffB); PG8_STAGE(PG8_SA(0, 0), a2, voffA);
.LBB0_1041:
	s_ashr_i32 s25, s24, 31
	s_lshl_b64 s[28:29], s[24:25], 20
	s_add_u32 s28, s56, s28
	s_addc_u32 s29, s57, s29
	s_and_b64 s[30:31], s[6:7], exec
	s_cselect_b32 s25, s29, s49
	s_cselect_b32 s73, s28, s48
	s_ashr_i32 s27, s26, 31
	s_lshl_b64 s[30:31], s[26:27], 20
	s_add_u32 s30, s54, s30
	s_addc_u32 s31, s55, s31
	s_and_b64 s[50:51], s[6:7], exec
	s_cselect_b32 s27, s31, s47
	s_cselect_b32 s74, s30, s46
	s_add_u32 s75, s46, 0x100
	s_addc_u32 s76, s47, 0
	s_add_u32 s46, s48, 0x80080
	s_addc_u32 s47, s49, 0
	s_mov_b32 s77, -2
	ds_read_b128 v[120:123], v169
	ds_read_b128 v[124:127], v169 offset:1024
	ds_read_b128 v[128:131], v169 offset:2048
	ds_read_b128 v[132:135], v169 offset:3072
	ds_read_b128 v[160:163], v170
	ds_read_b128 v[172:175], v170 offset:1024
	ds_read_b128 v[176:179], v170 offset:2048
	ds_read_b128 v[180:183], v170 offset:3072
	s_add_u32 s48, s46, 0xfff80080
	s_addc_u32 s49, s47, -1
	s_cmp_eq_u32 s77, 28
	s_cselect_b32 s51, s25, s49
	s_cselect_b32 s50, s73, s48
	s_cselect_b32 s49, s27, s76
	s_cselect_b32 s48, s74, s75
	v_lshl_add_u64 v[164:165], s[46:47], 0, v[154:155]
	s_add_i32 m0, s35, 0xc000
	ds_read_b128 v[184:187], v171
	ds_read_b128 v[188:191], v171 offset:1024
	ds_read_b128 v[194:197], v171 offset:2048
	ds_read_b128 v[198:201], v171 offset:3072
	ds_read_b128 v[202:205], v171 offset:4096
	ds_read_b128 v[206:209], v171 offset:5120
	ds_read_b128 v[210:213], v171 offset:6144
	ds_read_b128 v[214:217], v171 offset:7168
	global_load_lds_dwordx4 v[164:165], off
	v_lshl_add_u64 v[164:165], s[46:47], 0, v[152:153]
	s_add_i32 m0, s35, 0xe000
	s_nop 0
	global_load_lds_dwordx4 v[164:165], off
	s_waitcnt vmcnt(8)
	s_waitcnt lgkmcnt(0)
	s_barrier
	s_setprio 1
	s_waitcnt lgkmcnt(0)
	v_mfma_f32_16x16x32_bf16 v[140:143], v[120:123], v[184:187], 0
	v_mfma_f32_16x16x32_bf16 v[136:139], v[128:131], v[184:187], 0
	v_mfma_f32_16x16x32_bf16 v[112:115], v[120:123], v[194:197], 0
	v_mfma_f32_16x16x32_bf16 v[104:107], v[128:131], v[194:197], 0
	v_mfma_f32_16x16x32_bf16 v[96:99], v[120:123], v[202:205], 0
	v_mfma_f32_16x16x32_bf16 v[88:91], v[128:131], v[202:205], 0
	v_mfma_f32_16x16x32_bf16 v[80:83], v[120:123], v[210:213], 0
	v_mfma_f32_16x16x32_bf16 v[72:75], v[128:131], v[210:213], 0
	v_mfma_f32_16x16x32_bf16 v[140:143], v[124:127], v[188:191], v[140:143]
	v_mfma_f32_16x16x32_bf16 v[136:139], v[132:135], v[188:191], v[136:139]
	v_mfma_f32_16x16x32_bf16 v[112:115], v[124:127], v[198:201], v[112:115]
	v_mfma_f32_16x16x32_bf16 v[104:107], v[132:135], v[198:201], v[104:107]
	v_mfma_f32_16x16x32_bf16 v[96:99], v[124:127], v[206:209], v[96:99]
	v_mfma_f32_16x16x32_bf16 v[88:91], v[132:135], v[206:209], v[88:91]
	v_mfma_f32_16x16x32_bf16 v[80:83], v[124:127], v[214:217], v[80:83]
	v_mfma_f32_16x16x32_bf16 v[72:75], v[132:135], v[214:217], v[72:75]
	s_setprio 0
	s_setprio 1
	v_mfma_f32_16x16x32_bf16 v[116:119], v[160:163], v[184:187], 0
	v_mfma_f32_16x16x32_bf16 v[108:111], v[176:179], v[184:187], 0
	v_mfma_f32_16x16x32_bf16 v[100:103], v[160:163], v[194:197], 0
	v_mfma_f32_16x16x32_bf16 v[92:95], v[176:179], v[194:197], 0
	v_mfma_f32_16x16x32_bf16 v[84:87], v[160:163], v[202:205], 0
	v_mfma_f32_16x16x32_bf16 v[76:79], v[176:179], v[202:205], 0
	v_mfma_f32_16x16x32_bf16 v[68:71], v[160:163], v[210:213], 0
	v_mfma_f32_16x16x32_bf16 v[64:67], v[176:179], v[210:213], 0
	v_mfma_f32_16x16x32_bf16 v[116:119], v[172:175], v[188:191], v[116:119]
	v_mfma_f32_16x16x32_bf16 v[108:111], v[180:183], v[188:191], v[108:111]
	v_mfma_f32_16x16x32_bf16 v[100:103], v[172:175], v[198:201], v[100:103]
	v_mfma_f32_16x16x32_bf16 v[92:95], v[180:183], v[198:201], v[92:95]
	v_mfma_f32_16x16x32_bf16 v[84:87], v[172:175], v[206:209], v[84:87]
	v_mfma_f32_16x16x32_bf16 v[76:79], v[180:183], v[206:209], v[76:79]
	v_mfma_f32_16x16x32_bf16 v[68:71], v[172:175], v[214:217], v[68:71]
	v_mfma_f32_16x16x32_bf16 v[64:67], v[180:183], v[214:217], v[64:67]
	s_setprio 0
	s_barrier
	s_add_i32 s78, s67, s58
	v_lshl_add_u64 v[164:165], s[48:49], 0, v[146:147]
	s_mov_b32 m0, s78
	ds_read_b128 v[184:187], v171 offset:16384
	ds_read_b128 v[188:191], v171 offset:17408
	ds_read_b128 v[194:197], v171 offset:18432
	ds_read_b128 v[198:201], v171 offset:19456
	ds_read_b128 v[202:205], v171 offset:20480
	ds_read_b128 v[206:209], v171 offset:21504
	ds_read_b128 v[210:213], v171 offset:22528
	ds_read_b128 v[214:217], v171 offset:23552
	global_load_lds_dwordx4 v[164:165], off
	s_add_i32 m0, s78, 0x2000
	s_add_u32 s78, s48, 0x80000
	v_lshl_add_u64 v[218:219], s[48:49], 0, v[150:151]
	s_addc_u32 s79, s49, 0
	s_add_i32 s80, s68, s58
	global_load_lds_dwordx4 v[218:219], off
	v_lshl_add_u64 v[220:221], s[78:79], 0, v[146:147]
	s_mov_b32 m0, s80
	v_lshl_add_u64 v[222:223], s[50:51], 0, v[148:149]
	global_load_lds_dwordx4 v[220:221], off
	v_lshl_add_u64 v[220:221], s[78:79], 0, v[150:151]
	s_add_i32 m0, s80, 0x2000
	s_nop 0
	global_load_lds_dwordx4 v[220:221], off
	v_lshl_add_u64 v[220:221], s[50:51], 0, v[144:145]
	s_mov_b32 m0, s35
	s_nop 0
	global_load_lds_dwordx4 v[220:221], off
	s_mov_b32 m0, s37
	s_nop 0
	global_load_lds_dwordx4 v[222:223], off
	s_waitcnt vmcnt(8)
	s_waitcnt lgkmcnt(0)
	s_barrier
; #define PG8_STAGE(bufoff, gbase, voff) do { _Pragma("unroll") for (int _i = 0; _i < 2; ++_i) \
;         __builtin_amdgcn_global_load_lds((const unsigned*)((const char*)(gbase) + (voff)[_i]), (PG8_LAS unsigned*)(lds + (bufoff) + ldsw + _i * 8192), 16, 0, 0); } while (0)
; #define PG8_LDA(dst, b, h) do { _Pragma("unroll") for (int m = 0; m < 4; ++m) _Pragma("unroll") for (int k = 0; k < 2; ++k) dst[m][k] = *(const PG8_LAS bf16x8*)(lds + PG8_SA(b, h) + aoff + m * 2048 + k * 1024); } while (0)
; #define PG8_LDB(dst, b, h) do { _Pragma("unroll") for (int n = 0; n < 2; ++n) _Pragma("unroll") for (int k = 0; k < 2; ++k) dst[n][k] = *(const PG8_LAS bf16x8*)(lds + PG8_SB(b, h) + boff + n * 2048 + k * 1024); } while (0)
; #define PG8_MMA(ai, bj, At, Bt) do { __builtin_amdgcn_s_setprio(1); _Pragma("unroll") for (int m = 0; m < 4; ++m) _Pragma("unroll") for (int n = 0; n < 2; ++n) _Pragma("unroll") for (int k = 0; k < 2; ++k) \
;         acc[ai][bj][m][n] = __builtin_amdgcn_mfma_f32_16x16x32_bf16(Bt[n][k], At[m][k], acc[ai][bj][m][n], 0, 0, 0); __builtin_amdgcn_s_setprio(0); } while (0)
; #define PG8_WAIT_V(n) asm volatile("s_waitcnt vmcnt(" #n ")" ::: "memory")
; #define PG8_WAIT_L(n) asm volatile("s_waitcnt lgkmcnt(" #n ")" ::: "memory")
; #define PG8_BAR __builtin_amdgcn_s_barrier()
; #define PG8_SCHED __builtin_amdgcn_sched_barrier(0)
; template <class Epi, class Sched, bool ALIGN_EPI = false, bool SP2 = false>
; __device__ __forceinline__ void gemm_phase(PG8_LAS unsigned char* lds, const Gemm g, const Sched& S, const Epi& E) {
;     ...
;             PG8_WAIT_V(8); PG8_WAIT_L(0); PG8_BAR; PG8_MMA(1, 0, At, B0); PG8_MMA(1, 1, At, B1); PG8_BAR; PG8_SCHED;
;             PG8_LDB(B0, 1, 0); PG8_LDB(B1, 1, 1); PG8_SCHED; PG8_LDA(At, 1, 0); PG8_STAGE(PG8_SA(0, 1), a2 + hstep, voffA);
;             PG8_WAIT_V(8); PG8_WAIT_L(0); PG8_BAR; PG8_MMA(0, 0, At, B0); PG8_MMA(0, 1, At, B1); PG8_BAR; PG8_SCHED;
	s_setprio 1
	s_waitcnt lgkmcnt(0)
	v_mfma_f32_16x16x32_bf16 v[60:63], v[120:123], v[184:187], 0
	v_mfma_f32_16x16x32_bf16 v[56:59], v[128:131], v[184:187], 0
	v_mfma_f32_16x16x32_bf16 v[48:51], v[120:123], v[194:197], 0
	v_mfma_f32_16x16x32_bf16 v[40:43], v[128:131], v[194:197], 0
	v_mfma_f32_16x16x32_bf16 v[32:35], v[120:123], v[202:205], 0
	v_mfma_f32_16x16x32_bf16 v[24:27], v[128:131], v[202:205], 0
	v_mfma_f32_16x16x32_bf16 v[16:19], v[120:123], v[210:213], 0
	v_mfma_f32_16x16x32_bf16 v[8:11], v[128:131], v[210:213], 0
	v_mfma_f32_16x16x32_bf16 v[60:63], v[124:127], v[188:191], v[60:63]
	v_mfma_f32_16x16x32_bf16 v[56:59], v[132:135], v[188:191], v[56:59]
	v_mfma_f32_16x16x32_bf16 v[48:51], v[124:127], v[198:201], v[48:51]
	v_mfma_f32_16x16x32_bf16 v[40:43], v[132:135], v[198:201], v[40:43]
	v_mfma_f32_16x16x32_bf16 v[32:35], v[124:127], v[206:209], v[32:35]
	v_mfma_f32_16x16x32_bf16 v[24:27], v[132:135], v[206:209], v[24:27]
	v_mfma_f32_16x16x32_bf16 v[16:19], v[124:127], v[214:217], v[16:19]
	v_mfma_f32_16x16x32_bf16 v[8:11], v[132:135], v[214:217], v[8:11]
	s_setprio 0
	s_setprio 1
	v_mfma_f32_16x16x32_bf16 v[52:55], v[160:163], v[184:187], 0
	v_mfma_f32_16x16x32_bf16 v[44:47], v[176:179], v[184:187], 0
	v_mfma_f32_16x16x32_bf16 v[36:39], v[160:163], v[194:197], 0
	v_mfma_f32_16x16x32_bf16 v[28:31], v[176:179], v[194:197], 0
	v_mfma_f32_16x16x32_bf16 v[20:23], v[160:163], v[202:205], 0
	v_mfma_f32_16x16x32_bf16 v[12:15], v[176:179], v[202:205], 0
	v_mfma_f32_16x16x32_bf16 v[4:7], v[160:163], v[210:213], 0
	v_mfma_f32_16x16x32_bf16 v[0:3], v[176:179], v[210:213], 0
	v_mfma_f32_16x16x32_bf16 v[52:55], v[172:175], v[188:191], v[52:55]
	v_mfma_f32_16x16x32_bf16 v[44:47], v[180:183], v[188:191], v[44:47]
	v_mfma_f32_16x16x32_bf16 v[36:39], v[172:175], v[198:201], v[36:39]
	v_mfma_f32_16x16x32_bf16 v[28:31], v[180:183], v[198:201], v[28:31]
	v_mfma_f32_16x16x32_bf16 v[20:23], v[172:175], v[206:209], v[20:23]
	v_mfma_f32_16x16x32_bf16 v[12:15], v[180:183], v[206:209], v[12:15]
	v_mfma_f32_16x16x32_bf16 v[4:7], v[172:175], v[214:217], v[4:7]
	v_mfma_f32_16x16x32_bf16 v[0:3], v[180:183], v[214:217], v[0:3]
	s_setprio 0
	s_barrier
	s_add_i32 s78, 0, 0x18000
	s_add_i32 s79, 0, 0x1c000
	v_add_u32_e32 v132, s78, v167
	v_add_u32_e32 v180, s79, v167
	ds_read_b128 v[120:123], v132
	ds_read_b128 v[124:127], v132 offset:1024
	ds_read_b128 v[128:131], v132 offset:2048
	ds_read_b128 v[132:135], v132 offset:3072
	ds_read_b128 v[160:163], v180
	ds_read_b128 v[172:175], v180 offset:1024
	ds_read_b128 v[176:179], v180 offset:2048
	ds_read_b128 v[180:183], v180 offset:3072
	s_add_u32 s50, s50, 0x80000
	s_addc_u32 s51, s51, 0
	s_mov_b32 m0, s59
	v_lshl_add_u64 v[224:225], s[50:51], 0, v[144:145]
	ds_read_b128 v[184:187], v171 offset:32768
	ds_read_b128 v[188:191], v171 offset:33792
	ds_read_b128 v[194:197], v171 offset:34816
	ds_read_b128 v[198:201], v171 offset:35840
	ds_read_b128 v[202:205], v171 offset:36864
	ds_read_b128 v[206:209], v171 offset:37888
	ds_read_b128 v[210:213], v171 offset:38912
	ds_read_b128 v[214:217], v171 offset:39936
	global_load_lds_dwordx4 v[224:225], off
	v_lshl_add_u64 v[224:225], s[50:51], 0, v[148:149]
	s_mov_b32 m0, s60
	s_nop 0
	global_load_lds_dwordx4 v[224:225], off
	s_waitcnt vmcnt(8)
	s_waitcnt lgkmcnt(0)
	s_barrier
	s_setprio 1
	s_waitcnt lgkmcnt(0)
	v_mfma_f32_16x16x32_bf16 v[140:143], v[120:123], v[184:187], v[140:143]
	v_mfma_f32_16x16x32_bf16 v[136:139], v[128:131], v[184:187], v[136:139]
	v_mfma_f32_16x16x32_bf16 v[112:115], v[120:123], v[194:197], v[112:115]
	v_mfma_f32_16x16x32_bf16 v[104:107], v[128:131], v[194:197], v[104:107]
	v_mfma_f32_16x16x32_bf16 v[96:99], v[120:123], v[202:205], v[96:99]
	v_mfma_f32_16x16x32_bf16 v[88:91], v[128:131], v[202:205], v[88:91]
	v_mfma_f32_16x16x32_bf16 v[80:83], v[120:123], v[210:213], v[80:83]
	v_mfma_f32_16x16x32_bf16 v[72:75], v[128:131], v[210:213], v[72:75]
	v_mfma_f32_16x16x32_bf16 v[140:143], v[124:127], v[188:191], v[140:143]
	v_mfma_f32_16x16x32_bf16 v[136:139], v[132:135], v[188:191], v[136:139]
	v_mfma_f32_16x16x32_bf16 v[112:115], v[124:127], v[198:201], v[112:115]
	v_mfma_f32_16x16x32_bf16 v[104:107], v[132:135], v[198:201], v[104:107]
	v_mfma_f32_16x16x32_bf16 v[96:99], v[124:127], v[206:209], v[96:99]
	v_mfma_f32_16x16x32_bf16 v[88:91], v[132:135], v[206:209], v[88:91]
	v_mfma_f32_16x16x32_bf16 v[80:83], v[124:127], v[214:217], v[80:83]
	v_mfma_f32_16x16x32_bf16 v[72:75], v[132:135], v[214:217], v[72:75]
	s_setprio 0
	s_setprio 1
	v_mfma_f32_16x16x32_bf16 v[116:119], v[160:163], v[184:187], v[116:119]
	v_mfma_f32_16x16x32_bf16 v[108:111], v[176:179], v[184:187], v[108:111]
	v_mfma_f32_16x16x32_bf16 v[100:103], v[160:163], v[194:197], v[100:103]
	v_mfma_f32_16x16x32_bf16 v[92:95], v[176:179], v[194:197], v[92:95]
	v_mfma_f32_16x16x32_bf16 v[84:87], v[160:163], v[202:205], v[84:87]
	v_mfma_f32_16x16x32_bf16 v[76:79], v[176:179], v[202:205], v[76:79]
	v_mfma_f32_16x16x32_bf16 v[68:71], v[160:163], v[210:213], v[68:71]
	v_mfma_f32_16x16x32_bf16 v[64:67], v[176:179], v[210:213], v[64:67]
	v_mfma_f32_16x16x32_bf16 v[116:119], v[172:175], v[188:191], v[116:119]
	v_mfma_f32_16x16x32_bf16 v[108:111], v[180:183], v[188:191], v[108:111]
	v_mfma_f32_16x16x32_bf16 v[100:103], v[172:175], v[198:201], v[100:103]
	v_mfma_f32_16x16x32_bf16 v[92:95], v[180:183], v[198:201], v[92:95]
	v_mfma_f32_16x16x32_bf16 v[84:87], v[172:175], v[206:209], v[84:87]
	v_mfma_f32_16x16x32_bf16 v[76:79], v[180:183], v[206:209], v[76:79]
	v_mfma_f32_16x16x32_bf16 v[68:71], v[172:175], v[214:217], v[68:71]
	v_mfma_f32_16x16x32_bf16 v[64:67], v[180:183], v[214:217], v[64:67]
	s_setprio 0
	s_barrier
; #define PG8_STAGE(bufoff, gbase, voff) do { _Pragma("unroll") for (int _i = 0; _i < 2; ++_i) \
;         __builtin_amdgcn_global_load_lds((const unsigned*)((const char*)(gbase) + (voff)[_i]), (PG8_LAS unsigned*)(lds + (bufoff) + ldsw + _i * 8192), 16, 0, 0); } while (0)
; #define PG8_LDA(dst, b, h) do { _Pragma("unroll") for (int m = 0; m < 4; ++m) _Pragma("unroll") for (int k = 0; k < 2; ++k) dst[m][k] = *(const PG8_LAS bf16x8*)(lds + PG8_SA(b, h) + aoff + m * 2048 + k * 1024); } while (0)
; #define PG8_MMA(ai, bj, At, Bt) do { __builtin_amdgcn_s_setprio(1); _Pragma("unroll") for (int m = 0; m < 4; ++m) _Pragma("unroll") for (int n = 0; n < 2; ++n) _Pragma("unroll") for (int k = 0; k < 2; ++k) \
;         acc[ai][bj][m][n] = __builtin_amdgcn_mfma_f32_16x16x32_bf16(Bt[n][k], At[m][k], acc[ai][bj][m][n], 0, 0, 0); __builtin_amdgcn_s_setprio(0); } while (0)
; #define PG8_WAIT_V(n) asm volatile("s_waitcnt vmcnt(" #n ")" ::: "memory")
; #define PG8_WAIT_L(n) asm volatile("s_waitcnt lgkmcnt(" #n ")" ::: "memory")
; #define PG8_BAR __builtin_amdgcn_s_barrier()
; #define PG8_SCHED __builtin_amdgcn_sched_barrier(0)
; template <class Epi, class Sched, bool ALIGN_EPI = false, bool SP2 = false>
; __device__ __forceinline__ void gemm_phase(PG8_LAS unsigned char* lds, const Gemm g, const Sched& S, const Epi& E) {
;     ...
;             PG8_LDA(At, 1, 1); PG8_STAGE(PG8_SB(1, 0), b3, voffB); PG8_STAGE(PG8_SB(1, 1), b3 + hstep, voffB); PG8_STAGE(PG8_SA(1, 0), a3, voffA);
;             PG8_WAIT_V(8); PG8_WAIT_L(0); PG8_BAR; PG8_MMA(1, 0, At, B0); PG8_MMA(1, 1, At, B1); PG8_BAR; PG8_SCHED;
	s_add_i32 s50, s78, s58
	v_lshl_add_u64 v[164:165], v[164:165], 0, s[14:15]
	s_mov_b32 m0, s50
	ds_read_b128 v[184:187], v171 offset:49152
	ds_read_b128 v[188:191], v171 offset:50176
	ds_read_b128 v[194:197], v171 offset:51200
	ds_read_b128 v[198:201], v171 offset:52224
	ds_read_b128 v[202:205], v171 offset:53248
	ds_read_b128 v[206:209], v171 offset:54272
	ds_read_b128 v[210:213], v171 offset:55296
	ds_read_b128 v[214:217], v171 offset:56320
	global_load_lds_dwordx4 v[164:165], off
	s_add_i32 m0, s50, 0x2000
	s_add_u32 s48, s48, 0x80080
	v_lshl_add_u64 v[164:165], v[218:219], 0, s[14:15]
	s_addc_u32 s49, s49, 0
	s_add_i32 s50, s79, s58
	global_load_lds_dwordx4 v[164:165], off
	v_lshl_add_u64 v[164:165], s[48:49], 0, v[146:147]
	s_mov_b32 m0, s50
	s_nop 0
	global_load_lds_dwordx4 v[164:165], off
	v_lshl_add_u64 v[164:165], s[48:49], 0, v[150:151]
	s_add_i32 m0, s50, 0x2000
	s_nop 0
	global_load_lds_dwordx4 v[164:165], off
	v_lshl_add_u64 v[164:165], v[220:221], 0, s[14:15]
	s_mov_b32 m0, s64
	s_nop 0
	global_load_lds_dwordx4 v[164:165], off
	v_lshl_add_u64 v[164:165], v[222:223], 0, s[14:15]
	s_mov_b32 m0, s65
	s_nop 0
	global_load_lds_dwordx4 v[164:165], off
	s_waitcnt vmcnt(8)
	s_waitcnt lgkmcnt(0)
	s_barrier
	s_setprio 1
	s_waitcnt lgkmcnt(0)
	v_mfma_f32_16x16x32_bf16 v[60:63], v[120:123], v[184:187], v[60:63]
	v_mfma_f32_16x16x32_bf16 v[56:59], v[128:131], v[184:187], v[56:59]
	v_mfma_f32_16x16x32_bf16 v[48:51], v[120:123], v[194:197], v[48:51]
	v_mfma_f32_16x16x32_bf16 v[40:43], v[128:131], v[194:197], v[40:43]
	v_mfma_f32_16x16x32_bf16 v[32:35], v[120:123], v[202:205], v[32:35]
	v_mfma_f32_16x16x32_bf16 v[24:27], v[128:131], v[202:205], v[24:27]
	v_mfma_f32_16x16x32_bf16 v[16:19], v[120:123], v[210:213], v[16:19]
	v_mfma_f32_16x16x32_bf16 v[8:11], v[128:131], v[210:213], v[8:11]
	v_mfma_f32_16x16x32_bf16 v[60:63], v[124:127], v[188:191], v[60:63]
	v_mfma_f32_16x16x32_bf16 v[56:59], v[132:135], v[188:191], v[56:59]
	v_mfma_f32_16x16x32_bf16 v[48:51], v[124:127], v[198:201], v[48:51]
	v_mfma_f32_16x16x32_bf16 v[40:43], v[132:135], v[198:201], v[40:43]
	v_mfma_f32_16x16x32_bf16 v[32:35], v[124:127], v[206:209], v[32:35]
	v_mfma_f32_16x16x32_bf16 v[24:27], v[132:135], v[206:209], v[24:27]
	v_mfma_f32_16x16x32_bf16 v[16:19], v[124:127], v[214:217], v[16:19]
	v_mfma_f32_16x16x32_bf16 v[8:11], v[132:135], v[214:217], v[8:11]
	s_setprio 0
	s_setprio 1
	v_mfma_f32_16x16x32_bf16 v[52:55], v[160:163], v[184:187], v[52:55]
	v_mfma_f32_16x16x32_bf16 v[44:47], v[176:179], v[184:187], v[44:47]
	v_mfma_f32_16x16x32_bf16 v[36:39], v[160:163], v[194:197], v[36:39]
	v_mfma_f32_16x16x32_bf16 v[28:31], v[176:179], v[194:197], v[28:31]
	v_mfma_f32_16x16x32_bf16 v[20:23], v[160:163], v[202:205], v[20:23]
	v_mfma_f32_16x16x32_bf16 v[12:15], v[176:179], v[202:205], v[12:15]
	v_mfma_f32_16x16x32_bf16 v[4:7], v[160:163], v[210:213], v[4:7]
	v_mfma_f32_16x16x32_bf16 v[0:3], v[176:179], v[210:213], v[0:3]
	v_mfma_f32_16x16x32_bf16 v[52:55], v[172:175], v[188:191], v[52:55]
	v_mfma_f32_16x16x32_bf16 v[44:47], v[180:183], v[188:191], v[44:47]
	v_mfma_f32_16x16x32_bf16 v[36:39], v[172:175], v[198:201], v[36:39]
	v_mfma_f32_16x16x32_bf16 v[28:31], v[180:183], v[198:201], v[28:31]
	v_mfma_f32_16x16x32_bf16 v[20:23], v[172:175], v[206:209], v[20:23]
	v_mfma_f32_16x16x32_bf16 v[12:15], v[180:183], v[206:209], v[12:15]
	v_mfma_f32_16x16x32_bf16 v[4:7], v[172:175], v[214:217], v[4:7]
	v_mfma_f32_16x16x32_bf16 v[0:3], v[180:183], v[214:217], v[0:3]
	s_setprio 0
	s_barrier
	s_add_i32 s77, s77, 2
	s_add_u32 s75, s75, 0x100
	s_addc_u32 s76, s76, 0
	s_add_u32 s46, s46, 0x100
	s_addc_u32 s47, s47, 0
	s_cmp_gt_u32 s77, 29
	s_cbranch_scc1 .Lpeel_exit_5

; #define PG8_STAGE(bufoff, gbase, voff) do { _Pragma("unroll") for (int _i = 0; _i < 2; ++_i) \
;         __builtin_amdgcn_global_load_lds((const unsigned*)((const char*)(gbase) + (voff)[_i]), (PG8_LAS unsigned*)(lds + (bufoff) + ldsw + _i * 8192), 16, 0, 0); } while (0)
; #define PG8_LDA(dst, b, h) do { _Pragma("unroll") for (int m = 0; m < 4; ++m) _Pragma("unroll") for (int k = 0; k < 2; ++k) dst[m][k] = *(const PG8_LAS bf16x8*)(lds + PG8_SA(b, h) + aoff + m * 2048 + k * 1024); } while (0)
; #define PG8_LDB(dst, b, h) do { _Pragma("unroll") for (int n = 0; n < 2; ++n) _Pragma("unroll") for (int k = 0; k < 2; ++k) dst[n][k] = *(const PG8_LAS bf16x8*)(lds + PG8_SB(b, h) + boff + n * 2048 + k * 1024); } while (0)
; #define PG8_MMA(ai, bj, At, Bt) do { __builtin_amdgcn_s_setprio(1); _Pragma("unroll") for (int m = 0; m < 4; ++m) _Pragma("unroll") for (int n = 0; n < 2; ++n) _Pragma("unroll") for (int k = 0; k < 2; ++k) \
;         acc[ai][bj][m][n] = __builtin_amdgcn_mfma_f32_16x16x32_bf16(Bt[n][k], At[m][k], acc[ai][bj][m][n], 0, 0, 0); __builtin_amdgcn_s_setprio(0); } while (0)
; #define PG8_BAR __builtin_amdgcn_s_barrier()
; template <class Epi, class Sched, bool ALIGN_EPI = false, bool SP2 = false>
; __device__ __forceinline__ void gemm_phase(PG8_LAS unsigned char* lds, const Gemm g, const Sched& S, const Epi& E) {
;     ...
;         const bool has_next = S.next(ui + 1, nxt);
;         const char* nA = has_next ? (const char*)g.A + (size_t)nxt.pm * tstep : cA; const char* nB = has_next ? (const char*)g.Bt + (size_t)nxt.pn * tstep : cB;
;         for (int t = 0; t < nt; t += 2) {
;             const bool last = (t == nt - 2);
;             const char* a1 = cA + (size_t)(t + 1) * kstep;
;             const char* a2 = last ? nA : cA + (size_t)(t + 2) * kstep; const char* b2 = last ? nB : cB + (size_t)(t + 2) * kstep;
;             const char* a3 = a2 + kstep; const char* b3 = b2 + kstep;
;             if (last && has_next) S.a_ready(nxt);
;             if constexpr (SP2) {
;             PG8_LDB(B0, 0, 0); PG8_LDB(B1, 0, 1); PG8_SCHED; PG8_LDA(At, 0, 0); PG8_STAGE(PG8_SA(1, 1), a1 + hstep, voffA);
;             PG8_WAIT_V(8); PG8_WAIT_L(0); PG8_BAR; PG8_MMA(0, 0, At, B0); PG8_MMA(0, 1, At, B1); PG8_BAR; PG8_SCHED;
;             PG8_LDA(At, 0, 1); PG8_STAGE(PG8_SB(0, 0), b2, voffB); PG8_STAGE(PG8_SB(0, 1), b2 + hstep, voffB); PG8_STAGE(PG8_SA(0, 0), a2, voffA);
.LBB0_1169:
	s_ashr_i32 s17, s16, 31
	s_lshl_b64 s[20:21], s[16:17], 20
	s_add_u32 s20, s37, s20
	s_addc_u32 s21, s46, s21
	s_and_b64 s[22:23], s[6:7], exec
	s_cselect_b32 s17, s21, s31
	s_cselect_b32 s61, s20, s30
	s_ashr_i32 s19, s18, 31
	s_lshl_b64 s[22:23], s[18:19], 20
	s_add_u32 s22, s47, s22
	s_addc_u32 s23, s48, s23
	s_and_b64 s[34:35], s[6:7], exec
	s_cselect_b32 s19, s23, s29
	s_cselect_b32 s62, s22, s28
	s_add_u32 s63, s28, 0x100
	s_addc_u32 s64, s29, 0
	s_add_u32 s28, s30, 0x80080
	s_addc_u32 s29, s31, 0
	s_mov_b32 s65, -2
	ds_read_b128 v[144:147], v151
	ds_read_b128 v[154:157], v151 offset:1024
	ds_read_b128 v[158:161], v151 offset:2048
	ds_read_b128 v[162:165], v151 offset:3072
	ds_read_b128 v[166:169], v152
	ds_read_b128 v[170:173], v152 offset:1024
	ds_read_b128 v[174:177], v152 offset:2048
	ds_read_b128 v[178:181], v152 offset:3072
	s_add_u32 s30, s28, 0xfff80080
	s_addc_u32 s31, s29, -1
	s_cmp_eq_u32 s65, 28
	s_cselect_b32 s35, s17, s31
	s_cselect_b32 s34, s61, s30
	s_cselect_b32 s31, s19, s64
	s_cselect_b32 s30, s62, s63
	v_lshl_add_u64 v[190:191], s[28:29], 0, v[138:139]
	s_add_i32 m0, s25, 0xc000
	ds_read_b128 v[182:185], v153
	ds_read_b128 v[186:189], v153 offset:1024
	ds_read_b128 v[194:197], v153 offset:2048
	ds_read_b128 v[198:201], v153 offset:3072
	ds_read_b128 v[202:205], v153 offset:4096
	ds_read_b128 v[206:209], v153 offset:5120
	ds_read_b128 v[210:213], v153 offset:6144
	ds_read_b128 v[214:217], v153 offset:7168
	global_load_lds_dwordx4 v[190:191], off
	v_lshl_add_u64 v[190:191], s[28:29], 0, v[136:137]
	s_add_i32 m0, s25, 0xe000
	s_nop 0
	global_load_lds_dwordx4 v[190:191], off
	s_waitcnt vmcnt(8)
	s_waitcnt lgkmcnt(0)
	s_barrier
	s_setprio 1
	s_waitcnt lgkmcnt(0)
	v_mfma_f32_16x16x32_bf16 v[124:127], v[144:147], v[182:185], 0
	v_mfma_f32_16x16x32_bf16 v[120:123], v[158:161], v[182:185], 0
	v_mfma_f32_16x16x32_bf16 v[108:111], v[144:147], v[194:197], 0
	v_mfma_f32_16x16x32_bf16 v[104:107], v[158:161], v[194:197], 0
	v_mfma_f32_16x16x32_bf16 v[92:95], v[144:147], v[202:205], 0
	v_mfma_f32_16x16x32_bf16 v[88:91], v[158:161], v[202:205], 0
	v_mfma_f32_16x16x32_bf16 v[76:79], v[144:147], v[210:213], 0
	v_mfma_f32_16x16x32_bf16 v[72:75], v[158:161], v[210:213], 0
	v_mfma_f32_16x16x32_bf16 v[124:127], v[154:157], v[186:189], v[124:127]
	v_mfma_f32_16x16x32_bf16 v[120:123], v[162:165], v[186:189], v[120:123]
	v_mfma_f32_16x16x32_bf16 v[108:111], v[154:157], v[198:201], v[108:111]
	v_mfma_f32_16x16x32_bf16 v[104:107], v[162:165], v[198:201], v[104:107]
	v_mfma_f32_16x16x32_bf16 v[92:95], v[154:157], v[206:209], v[92:95]
	v_mfma_f32_16x16x32_bf16 v[88:91], v[162:165], v[206:209], v[88:91]
	v_mfma_f32_16x16x32_bf16 v[76:79], v[154:157], v[214:217], v[76:79]
	v_mfma_f32_16x16x32_bf16 v[72:75], v[162:165], v[214:217], v[72:75]
	s_setprio 0
	s_setprio 1
	v_mfma_f32_16x16x32_bf16 v[116:119], v[166:169], v[182:185], 0
	v_mfma_f32_16x16x32_bf16 v[112:115], v[174:177], v[182:185], 0
	v_mfma_f32_16x16x32_bf16 v[100:103], v[166:169], v[194:197], 0
	v_mfma_f32_16x16x32_bf16 v[96:99], v[174:177], v[194:197], 0
	v_mfma_f32_16x16x32_bf16 v[84:87], v[166:169], v[202:205], 0
	v_mfma_f32_16x16x32_bf16 v[80:83], v[174:177], v[202:205], 0
	v_mfma_f32_16x16x32_bf16 v[68:71], v[166:169], v[210:213], 0
	v_mfma_f32_16x16x32_bf16 v[64:67], v[174:177], v[210:213], 0
	v_mfma_f32_16x16x32_bf16 v[116:119], v[170:173], v[186:189], v[116:119]
	v_mfma_f32_16x16x32_bf16 v[112:115], v[178:181], v[186:189], v[112:115]
	v_mfma_f32_16x16x32_bf16 v[100:103], v[170:173], v[198:201], v[100:103]
	v_mfma_f32_16x16x32_bf16 v[96:99], v[178:181], v[198:201], v[96:99]
	v_mfma_f32_16x16x32_bf16 v[84:87], v[170:173], v[206:209], v[84:87]
	v_mfma_f32_16x16x32_bf16 v[80:83], v[178:181], v[206:209], v[80:83]
	v_mfma_f32_16x16x32_bf16 v[68:71], v[170:173], v[214:217], v[68:71]
	v_mfma_f32_16x16x32_bf16 v[64:67], v[178:181], v[214:217], v[64:67]
	s_setprio 0
	s_barrier
	s_add_i32 s66, s58, s49
	v_lshl_add_u64 v[190:191], s[30:31], 0, v[132:133]
	s_mov_b32 m0, s66
	ds_read_b128 v[182:185], v153 offset:16384
	ds_read_b128 v[186:189], v153 offset:17408
	ds_read_b128 v[194:197], v153 offset:18432
	ds_read_b128 v[198:201], v153 offset:19456
	ds_read_b128 v[202:205], v153 offset:20480
	ds_read_b128 v[206:209], v153 offset:21504
	ds_read_b128 v[210:213], v153 offset:22528
	ds_read_b128 v[214:217], v153 offset:23552
	global_load_lds_dwordx4 v[190:191], off
	s_add_i32 m0, s66, 0x2000
	s_add_u32 s66, s30, 0x80000
	v_lshl_add_u64 v[218:219], s[30:31], 0, v[128:129]
	s_addc_u32 s67, s31, 0
	s_add_i32 s68, s59, s49
	global_load_lds_dwordx4 v[218:219], off
	v_lshl_add_u64 v[220:221], s[66:67], 0, v[132:133]
	s_mov_b32 m0, s68
	v_lshl_add_u64 v[222:223], s[34:35], 0, v[130:131]
	global_load_lds_dwordx4 v[220:221], off
	v_lshl_add_u64 v[220:221], s[66:67], 0, v[128:129]
	s_add_i32 m0, s68, 0x2000
	s_nop 0
	global_load_lds_dwordx4 v[220:221], off
	v_lshl_add_u64 v[220:221], s[34:35], 0, v[134:135]
	s_mov_b32 m0, s25
	s_nop 0
	global_load_lds_dwordx4 v[220:221], off
	s_mov_b32 m0, s27
	s_nop 0
	global_load_lds_dwordx4 v[222:223], off
	s_waitcnt vmcnt(8)
	s_waitcnt lgkmcnt(0)
	s_barrier
; #define PG8_STAGE(bufoff, gbase, voff) do { _Pragma("unroll") for (int _i = 0; _i < 2; ++_i) \
;         __builtin_amdgcn_global_load_lds((const unsigned*)((const char*)(gbase) + (voff)[_i]), (PG8_LAS unsigned*)(lds + (bufoff) + ldsw + _i * 8192), 16, 0, 0); } while (0)
; #define PG8_LDA(dst, b, h) do { _Pragma("unroll") for (int m = 0; m < 4; ++m) _Pragma("unroll") for (int k = 0; k < 2; ++k) dst[m][k] = *(const PG8_LAS bf16x8*)(lds + PG8_SA(b, h) + aoff + m * 2048 + k * 1024); } while (0)
; #define PG8_LDB(dst, b, h) do { _Pragma("unroll") for (int n = 0; n < 2; ++n) _Pragma("unroll") for (int k = 0; k < 2; ++k) dst[n][k] = *(const PG8_LAS bf16x8*)(lds + PG8_SB(b, h) + boff + n * 2048 + k * 1024); } while (0)
; #define PG8_MMA(ai, bj, At, Bt) do { __builtin_amdgcn_s_setprio(1); _Pragma("unroll") for (int m = 0; m < 4; ++m) _Pragma("unroll") for (int n = 0; n < 2; ++n) _Pragma("unroll") for (int k = 0; k < 2; ++k) \
;         acc[ai][bj][m][n] = __builtin_amdgcn_mfma_f32_16x16x32_bf16(Bt[n][k], At[m][k], acc[ai][bj][m][n], 0, 0, 0); __builtin_amdgcn_s_setprio(0); } while (0)
; #define PG8_WAIT_V(n) asm volatile("s_waitcnt vmcnt(" #n ")" ::: "memory")
; #define PG8_WAIT_L(n) asm volatile("s_waitcnt lgkmcnt(" #n ")" ::: "memory")
; #define PG8_BAR __builtin_amdgcn_s_barrier()
; #define PG8_SCHED __builtin_amdgcn_sched_barrier(0)
; template <class Epi, class Sched, bool ALIGN_EPI = false, bool SP2 = false>
; __device__ __forceinline__ void gemm_phase(PG8_LAS unsigned char* lds, const Gemm g, const Sched& S, const Epi& E) {
;     ...
;             PG8_WAIT_V(8); PG8_WAIT_L(0); PG8_BAR; PG8_MMA(1, 0, At, B0); PG8_MMA(1, 1, At, B1); PG8_BAR; PG8_SCHED;
;             PG8_LDB(B0, 1, 0); PG8_LDB(B1, 1, 1); PG8_SCHED; PG8_LDA(At, 1, 0); PG8_STAGE(PG8_SA(0, 1), a2 + hstep, voffA);
;             PG8_WAIT_V(8); PG8_WAIT_L(0); PG8_BAR; PG8_MMA(0, 0, At, B0); PG8_MMA(0, 1, At, B1); PG8_BAR; PG8_SCHED;
	s_setprio 1
	s_waitcnt lgkmcnt(0)
	v_mfma_f32_16x16x32_bf16 v[60:63], v[144:147], v[182:185], 0
	v_mfma_f32_16x16x32_bf16 v[56:59], v[158:161], v[182:185], 0
	v_mfma_f32_16x16x32_bf16 v[44:47], v[144:147], v[194:197], 0
	v_mfma_f32_16x16x32_bf16 v[40:43], v[158:161], v[194:197], 0
	v_mfma_f32_16x16x32_bf16 v[28:31], v[144:147], v[202:205], 0
	v_mfma_f32_16x16x32_bf16 v[24:27], v[158:161], v[202:205], 0
	v_mfma_f32_16x16x32_bf16 v[12:15], v[144:147], v[210:213], 0
	v_mfma_f32_16x16x32_bf16 v[8:11], v[158:161], v[210:213], 0
	v_mfma_f32_16x16x32_bf16 v[60:63], v[154:157], v[186:189], v[60:63]
	v_mfma_f32_16x16x32_bf16 v[56:59], v[162:165], v[186:189], v[56:59]
	v_mfma_f32_16x16x32_bf16 v[44:47], v[154:157], v[198:201], v[44:47]
	v_mfma_f32_16x16x32_bf16 v[40:43], v[162:165], v[198:201], v[40:43]
	v_mfma_f32_16x16x32_bf16 v[28:31], v[154:157], v[206:209], v[28:31]
	v_mfma_f32_16x16x32_bf16 v[24:27], v[162:165], v[206:209], v[24:27]
	v_mfma_f32_16x16x32_bf16 v[12:15], v[154:157], v[214:217], v[12:15]
	v_mfma_f32_16x16x32_bf16 v[8:11], v[162:165], v[214:217], v[8:11]
	s_setprio 0
	s_setprio 1
	v_mfma_f32_16x16x32_bf16 v[52:55], v[166:169], v[182:185], 0
	v_mfma_f32_16x16x32_bf16 v[48:51], v[174:177], v[182:185], 0
	v_mfma_f32_16x16x32_bf16 v[36:39], v[166:169], v[194:197], 0
	v_mfma_f32_16x16x32_bf16 v[32:35], v[174:177], v[194:197], 0
	v_mfma_f32_16x16x32_bf16 v[20:23], v[166:169], v[202:205], 0
	v_mfma_f32_16x16x32_bf16 v[16:19], v[174:177], v[202:205], 0
	v_mfma_f32_16x16x32_bf16 v[4:7], v[166:169], v[210:213], 0
	v_mfma_f32_16x16x32_bf16 v[0:3], v[174:177], v[210:213], 0
	v_mfma_f32_16x16x32_bf16 v[52:55], v[170:173], v[186:189], v[52:55]
	v_mfma_f32_16x16x32_bf16 v[48:51], v[178:181], v[186:189], v[48:51]
	v_mfma_f32_16x16x32_bf16 v[36:39], v[170:173], v[198:201], v[36:39]
	v_mfma_f32_16x16x32_bf16 v[32:35], v[178:181], v[198:201], v[32:35]
	v_mfma_f32_16x16x32_bf16 v[20:23], v[170:173], v[206:209], v[20:23]
	v_mfma_f32_16x16x32_bf16 v[16:19], v[178:181], v[206:209], v[16:19]
	v_mfma_f32_16x16x32_bf16 v[4:7], v[170:173], v[214:217], v[4:7]
	v_mfma_f32_16x16x32_bf16 v[0:3], v[178:181], v[214:217], v[0:3]
	s_setprio 0
	s_barrier
	s_add_i32 s66, 0, 0x18000
	s_add_i32 s67, 0, 0x1c000
	v_add_u32_e32 v162, s66, v149
	v_add_u32_e32 v178, s67, v149
	ds_read_b128 v[144:147], v162
	ds_read_b128 v[154:157], v162 offset:1024
	ds_read_b128 v[158:161], v162 offset:2048
	ds_read_b128 v[162:165], v162 offset:3072
	ds_read_b128 v[166:169], v178
	ds_read_b128 v[170:173], v178 offset:1024
	ds_read_b128 v[174:177], v178 offset:2048
	ds_read_b128 v[178:181], v178 offset:3072
	s_add_u32 s34, s34, 0x80000
	s_addc_u32 s35, s35, 0
	s_mov_b32 m0, s52
	v_lshl_add_u64 v[224:225], s[34:35], 0, v[134:135]
	ds_read_b128 v[182:185], v153 offset:32768
	ds_read_b128 v[186:189], v153 offset:33792
	ds_read_b128 v[194:197], v153 offset:34816
	ds_read_b128 v[198:201], v153 offset:35840
	ds_read_b128 v[202:205], v153 offset:36864
	ds_read_b128 v[206:209], v153 offset:37888
	ds_read_b128 v[210:213], v153 offset:38912
	ds_read_b128 v[214:217], v153 offset:39936
	global_load_lds_dwordx4 v[224:225], off
	v_lshl_add_u64 v[224:225], s[34:35], 0, v[130:131]
	s_mov_b32 m0, s53
	s_nop 0
	global_load_lds_dwordx4 v[224:225], off
	s_waitcnt vmcnt(8)
	s_waitcnt lgkmcnt(0)
	s_barrier
	s_setprio 1
	s_waitcnt lgkmcnt(0)
	v_mfma_f32_16x16x32_bf16 v[124:127], v[144:147], v[182:185], v[124:127]
	v_mfma_f32_16x16x32_bf16 v[120:123], v[158:161], v[182:185], v[120:123]
	v_mfma_f32_16x16x32_bf16 v[108:111], v[144:147], v[194:197], v[108:111]
	v_mfma_f32_16x16x32_bf16 v[104:107], v[158:161], v[194:197], v[104:107]
	v_mfma_f32_16x16x32_bf16 v[92:95], v[144:147], v[202:205], v[92:95]
	v_mfma_f32_16x16x32_bf16 v[88:91], v[158:161], v[202:205], v[88:91]
	v_mfma_f32_16x16x32_bf16 v[76:79], v[144:147], v[210:213], v[76:79]
	v_mfma_f32_16x16x32_bf16 v[72:75], v[158:161], v[210:213], v[72:75]
	v_mfma_f32_16x16x32_bf16 v[124:127], v[154:157], v[186:189], v[124:127]
	v_mfma_f32_16x16x32_bf16 v[120:123], v[162:165], v[186:189], v[120:123]
	v_mfma_f32_16x16x32_bf16 v[108:111], v[154:157], v[198:201], v[108:111]
	v_mfma_f32_16x16x32_bf16 v[104:107], v[162:165], v[198:201], v[104:107]
	v_mfma_f32_16x16x32_bf16 v[92:95], v[154:157], v[206:209], v[92:95]
	v_mfma_f32_16x16x32_bf16 v[88:91], v[162:165], v[206:209], v[88:91]
	v_mfma_f32_16x16x32_bf16 v[76:79], v[154:157], v[214:217], v[76:79]
	v_mfma_f32_16x16x32_bf16 v[72:75], v[162:165], v[214:217], v[72:75]
	s_setprio 0
	s_setprio 1
	v_mfma_f32_16x16x32_bf16 v[116:119], v[166:169], v[182:185], v[116:119]
	v_mfma_f32_16x16x32_bf16 v[112:115], v[174:177], v[182:185], v[112:115]
	v_mfma_f32_16x16x32_bf16 v[100:103], v[166:169], v[194:197], v[100:103]
	v_mfma_f32_16x16x32_bf16 v[96:99], v[174:177], v[194:197], v[96:99]
	v_mfma_f32_16x16x32_bf16 v[84:87], v[166:169], v[202:205], v[84:87]
	v_mfma_f32_16x16x32_bf16 v[80:83], v[174:177], v[202:205], v[80:83]
	v_mfma_f32_16x16x32_bf16 v[68:71], v[166:169], v[210:213], v[68:71]
	v_mfma_f32_16x16x32_bf16 v[64:67], v[174:177], v[210:213], v[64:67]
	v_mfma_f32_16x16x32_bf16 v[116:119], v[170:173], v[186:189], v[116:119]
	v_mfma_f32_16x16x32_bf16 v[112:115], v[178:181], v[186:189], v[112:115]
	v_mfma_f32_16x16x32_bf16 v[100:103], v[170:173], v[198:201], v[100:103]
	v_mfma_f32_16x16x32_bf16 v[96:99], v[178:181], v[198:201], v[96:99]
	v_mfma_f32_16x16x32_bf16 v[84:87], v[170:173], v[206:209], v[84:87]
	v_mfma_f32_16x16x32_bf16 v[80:83], v[178:181], v[206:209], v[80:83]
	v_mfma_f32_16x16x32_bf16 v[68:71], v[170:173], v[214:217], v[68:71]
	v_mfma_f32_16x16x32_bf16 v[64:67], v[178:181], v[214:217], v[64:67]
	s_setprio 0
	s_barrier
; #define PG8_STAGE(bufoff, gbase, voff) do { _Pragma("unroll") for (int _i = 0; _i < 2; ++_i) \
;         __builtin_amdgcn_global_load_lds((const unsigned*)((const char*)(gbase) + (voff)[_i]), (PG8_LAS unsigned*)(lds + (bufoff) + ldsw + _i * 8192), 16, 0, 0); } while (0)
; #define PG8_LDA(dst, b, h) do { _Pragma("unroll") for (int m = 0; m < 4; ++m) _Pragma("unroll") for (int k = 0; k < 2; ++k) dst[m][k] = *(const PG8_LAS bf16x8*)(lds + PG8_SA(b, h) + aoff + m * 2048 + k * 1024); } while (0)
; #define PG8_MMA(ai, bj, At, Bt) do { __builtin_amdgcn_s_setprio(1); _Pragma("unroll") for (int m = 0; m < 4; ++m) _Pragma("unroll") for (int n = 0; n < 2; ++n) _Pragma("unroll") for (int k = 0; k < 2; ++k) \
;         acc[ai][bj][m][n] = __builtin_amdgcn_mfma_f32_16x16x32_bf16(Bt[n][k], At[m][k], acc[ai][bj][m][n], 0, 0, 0); __builtin_amdgcn_s_setprio(0); } while (0)
; #define PG8_WAIT_V(n) asm volatile("s_waitcnt vmcnt(" #n ")" ::: "memory")
; #define PG8_WAIT_L(n) asm volatile("s_waitcnt lgkmcnt(" #n ")" ::: "memory")
; #define PG8_BAR __builtin_amdgcn_s_barrier()
; #define PG8_SCHED __builtin_amdgcn_sched_barrier(0)
; template <class Epi, class Sched, bool ALIGN_EPI = false, bool SP2 = false>
; __device__ __forceinline__ void gemm_phase(PG8_LAS unsigned char* lds, const Gemm g, const Sched& S, const Epi& E) {
;     ...
;             PG8_LDA(At, 1, 1); PG8_STAGE(PG8_SB(1, 0), b3, voffB); PG8_STAGE(PG8_SB(1, 1), b3 + hstep, voffB); PG8_STAGE(PG8_SA(1, 0), a3, voffA);
;             PG8_WAIT_V(8); PG8_WAIT_L(0); PG8_BAR; PG8_MMA(1, 0, At, B0); PG8_MMA(1, 1, At, B1); PG8_BAR; PG8_SCHED;
	s_add_i32 s34, s66, s49
	v_lshl_add_u64 v[190:191], v[190:191], 0, s[12:13]
	s_mov_b32 m0, s34
	ds_read_b128 v[182:185], v153 offset:49152
	ds_read_b128 v[186:189], v153 offset:50176
	ds_read_b128 v[194:197], v153 offset:51200
	ds_read_b128 v[198:201], v153 offset:52224
	ds_read_b128 v[202:205], v153 offset:53248
	ds_read_b128 v[206:209], v153 offset:54272
	ds_read_b128 v[210:213], v153 offset:55296
	ds_read_b128 v[214:217], v153 offset:56320
	global_load_lds_dwordx4 v[190:191], off
	s_add_i32 m0, s34, 0x2000
	s_add_u32 s30, s30, 0x80080
	v_lshl_add_u64 v[190:191], v[218:219], 0, s[12:13]
	s_addc_u32 s31, s31, 0
	s_add_i32 s34, s67, s49
	global_load_lds_dwordx4 v[190:191], off
	v_lshl_add_u64 v[190:191], s[30:31], 0, v[132:133]
	s_mov_b32 m0, s34
	s_nop 0
	global_load_lds_dwordx4 v[190:191], off
	v_lshl_add_u64 v[190:191], s[30:31], 0, v[128:129]
	s_add_i32 m0, s34, 0x2000
	s_nop 0
	global_load_lds_dwordx4 v[190:191], off
	v_lshl_add_u64 v[190:191], v[220:221], 0, s[12:13]
	s_mov_b32 m0, s55
	s_nop 0
	global_load_lds_dwordx4 v[190:191], off
	v_lshl_add_u64 v[190:191], v[222:223], 0, s[12:13]
	s_mov_b32 m0, s56
	s_nop 0
	global_load_lds_dwordx4 v[190:191], off
	s_waitcnt vmcnt(8)
	s_waitcnt lgkmcnt(0)
	s_barrier
	s_setprio 1
	s_waitcnt lgkmcnt(0)
	v_mfma_f32_16x16x32_bf16 v[60:63], v[144:147], v[182:185], v[60:63]
	v_mfma_f32_16x16x32_bf16 v[56:59], v[158:161], v[182:185], v[56:59]
	v_mfma_f32_16x16x32_bf16 v[44:47], v[144:147], v[194:197], v[44:47]
	v_mfma_f32_16x16x32_bf16 v[40:43], v[158:161], v[194:197], v[40:43]
	v_mfma_f32_16x16x32_bf16 v[28:31], v[144:147], v[202:205], v[28:31]
	v_mfma_f32_16x16x32_bf16 v[24:27], v[158:161], v[202:205], v[24:27]
	v_mfma_f32_16x16x32_bf16 v[12:15], v[144:147], v[210:213], v[12:15]
	v_mfma_f32_16x16x32_bf16 v[8:11], v[158:161], v[210:213], v[8:11]
	v_mfma_f32_16x16x32_bf16 v[60:63], v[154:157], v[186:189], v[60:63]
	v_mfma_f32_16x16x32_bf16 v[56:59], v[162:165], v[186:189], v[56:59]
	v_mfma_f32_16x16x32_bf16 v[44:47], v[154:157], v[198:201], v[44:47]
	v_mfma_f32_16x16x32_bf16 v[40:43], v[162:165], v[198:201], v[40:43]
	v_mfma_f32_16x16x32_bf16 v[28:31], v[154:157], v[206:209], v[28:31]
	v_mfma_f32_16x16x32_bf16 v[24:27], v[162:165], v[206:209], v[24:27]
	v_mfma_f32_16x16x32_bf16 v[12:15], v[154:157], v[214:217], v[12:15]
	v_mfma_f32_16x16x32_bf16 v[8:11], v[162:165], v[214:217], v[8:11]
	s_setprio 0
	s_setprio 1
	v_mfma_f32_16x16x32_bf16 v[52:55], v[166:169], v[182:185], v[52:55]
	v_mfma_f32_16x16x32_bf16 v[48:51], v[174:177], v[182:185], v[48:51]
	v_mfma_f32_16x16x32_bf16 v[36:39], v[166:169], v[194:197], v[36:39]
	v_mfma_f32_16x16x32_bf16 v[32:35], v[174:177], v[194:197], v[32:35]
	v_mfma_f32_16x16x32_bf16 v[20:23], v[166:169], v[202:205], v[20:23]
	v_mfma_f32_16x16x32_bf16 v[16:19], v[174:177], v[202:205], v[16:19]
	v_mfma_f32_16x16x32_bf16 v[4:7], v[166:169], v[210:213], v[4:7]
	v_mfma_f32_16x16x32_bf16 v[0:3], v[174:177], v[210:213], v[0:3]
	v_mfma_f32_16x16x32_bf16 v[52:55], v[170:173], v[186:189], v[52:55]
	v_mfma_f32_16x16x32_bf16 v[48:51], v[178:181], v[186:189], v[48:51]
	v_mfma_f32_16x16x32_bf16 v[36:39], v[170:173], v[198:201], v[36:39]
	v_mfma_f32_16x16x32_bf16 v[32:35], v[178:181], v[198:201], v[32:35]
	v_mfma_f32_16x16x32_bf16 v[20:23], v[170:173], v[206:209], v[20:23]
	v_mfma_f32_16x16x32_bf16 v[16:19], v[178:181], v[206:209], v[16:19]
	v_mfma_f32_16x16x32_bf16 v[4:7], v[170:173], v[214:217], v[4:7]
	v_mfma_f32_16x16x32_bf16 v[0:3], v[178:181], v[214:217], v[0:3]
	s_setprio 0
	s_barrier
	s_add_i32 s65, s65, 2
	s_add_u32 s63, s63, 0x100
	s_addc_u32 s64, s64, 0
	s_add_u32 s28, s28, 0x100
	s_addc_u32 s29, s29, 0
	s_cmp_gt_u32 s65, 29
	s_cbranch_scc1 .Lpeel_exit_6

; #define PG8_STAGE(bufoff, gbase, voff) do { _Pragma("unroll") for (int _i = 0; _i < 2; ++_i) \
;         __builtin_amdgcn_global_load_lds((const unsigned*)((const char*)(gbase) + (voff)[_i]), (PG8_LAS unsigned*)(lds + (bufoff) + ldsw + _i * 8192), 16, 0, 0); } while (0)
; #define PG8_LDA(dst, b, h) do { _Pragma("unroll") for (int m = 0; m < 4; ++m) _Pragma("unroll") for (int k = 0; k < 2; ++k) dst[m][k] = *(const PG8_LAS bf16x8*)(lds + PG8_SA(b, h) + aoff + m * 2048 + k * 1024); } while (0)
; #define PG8_LDB(dst, b, h) do { _Pragma("unroll") for (int n = 0; n < 2; ++n) _Pragma("unroll") for (int k = 0; k < 2; ++k) dst[n][k] = *(const PG8_LAS bf16x8*)(lds + PG8_SB(b, h) + boff + n * 2048 + k * 1024); } while (0)
; #define PG8_MMA(ai, bj, At, Bt) do { __builtin_amdgcn_s_setprio(1); _Pragma("unroll") for (int m = 0; m < 4; ++m) _Pragma("unroll") for (int n = 0; n < 2; ++n) _Pragma("unroll") for (int k = 0; k < 2; ++k) \
;         acc[ai][bj][m][n] = __builtin_amdgcn_mfma_f32_16x16x32_bf16(Bt[n][k], At[m][k], acc[ai][bj][m][n], 0, 0, 0); __builtin_amdgcn_s_setprio(0); } while (0)
; #define PG8_WAIT_V(n) asm volatile("s_waitcnt vmcnt(" #n ")" ::: "memory")
; #define PG8_WAIT_L(n) asm volatile("s_waitcnt lgkmcnt(" #n ")" ::: "memory")
; #define PG8_BAR __builtin_amdgcn_s_barrier()
; #define PG8_SCHED __builtin_amdgcn_sched_barrier(0)
; template <class Epi, class Sched, bool ALIGN_EPI = false, bool SP2 = false>
; __device__ __forceinline__ void gemm_phase(PG8_LAS unsigned char* lds, const Gemm g, const Sched& S, const Epi& E) {
;     ...
;             const char* a2 = last ? nA : cA + (size_t)(t + 2) * kstep; const char* b2 = last ? nB : cB + (size_t)(t + 2) * kstep;
;             const char* a3 = a2 + kstep; const char* b3 = b2 + kstep;
;             if (last && has_next) S.a_ready(nxt);
;             if constexpr (SP2) {
;             PG8_LDB(B0, 0, 0); PG8_LDB(B1, 0, 1); PG8_SCHED; PG8_LDA(At, 0, 0); PG8_STAGE(PG8_SA(1, 1), a1 + hstep, voffA);
;             PG8_WAIT_V(8); PG8_WAIT_L(0); PG8_BAR; PG8_MMA(0, 0, At, B0); PG8_MMA(0, 1, At, B1); PG8_BAR; PG8_SCHED;
;             PG8_LDA(At, 0, 1); PG8_STAGE(PG8_SB(0, 0), b2, voffB); PG8_STAGE(PG8_SB(0, 1), b2 + hstep, voffB); PG8_STAGE(PG8_SA(0, 0), a2, voffA);
.LBB0_1249:
	s_add_u32 s71, s34, 0x100
	s_addc_u32 s72, s35, 0
	s_mov_b32 s73, -2
	ds_read_b128 v[124:127], v169
	ds_read_b128 v[132:135], v169 offset:1024
	ds_read_b128 v[136:139], v169 offset:2048
	ds_read_b128 v[140:143], v169 offset:3072
	ds_read_b128 v[160:163], v170
	ds_read_b128 v[172:175], v170 offset:1024
	ds_read_b128 v[176:179], v170 offset:2048
	ds_read_b128 v[180:183], v170 offset:3072
	s_add_u32 s34, s30, 0x100
	s_addc_u32 s35, s31, 0
	s_cmpk_eq_i32 s73, 0x54
	s_cselect_b32 s47, s9, s35
	s_cselect_b32 s46, s8, s34
	s_cselect_b32 s37, s29, s72
	s_cselect_b32 s36, s28, s71
	v_lshl_add_u64 v[164:165], s[30:31], 0, v[154:155]
	s_add_i32 m0, s55, 0xc000
	ds_read_b128 v[184:187], v171
	ds_read_b128 v[188:191], v171 offset:1024
	ds_read_b128 v[194:197], v171 offset:2048
	ds_read_b128 v[198:201], v171 offset:3072
	ds_read_b128 v[202:205], v171 offset:4096
	ds_read_b128 v[206:209], v171 offset:5120
	ds_read_b128 v[210:213], v171 offset:6144
	ds_read_b128 v[214:217], v171 offset:7168
	global_load_lds_dwordx4 v[164:165], off
	v_lshl_add_u64 v[164:165], s[30:31], 0, v[152:153]
	s_add_i32 m0, s55, 0xe000
	s_nop 0
	global_load_lds_dwordx4 v[164:165], off
	s_waitcnt vmcnt(8)
	s_waitcnt lgkmcnt(0)
	s_barrier
	s_setprio 1
	s_waitcnt lgkmcnt(0)
	v_mfma_f32_16x16x32_bf16 v[128:131], v[124:127], v[184:187], 0
	v_mfma_f32_16x16x32_bf16 v[120:123], v[136:139], v[184:187], 0
	v_mfma_f32_16x16x32_bf16 v[108:111], v[124:127], v[194:197], 0
	v_mfma_f32_16x16x32_bf16 v[104:107], v[136:139], v[194:197], 0
	v_mfma_f32_16x16x32_bf16 v[92:95], v[124:127], v[202:205], 0
	v_mfma_f32_16x16x32_bf16 v[88:91], v[136:139], v[202:205], 0
	v_mfma_f32_16x16x32_bf16 v[76:79], v[124:127], v[210:213], 0
	v_mfma_f32_16x16x32_bf16 v[72:75], v[136:139], v[210:213], 0
	v_mfma_f32_16x16x32_bf16 v[128:131], v[132:135], v[188:191], v[128:131]
	v_mfma_f32_16x16x32_bf16 v[120:123], v[140:143], v[188:191], v[120:123]
	v_mfma_f32_16x16x32_bf16 v[108:111], v[132:135], v[198:201], v[108:111]
	v_mfma_f32_16x16x32_bf16 v[104:107], v[140:143], v[198:201], v[104:107]
	v_mfma_f32_16x16x32_bf16 v[92:95], v[132:135], v[206:209], v[92:95]
	v_mfma_f32_16x16x32_bf16 v[88:91], v[140:143], v[206:209], v[88:91]
	v_mfma_f32_16x16x32_bf16 v[76:79], v[132:135], v[214:217], v[76:79]
	v_mfma_f32_16x16x32_bf16 v[72:75], v[140:143], v[214:217], v[72:75]
	s_setprio 0
	s_setprio 1
	v_mfma_f32_16x16x32_bf16 v[116:119], v[160:163], v[184:187], 0
	v_mfma_f32_16x16x32_bf16 v[112:115], v[176:179], v[184:187], 0
	v_mfma_f32_16x16x32_bf16 v[100:103], v[160:163], v[194:197], 0
	v_mfma_f32_16x16x32_bf16 v[96:99], v[176:179], v[194:197], 0
	v_mfma_f32_16x16x32_bf16 v[84:87], v[160:163], v[202:205], 0
	v_mfma_f32_16x16x32_bf16 v[80:83], v[176:179], v[202:205], 0
	v_mfma_f32_16x16x32_bf16 v[68:71], v[160:163], v[210:213], 0
	v_mfma_f32_16x16x32_bf16 v[64:67], v[176:179], v[210:213], 0
	v_mfma_f32_16x16x32_bf16 v[116:119], v[172:175], v[188:191], v[116:119]
	v_mfma_f32_16x16x32_bf16 v[112:115], v[180:183], v[188:191], v[112:115]
	v_mfma_f32_16x16x32_bf16 v[100:103], v[172:175], v[198:201], v[100:103]
	v_mfma_f32_16x16x32_bf16 v[96:99], v[180:183], v[198:201], v[96:99]
	v_mfma_f32_16x16x32_bf16 v[84:87], v[172:175], v[206:209], v[84:87]
	v_mfma_f32_16x16x32_bf16 v[80:83], v[180:183], v[206:209], v[80:83]
	v_mfma_f32_16x16x32_bf16 v[68:71], v[172:175], v[214:217], v[68:71]
	v_mfma_f32_16x16x32_bf16 v[64:67], v[180:183], v[214:217], v[64:67]
	s_setprio 0
	s_barrier
	s_add_i32 s30, s65, s54
	v_lshl_add_u64 v[164:165], s[36:37], 0, v[146:147]
	s_mov_b32 m0, s30
	ds_read_b128 v[184:187], v171 offset:16384
	ds_read_b128 v[188:191], v171 offset:17408
	ds_read_b128 v[194:197], v171 offset:18432
	ds_read_b128 v[198:201], v171 offset:19456
	ds_read_b128 v[202:205], v171 offset:20480
	ds_read_b128 v[206:209], v171 offset:21504
	ds_read_b128 v[210:213], v171 offset:22528
	ds_read_b128 v[214:217], v171 offset:23552
	global_load_lds_dwordx4 v[164:165], off
	s_add_i32 m0, s30, 0x2000
	s_add_u32 s30, s36, 0x160000
	v_lshl_add_u64 v[218:219], s[36:37], 0, v[150:151]
	s_addc_u32 s31, s37, 0
	s_add_i32 s74, s66, s54
	global_load_lds_dwordx4 v[218:219], off
	v_lshl_add_u64 v[220:221], s[30:31], 0, v[146:147]
	s_mov_b32 m0, s74
	v_lshl_add_u64 v[222:223], s[46:47], 0, v[148:149]
	global_load_lds_dwordx4 v[220:221], off
	v_lshl_add_u64 v[220:221], s[30:31], 0, v[150:151]
	s_add_i32 m0, s74, 0x2000
	s_nop 0
	global_load_lds_dwordx4 v[220:221], off
	v_lshl_add_u64 v[220:221], s[46:47], 0, v[144:145]
	s_mov_b32 m0, s55
	s_nop 0
	global_load_lds_dwordx4 v[220:221], off
	s_mov_b32 m0, s56
	s_nop 0
	global_load_lds_dwordx4 v[222:223], off
	s_waitcnt vmcnt(8)
	s_waitcnt lgkmcnt(0)
	s_barrier
; #define PG8_STAGE(bufoff, gbase, voff) do { _Pragma("unroll") for (int _i = 0; _i < 2; ++_i) \
;         __builtin_amdgcn_global_load_lds((const unsigned*)((const char*)(gbase) + (voff)[_i]), (PG8_LAS unsigned*)(lds + (bufoff) + ldsw + _i * 8192), 16, 0, 0); } while (0)
; #define PG8_LDA(dst, b, h) do { _Pragma("unroll") for (int m = 0; m < 4; ++m) _Pragma("unroll") for (int k = 0; k < 2; ++k) dst[m][k] = *(const PG8_LAS bf16x8*)(lds + PG8_SA(b, h) + aoff + m * 2048 + k * 1024); } while (0)
; #define PG8_LDB(dst, b, h) do { _Pragma("unroll") for (int n = 0; n < 2; ++n) _Pragma("unroll") for (int k = 0; k < 2; ++k) dst[n][k] = *(const PG8_LAS bf16x8*)(lds + PG8_SB(b, h) + boff + n * 2048 + k * 1024); } while (0)
; #define PG8_MMA(ai, bj, At, Bt) do { __builtin_amdgcn_s_setprio(1); _Pragma("unroll") for (int m = 0; m < 4; ++m) _Pragma("unroll") for (int n = 0; n < 2; ++n) _Pragma("unroll") for (int k = 0; k < 2; ++k) \
;         acc[ai][bj][m][n] = __builtin_amdgcn_mfma_f32_16x16x32_bf16(Bt[n][k], At[m][k], acc[ai][bj][m][n], 0, 0, 0); __builtin_amdgcn_s_setprio(0); } while (0)
; #define PG8_WAIT_V(n) asm volatile("s_waitcnt vmcnt(" #n ")" ::: "memory")
; #define PG8_WAIT_L(n) asm volatile("s_waitcnt lgkmcnt(" #n ")" ::: "memory")
; #define PG8_BAR __builtin_amdgcn_s_barrier()
; #define PG8_SCHED __builtin_amdgcn_sched_barrier(0)
; template <class Epi, class Sched, bool ALIGN_EPI = false, bool SP2 = false>
; __device__ __forceinline__ void gemm_phase(PG8_LAS unsigned char* lds, const Gemm g, const Sched& S, const Epi& E) {
;     ...
;             PG8_WAIT_V(8); PG8_WAIT_L(0); PG8_BAR; PG8_MMA(1, 0, At, B0); PG8_MMA(1, 1, At, B1); PG8_BAR; PG8_SCHED;
;             PG8_LDB(B0, 1, 0); PG8_LDB(B1, 1, 1); PG8_SCHED; PG8_LDA(At, 1, 0); PG8_STAGE(PG8_SA(0, 1), a2 + hstep, voffA);
;             PG8_WAIT_V(8); PG8_WAIT_L(0); PG8_BAR; PG8_MMA(0, 0, At, B0); PG8_MMA(0, 1, At, B1); PG8_BAR; PG8_SCHED;
	s_setprio 1
	s_waitcnt lgkmcnt(0)
	v_mfma_f32_16x16x32_bf16 v[60:63], v[124:127], v[184:187], 0
	v_mfma_f32_16x16x32_bf16 v[56:59], v[136:139], v[184:187], 0
	v_mfma_f32_16x16x32_bf16 v[44:47], v[124:127], v[194:197], 0
	v_mfma_f32_16x16x32_bf16 v[40:43], v[136:139], v[194:197], 0
	v_mfma_f32_16x16x32_bf16 v[28:31], v[124:127], v[202:205], 0
	v_mfma_f32_16x16x32_bf16 v[24:27], v[136:139], v[202:205], 0
	v_mfma_f32_16x16x32_bf16 v[12:15], v[124:127], v[210:213], 0
	v_mfma_f32_16x16x32_bf16 v[8:11], v[136:139], v[210:213], 0
	v_mfma_f32_16x16x32_bf16 v[60:63], v[132:135], v[188:191], v[60:63]
	v_mfma_f32_16x16x32_bf16 v[56:59], v[140:143], v[188:191], v[56:59]
	v_mfma_f32_16x16x32_bf16 v[44:47], v[132:135], v[198:201], v[44:47]
	v_mfma_f32_16x16x32_bf16 v[40:43], v[140:143], v[198:201], v[40:43]
	v_mfma_f32_16x16x32_bf16 v[28:31], v[132:135], v[206:209], v[28:31]
	v_mfma_f32_16x16x32_bf16 v[24:27], v[140:143], v[206:209], v[24:27]
	v_mfma_f32_16x16x32_bf16 v[12:15], v[132:135], v[214:217], v[12:15]
	v_mfma_f32_16x16x32_bf16 v[8:11], v[140:143], v[214:217], v[8:11]
	s_setprio 0
	s_setprio 1
	v_mfma_f32_16x16x32_bf16 v[52:55], v[160:163], v[184:187], 0
	v_mfma_f32_16x16x32_bf16 v[48:51], v[176:179], v[184:187], 0
	v_mfma_f32_16x16x32_bf16 v[36:39], v[160:163], v[194:197], 0
	v_mfma_f32_16x16x32_bf16 v[32:35], v[176:179], v[194:197], 0
	v_mfma_f32_16x16x32_bf16 v[20:23], v[160:163], v[202:205], 0
	v_mfma_f32_16x16x32_bf16 v[16:19], v[176:179], v[202:205], 0
	v_mfma_f32_16x16x32_bf16 v[4:7], v[160:163], v[210:213], 0
	v_mfma_f32_16x16x32_bf16 v[0:3], v[176:179], v[210:213], 0
	v_mfma_f32_16x16x32_bf16 v[52:55], v[172:175], v[188:191], v[52:55]
	v_mfma_f32_16x16x32_bf16 v[48:51], v[180:183], v[188:191], v[48:51]
	v_mfma_f32_16x16x32_bf16 v[36:39], v[172:175], v[198:201], v[36:39]
	v_mfma_f32_16x16x32_bf16 v[32:35], v[180:183], v[198:201], v[32:35]
	v_mfma_f32_16x16x32_bf16 v[20:23], v[172:175], v[206:209], v[20:23]
	v_mfma_f32_16x16x32_bf16 v[16:19], v[180:183], v[206:209], v[16:19]
	v_mfma_f32_16x16x32_bf16 v[4:7], v[172:175], v[214:217], v[4:7]
	v_mfma_f32_16x16x32_bf16 v[0:3], v[180:183], v[214:217], v[0:3]
	s_setprio 0
	s_barrier
	s_add_i32 s74, 0, 0x18000
	s_add_i32 s75, 0, 0x1c000
	v_add_u32_e32 v140, s74, v167
	v_add_u32_e32 v180, s75, v167
	ds_read_b128 v[124:127], v140
	ds_read_b128 v[132:135], v140 offset:1024
	ds_read_b128 v[136:139], v140 offset:2048
	ds_read_b128 v[140:143], v140 offset:3072
	ds_read_b128 v[160:163], v180
	ds_read_b128 v[172:175], v180 offset:1024
	ds_read_b128 v[176:179], v180 offset:2048
	ds_read_b128 v[180:183], v180 offset:3072
	s_add_u32 s30, s46, 0x160000
	s_addc_u32 s31, s47, 0
	s_mov_b32 m0, s57
	v_lshl_add_u64 v[224:225], s[30:31], 0, v[144:145]
	ds_read_b128 v[184:187], v171 offset:32768
	ds_read_b128 v[188:191], v171 offset:33792
	ds_read_b128 v[194:197], v171 offset:34816
	ds_read_b128 v[198:201], v171 offset:35840
	ds_read_b128 v[202:205], v171 offset:36864
	ds_read_b128 v[206:209], v171 offset:37888
	ds_read_b128 v[210:213], v171 offset:38912
	ds_read_b128 v[214:217], v171 offset:39936
	global_load_lds_dwordx4 v[224:225], off
	v_lshl_add_u64 v[224:225], s[30:31], 0, v[148:149]
	s_mov_b32 m0, s58
	s_nop 0
	global_load_lds_dwordx4 v[224:225], off
	s_waitcnt vmcnt(8)
	s_waitcnt lgkmcnt(0)
	s_barrier
	s_setprio 1
	s_waitcnt lgkmcnt(0)
	v_mfma_f32_16x16x32_bf16 v[128:131], v[124:127], v[184:187], v[128:131]
	v_mfma_f32_16x16x32_bf16 v[120:123], v[136:139], v[184:187], v[120:123]
	v_mfma_f32_16x16x32_bf16 v[108:111], v[124:127], v[194:197], v[108:111]
	v_mfma_f32_16x16x32_bf16 v[104:107], v[136:139], v[194:197], v[104:107]
	v_mfma_f32_16x16x32_bf16 v[92:95], v[124:127], v[202:205], v[92:95]
	v_mfma_f32_16x16x32_bf16 v[88:91], v[136:139], v[202:205], v[88:91]
	v_mfma_f32_16x16x32_bf16 v[76:79], v[124:127], v[210:213], v[76:79]
	v_mfma_f32_16x16x32_bf16 v[72:75], v[136:139], v[210:213], v[72:75]
	v_mfma_f32_16x16x32_bf16 v[128:131], v[132:135], v[188:191], v[128:131]
	v_mfma_f32_16x16x32_bf16 v[120:123], v[140:143], v[188:191], v[120:123]
	v_mfma_f32_16x16x32_bf16 v[108:111], v[132:135], v[198:201], v[108:111]
	v_mfma_f32_16x16x32_bf16 v[104:107], v[140:143], v[198:201], v[104:107]
	v_mfma_f32_16x16x32_bf16 v[92:95], v[132:135], v[206:209], v[92:95]
	v_mfma_f32_16x16x32_bf16 v[88:91], v[140:143], v[206:209], v[88:91]
	v_mfma_f32_16x16x32_bf16 v[76:79], v[132:135], v[214:217], v[76:79]
	v_mfma_f32_16x16x32_bf16 v[72:75], v[140:143], v[214:217], v[72:75]
	s_setprio 0
	s_setprio 1
	v_mfma_f32_16x16x32_bf16 v[116:119], v[160:163], v[184:187], v[116:119]
	v_mfma_f32_16x16x32_bf16 v[112:115], v[176:179], v[184:187], v[112:115]
	v_mfma_f32_16x16x32_bf16 v[100:103], v[160:163], v[194:197], v[100:103]
	v_mfma_f32_16x16x32_bf16 v[96:99], v[176:179], v[194:197], v[96:99]
	v_mfma_f32_16x16x32_bf16 v[84:87], v[160:163], v[202:205], v[84:87]
	v_mfma_f32_16x16x32_bf16 v[80:83], v[176:179], v[202:205], v[80:83]
	v_mfma_f32_16x16x32_bf16 v[68:71], v[160:163], v[210:213], v[68:71]
	v_mfma_f32_16x16x32_bf16 v[64:67], v[176:179], v[210:213], v[64:67]
	v_mfma_f32_16x16x32_bf16 v[116:119], v[172:175], v[188:191], v[116:119]
	v_mfma_f32_16x16x32_bf16 v[112:115], v[180:183], v[188:191], v[112:115]
	v_mfma_f32_16x16x32_bf16 v[100:103], v[172:175], v[198:201], v[100:103]
	v_mfma_f32_16x16x32_bf16 v[96:99], v[180:183], v[198:201], v[96:99]
	v_mfma_f32_16x16x32_bf16 v[84:87], v[172:175], v[206:209], v[84:87]
	v_mfma_f32_16x16x32_bf16 v[80:83], v[180:183], v[206:209], v[80:83]
	v_mfma_f32_16x16x32_bf16 v[68:71], v[172:175], v[214:217], v[68:71]
	v_mfma_f32_16x16x32_bf16 v[64:67], v[180:183], v[214:217], v[64:67]
	s_setprio 0
	s_barrier
; #define PG8_STAGE(bufoff, gbase, voff) do { _Pragma("unroll") for (int _i = 0; _i < 2; ++_i) \
;         __builtin_amdgcn_global_load_lds((const unsigned*)((const char*)(gbase) + (voff)[_i]), (PG8_LAS unsigned*)(lds + (bufoff) + ldsw + _i * 8192), 16, 0, 0); } while (0)
; #define PG8_LDA(dst, b, h) do { _Pragma("unroll") for (int m = 0; m < 4; ++m) _Pragma("unroll") for (int k = 0; k < 2; ++k) dst[m][k] = *(const PG8_LAS bf16x8*)(lds + PG8_SA(b, h) + aoff + m * 2048 + k * 1024); } while (0)
; #define PG8_MMA(ai, bj, At, Bt) do { __builtin_amdgcn_s_setprio(1); _Pragma("unroll") for (int m = 0; m < 4; ++m) _Pragma("unroll") for (int n = 0; n < 2; ++n) _Pragma("unroll") for (int k = 0; k < 2; ++k) \
;         acc[ai][bj][m][n] = __builtin_amdgcn_mfma_f32_16x16x32_bf16(Bt[n][k], At[m][k], acc[ai][bj][m][n], 0, 0, 0); __builtin_amdgcn_s_setprio(0); } while (0)
; #define PG8_WAIT_V(n) asm volatile("s_waitcnt vmcnt(" #n ")" ::: "memory")
; #define PG8_WAIT_L(n) asm volatile("s_waitcnt lgkmcnt(" #n ")" ::: "memory")
; #define PG8_BAR __builtin_amdgcn_s_barrier()
; #define PG8_SCHED __builtin_amdgcn_sched_barrier(0)
; template <class Epi, class Sched, bool ALIGN_EPI = false, bool SP2 = false>
; __device__ __forceinline__ void gemm_phase(PG8_LAS unsigned char* lds, const Gemm g, const Sched& S, const Epi& E) {
;     ...
;             PG8_LDA(At, 1, 1); PG8_STAGE(PG8_SB(1, 0), b3, voffB); PG8_STAGE(PG8_SB(1, 1), b3 + hstep, voffB); PG8_STAGE(PG8_SA(1, 0), a3, voffA);
;             PG8_WAIT_V(8); PG8_WAIT_L(0); PG8_BAR; PG8_MMA(1, 0, At, B0); PG8_MMA(1, 1, At, B1); PG8_BAR; PG8_SCHED;
	s_add_i32 s30, s74, s54
	v_lshl_add_u64 v[164:165], v[164:165], 0, s[16:17]
	s_mov_b32 m0, s30
	ds_read_b128 v[184:187], v171 offset:49152
	ds_read_b128 v[188:191], v171 offset:50176
	ds_read_b128 v[194:197], v171 offset:51200
	ds_read_b128 v[198:201], v171 offset:52224
	ds_read_b128 v[202:205], v171 offset:53248
	ds_read_b128 v[206:209], v171 offset:54272
	ds_read_b128 v[210:213], v171 offset:55296
	ds_read_b128 v[214:217], v171 offset:56320
	global_load_lds_dwordx4 v[164:165], off
	s_add_i32 m0, s30, 0x2000
	s_add_u32 s30, s36, 0x160080
	v_lshl_add_u64 v[164:165], v[218:219], 0, s[16:17]
	s_addc_u32 s31, s37, 0
	s_add_i32 s36, s75, s54
	global_load_lds_dwordx4 v[164:165], off
	v_lshl_add_u64 v[164:165], s[30:31], 0, v[146:147]
	s_mov_b32 m0, s36
	s_nop 0
	global_load_lds_dwordx4 v[164:165], off
	v_lshl_add_u64 v[164:165], s[30:31], 0, v[150:151]
	s_add_i32 m0, s36, 0x2000
	s_nop 0
	global_load_lds_dwordx4 v[164:165], off
	v_lshl_add_u64 v[164:165], v[220:221], 0, s[16:17]
	s_mov_b32 m0, s62
	s_nop 0
	global_load_lds_dwordx4 v[164:165], off
	v_lshl_add_u64 v[164:165], v[222:223], 0, s[16:17]
	s_mov_b32 m0, s63
	s_nop 0
	global_load_lds_dwordx4 v[164:165], off
	s_waitcnt vmcnt(8)
	s_waitcnt lgkmcnt(0)
	s_barrier
	s_setprio 1
	s_waitcnt lgkmcnt(0)
	v_mfma_f32_16x16x32_bf16 v[60:63], v[124:127], v[184:187], v[60:63]
	v_mfma_f32_16x16x32_bf16 v[56:59], v[136:139], v[184:187], v[56:59]
	v_mfma_f32_16x16x32_bf16 v[44:47], v[124:127], v[194:197], v[44:47]
	v_mfma_f32_16x16x32_bf16 v[40:43], v[136:139], v[194:197], v[40:43]
	v_mfma_f32_16x16x32_bf16 v[28:31], v[124:127], v[202:205], v[28:31]
	v_mfma_f32_16x16x32_bf16 v[24:27], v[136:139], v[202:205], v[24:27]
	v_mfma_f32_16x16x32_bf16 v[12:15], v[124:127], v[210:213], v[12:15]
	v_mfma_f32_16x16x32_bf16 v[8:11], v[136:139], v[210:213], v[8:11]
	v_mfma_f32_16x16x32_bf16 v[60:63], v[132:135], v[188:191], v[60:63]
	v_mfma_f32_16x16x32_bf16 v[56:59], v[140:143], v[188:191], v[56:59]
	v_mfma_f32_16x16x32_bf16 v[44:47], v[132:135], v[198:201], v[44:47]
	v_mfma_f32_16x16x32_bf16 v[40:43], v[140:143], v[198:201], v[40:43]
	v_mfma_f32_16x16x32_bf16 v[28:31], v[132:135], v[206:209], v[28:31]
	v_mfma_f32_16x16x32_bf16 v[24:27], v[140:143], v[206:209], v[24:27]
	v_mfma_f32_16x16x32_bf16 v[12:15], v[132:135], v[214:217], v[12:15]
	v_mfma_f32_16x16x32_bf16 v[8:11], v[140:143], v[214:217], v[8:11]
	s_setprio 0
	s_setprio 1
	v_mfma_f32_16x16x32_bf16 v[52:55], v[160:163], v[184:187], v[52:55]
	v_mfma_f32_16x16x32_bf16 v[48:51], v[176:179], v[184:187], v[48:51]
	v_mfma_f32_16x16x32_bf16 v[36:39], v[160:163], v[194:197], v[36:39]
	v_mfma_f32_16x16x32_bf16 v[32:35], v[176:179], v[194:197], v[32:35]
	v_mfma_f32_16x16x32_bf16 v[20:23], v[160:163], v[202:205], v[20:23]
	v_mfma_f32_16x16x32_bf16 v[16:19], v[176:179], v[202:205], v[16:19]
	v_mfma_f32_16x16x32_bf16 v[4:7], v[160:163], v[210:213], v[4:7]
	v_mfma_f32_16x16x32_bf16 v[0:3], v[176:179], v[210:213], v[0:3]
	v_mfma_f32_16x16x32_bf16 v[52:55], v[172:175], v[188:191], v[52:55]
	v_mfma_f32_16x16x32_bf16 v[48:51], v[180:183], v[188:191], v[48:51]
	v_mfma_f32_16x16x32_bf16 v[36:39], v[172:175], v[198:201], v[36:39]
	v_mfma_f32_16x16x32_bf16 v[32:35], v[180:183], v[198:201], v[32:35]
	v_mfma_f32_16x16x32_bf16 v[20:23], v[172:175], v[206:209], v[20:23]
	v_mfma_f32_16x16x32_bf16 v[16:19], v[180:183], v[206:209], v[16:19]
	v_mfma_f32_16x16x32_bf16 v[4:7], v[172:175], v[214:217], v[4:7]
	v_mfma_f32_16x16x32_bf16 v[0:3], v[180:183], v[214:217], v[0:3]
	s_setprio 0
	s_barrier
	s_add_i32 s73, s73, 2
	s_add_u32 s71, s71, 0x100
	s_addc_u32 s72, s72, 0
	s_cmpk_gt_u32 s73, 0x55
	s_mov_b64 s[30:31], s[34:35]
	s_cbranch_scc1 .Lpeel_exit_7

; #define PG8_BAR __builtin_amdgcn_s_barrier()
; template <class Epi, class Sched, bool ALIGN_EPI = false, bool SP2 = false>
; __device__ __forceinline__ void gemm_phase(PG8_LAS unsigned char* lds, const Gemm g, const Sched& S, const Epi& E) {
;     ...
;         if constexpr (ALIGN_EPI) { if (wr == 0) PG8_BAR; }
.Lpeel_exit_7:
	s_and_b64 vcc, exec, s[18:19]
	s_cbranch_vccz .LBB0_1253
	s_barrier
